# v38 minus the adjacent s_setprio 0/1 pairs in the middle of each GEMM super-phase (A/B of the flips)
# baseline (speedup 1.0000x reference)
; #define PG8_STAGE(bufoff, gbase, voff) do { _Pragma("unroll") for (int _i = 0; _i < 2; ++_i) \
;         __builtin_amdgcn_global_load_lds((const unsigned*)((const char*)(gbase) + (voff)[_i]), (PG8_LAS unsigned*)(lds + (bufoff) + ldsw + _i * 8192), 16, 0, 0); } while (0)
; #define PG8_LDA(dst, b, h) do { _Pragma("unroll") for (int m = 0; m < 4; ++m) _Pragma("unroll") for (int k = 0; k < 2; ++k) dst[m][k] = *(const PG8_LAS bf16x8*)(lds + PG8_SA(b, h) + aoff + m * 2048 + k * 1024); } while (0)
; #define PG8_LDB(dst, b, h) do { _Pragma("unroll") for (int n = 0; n < 2; ++n) _Pragma("unroll") for (int k = 0; k < 2; ++k) dst[n][k] = *(const PG8_LAS bf16x8*)(lds + PG8_SB(b, h) + boff + n * 2048 + k * 1024); } while (0)
; #define PG8_MMA(ai, bj, At, Bt) do { __builtin_amdgcn_s_setprio(1); _Pragma("unroll") for (int m = 0; m < 4; ++m) _Pragma("unroll") for (int n = 0; n < 2; ++n) _Pragma("unroll") for (int k = 0; k < 2; ++k) \
;         acc[ai][bj][m][n] = __builtin_amdgcn_mfma_f32_16x16x32_bf16(Bt[n][k], At[m][k], acc[ai][bj][m][n], 0, 0, 0); __builtin_amdgcn_s_setprio(0); } while (0)
; #define PG8_WAIT_V(n) asm volatile("s_waitcnt vmcnt(" #n ")" ::: "memory")
; #define PG8_WAIT_L(n) asm volatile("s_waitcnt lgkmcnt(" #n ")" ::: "memory")
; #define PG8_BAR __builtin_amdgcn_s_barrier()
; #define PG8_SCHED __builtin_amdgcn_sched_barrier(0)
; template <class Epi, class Sched, bool ALIGN_EPI = false, bool SP2 = false>
; __device__ __forceinline__ void gemm_phase(PG8_LAS unsigned char* lds, const Gemm g, const Sched& S, const Epi& E) {
;     ...
;             PG8_LDB(B0, 0, 0); PG8_LDB(B1, 0, 1); PG8_SCHED; PG8_LDA(At, 0, 0); PG8_STAGE(PG8_SA(1, 1), a1 + hstep, voffA);
;             PG8_WAIT_V(8); PG8_WAIT_L(0); PG8_BAR; PG8_MMA(0, 0, At, B0); PG8_MMA(0, 1, At, B1); PG8_BAR; PG8_SCHED;
;             PG8_LDA(At, 0, 1); PG8_STAGE(PG8_SB(0, 0), b2, voffB); PG8_STAGE(PG8_SB(0, 1), b2 + hstep, voffB); PG8_STAGE(PG8_SA(0, 0), a2, voffA);
;             PG8_WAIT_V(8); PG8_WAIT_L(0); PG8_BAR; PG8_MMA(1, 0, At, B0); PG8_MMA(1, 1, At, B1); PG8_BAR; PG8_SCHED;
.LBB0_126:
	ds_read_b128 v[128:131], v177
	ds_read_b128 v[132:135], v177 offset:1024
	ds_read_b128 v[136:139], v177 offset:2048
	ds_read_b128 v[140:143], v177 offset:3072
	ds_read_b128 v[168:171], v178
	ds_read_b128 v[182:185], v178 offset:1024
	ds_read_b128 v[190:193], v178 offset:2048
	ds_read_b128 v[194:197], v178 offset:3072
	s_add_u32 s42, s40, 0xfffc0080
	s_addc_u32 s43, s41, -1
	s_cmp_eq_u32 vcc_hi, 12
	s_cselect_b32 s45, s35, s43
	s_cselect_b32 s44, s95, s42
	s_cselect_b32 s43, s31, vcc_lo
	s_cselect_b32 s42, s96, s97
	v_lshl_add_u64 v[172:173], s[40:41], 0, v[160:161]
	s_add_i32 m0, s53, 0xc000
	ds_read_b128 v[198:201], v179
	ds_read_b128 v[202:205], v179 offset:1024
	ds_read_b128 v[206:209], v179 offset:2048
	ds_read_b128 v[210:213], v179 offset:3072
	ds_read_b128 v[214:217], v179 offset:4096
	ds_read_b128 v[218:221], v179 offset:5120
	ds_read_b128 v[222:225], v179 offset:6144
	ds_read_b128 v[226:229], v179 offset:7168
	global_load_lds_dwordx4 v[172:173], off
	v_lshl_add_u64 v[172:173], s[40:41], 0, v[162:163]
	s_add_i32 m0, s53, 0xe000
	s_nop 0
	global_load_lds_dwordx4 v[172:173], off
	s_waitcnt vmcnt(8)
	s_waitcnt lgkmcnt(0)
	s_barrier
	s_setprio 1
	s_waitcnt lgkmcnt(0)
	v_mfma_f32_16x16x32_bf16 v[124:127], v[128:131], v[198:201], v[124:127]
	v_mfma_f32_16x16x32_bf16 v[120:123], v[136:139], v[198:201], v[120:123]
	v_mfma_f32_16x16x32_bf16 v[108:111], v[128:131], v[206:209], v[108:111]
	v_mfma_f32_16x16x32_bf16 v[104:107], v[136:139], v[206:209], v[104:107]
	v_mfma_f32_16x16x32_bf16 v[96:99], v[128:131], v[214:217], v[96:99]
	v_mfma_f32_16x16x32_bf16 v[88:91], v[136:139], v[214:217], v[88:91]
	v_mfma_f32_16x16x32_bf16 v[80:83], v[128:131], v[222:225], v[80:83]
	v_mfma_f32_16x16x32_bf16 v[72:75], v[136:139], v[222:225], v[72:75]
	v_mfma_f32_16x16x32_bf16 v[124:127], v[132:135], v[202:205], v[124:127]
	v_mfma_f32_16x16x32_bf16 v[120:123], v[140:143], v[202:205], v[120:123]
	v_mfma_f32_16x16x32_bf16 v[108:111], v[132:135], v[210:213], v[108:111]
	v_mfma_f32_16x16x32_bf16 v[104:107], v[140:143], v[210:213], v[104:107]
	v_mfma_f32_16x16x32_bf16 v[96:99], v[132:135], v[218:221], v[96:99]
	v_mfma_f32_16x16x32_bf16 v[88:91], v[140:143], v[218:221], v[88:91]
	v_mfma_f32_16x16x32_bf16 v[80:83], v[132:135], v[226:229], v[80:83]
	v_mfma_f32_16x16x32_bf16 v[72:75], v[140:143], v[226:229], v[72:75]
	v_mfma_f32_16x16x32_bf16 v[116:119], v[168:171], v[198:201], v[116:119]
	v_mfma_f32_16x16x32_bf16 v[112:115], v[190:193], v[198:201], v[112:115]
	v_mfma_f32_16x16x32_bf16 v[100:103], v[168:171], v[206:209], v[100:103]
	v_mfma_f32_16x16x32_bf16 v[92:95], v[190:193], v[206:209], v[92:95]
	v_mfma_f32_16x16x32_bf16 v[84:87], v[168:171], v[214:217], v[84:87]
	v_mfma_f32_16x16x32_bf16 v[76:79], v[190:193], v[214:217], v[76:79]
	v_mfma_f32_16x16x32_bf16 v[68:71], v[168:171], v[222:225], v[68:71]
	v_mfma_f32_16x16x32_bf16 v[64:67], v[190:193], v[222:225], v[64:67]
	v_mfma_f32_16x16x32_bf16 v[116:119], v[182:185], v[202:205], v[116:119]
	v_mfma_f32_16x16x32_bf16 v[112:115], v[194:197], v[202:205], v[112:115]
	v_mfma_f32_16x16x32_bf16 v[100:103], v[182:185], v[210:213], v[100:103]
	v_mfma_f32_16x16x32_bf16 v[92:95], v[194:197], v[210:213], v[92:95]
	v_mfma_f32_16x16x32_bf16 v[84:87], v[182:185], v[218:221], v[84:87]
	v_mfma_f32_16x16x32_bf16 v[76:79], v[194:197], v[218:221], v[76:79]
	v_mfma_f32_16x16x32_bf16 v[68:71], v[182:185], v[226:229], v[68:71]
	v_mfma_f32_16x16x32_bf16 v[64:67], v[194:197], v[226:229], v[64:67]
	s_setprio 0
	s_barrier
	s_add_i32 s54, s71, s50
	v_lshl_add_u64 v[172:173], s[42:43], 0, v[146:147]
	s_mov_b32 m0, s54
	ds_read_b128 v[198:201], v179 offset:16384
	ds_read_b128 v[202:205], v179 offset:17408
	ds_read_b128 v[206:209], v179 offset:18432
	ds_read_b128 v[210:213], v179 offset:19456
	ds_read_b128 v[214:217], v179 offset:20480
	ds_read_b128 v[218:221], v179 offset:21504
	ds_read_b128 v[222:225], v179 offset:22528
	ds_read_b128 v[226:229], v179 offset:23552
	global_load_lds_dwordx4 v[172:173], off
	s_add_i32 m0, s54, 0x2000
	s_add_u32 s84, s42, 0x40000
	v_lshl_add_u64 v[186:187], s[42:43], 0, v[150:151]
	s_addc_u32 s85, s43, 0
	s_add_i32 s54, s72, s50
	global_load_lds_dwordx4 v[186:187], off
	v_lshl_add_u64 v[230:231], s[84:85], 0, v[146:147]
	s_mov_b32 m0, s54
	v_lshl_add_u64 v[232:233], s[44:45], 0, v[148:149]
	global_load_lds_dwordx4 v[230:231], off
	v_lshl_add_u64 v[230:231], s[84:85], 0, v[150:151]
	s_add_i32 m0, s54, 0x2000
	s_nop 0
	global_load_lds_dwordx4 v[230:231], off
	v_lshl_add_u64 v[230:231], s[44:45], 0, v[144:145]
	s_mov_b32 m0, s53
	s_nop 0
	global_load_lds_dwordx4 v[230:231], off
	s_mov_b32 m0, s58
	s_nop 0
	global_load_lds_dwordx4 v[232:233], off
	s_waitcnt vmcnt(8)
	s_waitcnt lgkmcnt(0)
	s_barrier
; #define PG8_STAGE(bufoff, gbase, voff) do { _Pragma("unroll") for (int _i = 0; _i < 2; ++_i) \
;         __builtin_amdgcn_global_load_lds((const unsigned*)((const char*)(gbase) + (voff)[_i]), (PG8_LAS unsigned*)(lds + (bufoff) + ldsw + _i * 8192), 16, 0, 0); } while (0)
; #define PG8_LDA(dst, b, h) do { _Pragma("unroll") for (int m = 0; m < 4; ++m) _Pragma("unroll") for (int k = 0; k < 2; ++k) dst[m][k] = *(const PG8_LAS bf16x8*)(lds + PG8_SA(b, h) + aoff + m * 2048 + k * 1024); } while (0)
; #define PG8_LDB(dst, b, h) do { _Pragma("unroll") for (int n = 0; n < 2; ++n) _Pragma("unroll") for (int k = 0; k < 2; ++k) dst[n][k] = *(const PG8_LAS bf16x8*)(lds + PG8_SB(b, h) + boff + n * 2048 + k * 1024); } while (0)
; #define PG8_MMA(ai, bj, At, Bt) do { __builtin_amdgcn_s_setprio(1); _Pragma("unroll") for (int m = 0; m < 4; ++m) _Pragma("unroll") for (int n = 0; n < 2; ++n) _Pragma("unroll") for (int k = 0; k < 2; ++k) \
;         acc[ai][bj][m][n] = __builtin_amdgcn_mfma_f32_16x16x32_bf16(Bt[n][k], At[m][k], acc[ai][bj][m][n], 0, 0, 0); __builtin_amdgcn_s_setprio(0); } while (0)
; #define PG8_WAIT_V(n) asm volatile("s_waitcnt vmcnt(" #n ")" ::: "memory")
; #define PG8_WAIT_L(n) asm volatile("s_waitcnt lgkmcnt(" #n ")" ::: "memory")
; #define PG8_BAR __builtin_amdgcn_s_barrier()
; #define PG8_SCHED __builtin_amdgcn_sched_barrier(0)
; template <class Epi, class Sched, bool ALIGN_EPI = false, bool SP2 = false>
; __device__ __forceinline__ void gemm_phase(PG8_LAS unsigned char* lds, const Gemm g, const Sched& S, const Epi& E) {
;     ...
;             PG8_WAIT_V(8); PG8_WAIT_L(0); PG8_BAR; PG8_MMA(1, 0, At, B0); PG8_MMA(1, 1, At, B1); PG8_BAR; PG8_SCHED;
;             PG8_LDB(B0, 1, 0); PG8_LDB(B1, 1, 1); PG8_SCHED; PG8_LDA(At, 1, 0); PG8_STAGE(PG8_SA(0, 1), a2 + hstep, voffA);
;             PG8_WAIT_V(8); PG8_WAIT_L(0); PG8_BAR; PG8_MMA(0, 0, At, B0); PG8_MMA(0, 1, At, B1); PG8_BAR; PG8_SCHED;
	s_setprio 1
	s_waitcnt lgkmcnt(0)
	v_mfma_f32_16x16x32_bf16 v[60:63], v[128:131], v[198:201], v[60:63]
	v_mfma_f32_16x16x32_bf16 v[56:59], v[136:139], v[198:201], v[56:59]
	v_mfma_f32_16x16x32_bf16 v[48:51], v[128:131], v[206:209], v[48:51]
	v_mfma_f32_16x16x32_bf16 v[40:43], v[136:139], v[206:209], v[40:43]
	v_mfma_f32_16x16x32_bf16 v[32:35], v[128:131], v[214:217], v[32:35]
	v_mfma_f32_16x16x32_bf16 v[24:27], v[136:139], v[214:217], v[24:27]
	v_mfma_f32_16x16x32_bf16 v[16:19], v[128:131], v[222:225], v[16:19]
	v_mfma_f32_16x16x32_bf16 v[8:11], v[136:139], v[222:225], v[8:11]
	v_mfma_f32_16x16x32_bf16 v[60:63], v[132:135], v[202:205], v[60:63]
	v_mfma_f32_16x16x32_bf16 v[56:59], v[140:143], v[202:205], v[56:59]
	v_mfma_f32_16x16x32_bf16 v[48:51], v[132:135], v[210:213], v[48:51]
	v_mfma_f32_16x16x32_bf16 v[40:43], v[140:143], v[210:213], v[40:43]
	v_mfma_f32_16x16x32_bf16 v[32:35], v[132:135], v[218:221], v[32:35]
	v_mfma_f32_16x16x32_bf16 v[24:27], v[140:143], v[218:221], v[24:27]
	v_mfma_f32_16x16x32_bf16 v[16:19], v[132:135], v[226:229], v[16:19]
	v_mfma_f32_16x16x32_bf16 v[8:11], v[140:143], v[226:229], v[8:11]
	v_mfma_f32_16x16x32_bf16 v[52:55], v[168:171], v[198:201], v[52:55]
	v_mfma_f32_16x16x32_bf16 v[44:47], v[190:193], v[198:201], v[44:47]
	v_mfma_f32_16x16x32_bf16 v[36:39], v[168:171], v[206:209], v[36:39]
	v_mfma_f32_16x16x32_bf16 v[28:31], v[190:193], v[206:209], v[28:31]
	v_mfma_f32_16x16x32_bf16 v[20:23], v[168:171], v[214:217], v[20:23]
	v_mfma_f32_16x16x32_bf16 v[12:15], v[190:193], v[214:217], v[12:15]
	v_mfma_f32_16x16x32_bf16 v[4:7], v[168:171], v[222:225], v[4:7]
	v_mfma_f32_16x16x32_bf16 v[0:3], v[190:193], v[222:225], v[0:3]
	v_mfma_f32_16x16x32_bf16 v[52:55], v[182:185], v[202:205], v[52:55]
	v_mfma_f32_16x16x32_bf16 v[44:47], v[194:197], v[202:205], v[44:47]
	v_mfma_f32_16x16x32_bf16 v[36:39], v[182:185], v[210:213], v[36:39]
	v_mfma_f32_16x16x32_bf16 v[28:31], v[194:197], v[210:213], v[28:31]
	v_mfma_f32_16x16x32_bf16 v[20:23], v[182:185], v[218:221], v[20:23]
	v_mfma_f32_16x16x32_bf16 v[12:15], v[194:197], v[218:221], v[12:15]
	v_mfma_f32_16x16x32_bf16 v[4:7], v[182:185], v[226:229], v[4:7]
	v_mfma_f32_16x16x32_bf16 v[0:3], v[194:197], v[226:229], v[0:3]
	s_setprio 0
	s_barrier
	s_add_i32 s54, 0, 0x18000
	s_add_i32 s55, 0, 0x1c000
	v_add_u32_e32 v140, s54, v175
	v_add_u32_e32 v152, s55, v175
	ds_read_b128 v[128:131], v140
	ds_read_b128 v[132:135], v140 offset:1024
	ds_read_b128 v[136:139], v140 offset:2048
	ds_read_b128 v[140:143], v140 offset:3072
	ds_read_b128 v[168:171], v152
	ds_read_b128 v[182:185], v152 offset:1024
	ds_read_b128 v[190:193], v152 offset:2048
	ds_read_b128 v[194:197], v152 offset:3072
	s_add_u32 s44, s44, 0x40000
	s_addc_u32 s45, s45, 0
	s_mov_b32 m0, s59
	v_lshl_add_u64 v[234:235], s[44:45], 0, v[144:145]
	ds_read_b128 v[198:201], v179 offset:32768
	ds_read_b128 v[202:205], v179 offset:33792
	ds_read_b128 v[206:209], v179 offset:34816
	ds_read_b128 v[210:213], v179 offset:35840
	ds_read_b128 v[214:217], v179 offset:36864
	ds_read_b128 v[218:221], v179 offset:37888
	ds_read_b128 v[222:225], v179 offset:38912
	ds_read_b128 v[226:229], v179 offset:39936
	global_load_lds_dwordx4 v[234:235], off
	v_lshl_add_u64 v[234:235], s[44:45], 0, v[148:149]
	s_mov_b32 m0, s60
	s_nop 0
	global_load_lds_dwordx4 v[234:235], off
	s_waitcnt vmcnt(8)
	s_waitcnt lgkmcnt(0)
	s_barrier
	s_setprio 1
	s_waitcnt lgkmcnt(0)
	v_mfma_f32_16x16x32_bf16 v[124:127], v[128:131], v[198:201], v[124:127]
	v_mfma_f32_16x16x32_bf16 v[120:123], v[136:139], v[198:201], v[120:123]
	v_mfma_f32_16x16x32_bf16 v[108:111], v[128:131], v[206:209], v[108:111]
	v_mfma_f32_16x16x32_bf16 v[104:107], v[136:139], v[206:209], v[104:107]
	v_mfma_f32_16x16x32_bf16 v[96:99], v[128:131], v[214:217], v[96:99]
	v_mfma_f32_16x16x32_bf16 v[88:91], v[136:139], v[214:217], v[88:91]
	v_mfma_f32_16x16x32_bf16 v[80:83], v[128:131], v[222:225], v[80:83]
	v_mfma_f32_16x16x32_bf16 v[72:75], v[136:139], v[222:225], v[72:75]
	v_mfma_f32_16x16x32_bf16 v[124:127], v[132:135], v[202:205], v[124:127]
	v_mfma_f32_16x16x32_bf16 v[120:123], v[140:143], v[202:205], v[120:123]
	v_mfma_f32_16x16x32_bf16 v[108:111], v[132:135], v[210:213], v[108:111]
	v_mfma_f32_16x16x32_bf16 v[104:107], v[140:143], v[210:213], v[104:107]
	v_mfma_f32_16x16x32_bf16 v[96:99], v[132:135], v[218:221], v[96:99]
	v_mfma_f32_16x16x32_bf16 v[88:91], v[140:143], v[218:221], v[88:91]
	v_mfma_f32_16x16x32_bf16 v[80:83], v[132:135], v[226:229], v[80:83]
	v_mfma_f32_16x16x32_bf16 v[72:75], v[140:143], v[226:229], v[72:75]
	v_mfma_f32_16x16x32_bf16 v[116:119], v[168:171], v[198:201], v[116:119]
	v_mfma_f32_16x16x32_bf16 v[112:115], v[190:193], v[198:201], v[112:115]
	v_mfma_f32_16x16x32_bf16 v[100:103], v[168:171], v[206:209], v[100:103]
	v_mfma_f32_16x16x32_bf16 v[92:95], v[190:193], v[206:209], v[92:95]
	v_mfma_f32_16x16x32_bf16 v[84:87], v[168:171], v[214:217], v[84:87]
	v_mfma_f32_16x16x32_bf16 v[76:79], v[190:193], v[214:217], v[76:79]
	v_mfma_f32_16x16x32_bf16 v[68:71], v[168:171], v[222:225], v[68:71]
	v_mfma_f32_16x16x32_bf16 v[64:67], v[190:193], v[222:225], v[64:67]
	v_mfma_f32_16x16x32_bf16 v[116:119], v[182:185], v[202:205], v[116:119]
	v_mfma_f32_16x16x32_bf16 v[112:115], v[194:197], v[202:205], v[112:115]
	v_mfma_f32_16x16x32_bf16 v[100:103], v[182:185], v[210:213], v[100:103]
	v_mfma_f32_16x16x32_bf16 v[92:95], v[194:197], v[210:213], v[92:95]
	v_mfma_f32_16x16x32_bf16 v[84:87], v[182:185], v[218:221], v[84:87]
	v_mfma_f32_16x16x32_bf16 v[76:79], v[194:197], v[218:221], v[76:79]
	v_mfma_f32_16x16x32_bf16 v[68:71], v[182:185], v[226:229], v[68:71]
	v_mfma_f32_16x16x32_bf16 v[64:67], v[194:197], v[226:229], v[64:67]
	s_setprio 0
	s_barrier
; #define PG8_STAGE(bufoff, gbase, voff) do { _Pragma("unroll") for (int _i = 0; _i < 2; ++_i) \
;         __builtin_amdgcn_global_load_lds((const unsigned*)((const char*)(gbase) + (voff)[_i]), (PG8_LAS unsigned*)(lds + (bufoff) + ldsw + _i * 8192), 16, 0, 0); } while (0)
; #define PG8_LDA(dst, b, h) do { _Pragma("unroll") for (int m = 0; m < 4; ++m) _Pragma("unroll") for (int k = 0; k < 2; ++k) dst[m][k] = *(const PG8_LAS bf16x8*)(lds + PG8_SA(b, h) + aoff + m * 2048 + k * 1024); } while (0)
; #define PG8_MMA(ai, bj, At, Bt) do { __builtin_amdgcn_s_setprio(1); _Pragma("unroll") for (int m = 0; m < 4; ++m) _Pragma("unroll") for (int n = 0; n < 2; ++n) _Pragma("unroll") for (int k = 0; k < 2; ++k) \
;         acc[ai][bj][m][n] = __builtin_amdgcn_mfma_f32_16x16x32_bf16(Bt[n][k], At[m][k], acc[ai][bj][m][n], 0, 0, 0); __builtin_amdgcn_s_setprio(0); } while (0)
; #define PG8_WAIT_V(n) asm volatile("s_waitcnt vmcnt(" #n ")" ::: "memory")
; #define PG8_WAIT_L(n) asm volatile("s_waitcnt lgkmcnt(" #n ")" ::: "memory")
; #define PG8_BAR __builtin_amdgcn_s_barrier()
; #define PG8_SCHED __builtin_amdgcn_sched_barrier(0)
; template <class Epi, class Sched, bool ALIGN_EPI = false, bool SP2 = false>
; __device__ __forceinline__ void gemm_phase(PG8_LAS unsigned char* lds, const Gemm g, const Sched& S, const Epi& E) {
;     ...
;             PG8_LDA(At, 1, 1); PG8_STAGE(PG8_SB(1, 0), b3, voffB); PG8_STAGE(PG8_SB(1, 1), b3 + hstep, voffB); PG8_STAGE(PG8_SA(1, 0), a3, voffA);
;             PG8_WAIT_V(8); PG8_WAIT_L(0); PG8_BAR; PG8_MMA(1, 0, At, B0); PG8_MMA(1, 1, At, B1); PG8_BAR; PG8_SCHED;
;     ...
;         if constexpr (ALIGN_EPI) { if (wr == 0) PG8_BAR; }
	s_add_i32 s44, s54, s50
	v_lshl_add_u64 v[172:173], v[172:173], 0, s[12:13]
	s_mov_b32 m0, s44
	ds_read_b128 v[198:201], v179 offset:49152
	ds_read_b128 v[202:205], v179 offset:50176
	ds_read_b128 v[206:209], v179 offset:51200
	ds_read_b128 v[210:213], v179 offset:52224
	ds_read_b128 v[214:217], v179 offset:53248
	ds_read_b128 v[218:221], v179 offset:54272
	ds_read_b128 v[222:225], v179 offset:55296
	ds_read_b128 v[226:229], v179 offset:56320
	global_load_lds_dwordx4 v[172:173], off
	s_add_i32 m0, s44, 0x2000
	s_add_u32 s42, s42, 0x40080
	v_lshl_add_u64 v[172:173], v[186:187], 0, s[12:13]
	s_addc_u32 s43, s43, 0
	s_add_i32 s44, s55, s50
	global_load_lds_dwordx4 v[172:173], off
	v_lshl_add_u64 v[172:173], s[42:43], 0, v[146:147]
	s_mov_b32 m0, s44
	s_nop 0
	global_load_lds_dwordx4 v[172:173], off
	v_lshl_add_u64 v[172:173], s[42:43], 0, v[150:151]
	s_add_i32 m0, s44, 0x2000
	s_nop 0
	global_load_lds_dwordx4 v[172:173], off
	v_lshl_add_u64 v[172:173], v[230:231], 0, s[12:13]
	s_mov_b32 m0, s62
	s_nop 0
	global_load_lds_dwordx4 v[172:173], off
	v_lshl_add_u64 v[172:173], v[232:233], 0, s[12:13]
	s_mov_b32 m0, s63
	s_nop 0
	global_load_lds_dwordx4 v[172:173], off
	s_waitcnt vmcnt(8)
	s_waitcnt lgkmcnt(0)
	s_barrier
	s_setprio 1
	s_waitcnt lgkmcnt(0)
	v_mfma_f32_16x16x32_bf16 v[60:63], v[128:131], v[198:201], v[60:63]
	v_mfma_f32_16x16x32_bf16 v[56:59], v[136:139], v[198:201], v[56:59]
	v_mfma_f32_16x16x32_bf16 v[48:51], v[128:131], v[206:209], v[48:51]
	v_mfma_f32_16x16x32_bf16 v[40:43], v[136:139], v[206:209], v[40:43]
	v_mfma_f32_16x16x32_bf16 v[32:35], v[128:131], v[214:217], v[32:35]
	v_mfma_f32_16x16x32_bf16 v[24:27], v[136:139], v[214:217], v[24:27]
	v_mfma_f32_16x16x32_bf16 v[16:19], v[128:131], v[222:225], v[16:19]
	v_mfma_f32_16x16x32_bf16 v[8:11], v[136:139], v[222:225], v[8:11]
	v_mfma_f32_16x16x32_bf16 v[60:63], v[132:135], v[202:205], v[60:63]
	v_mfma_f32_16x16x32_bf16 v[56:59], v[140:143], v[202:205], v[56:59]
	v_mfma_f32_16x16x32_bf16 v[48:51], v[132:135], v[210:213], v[48:51]
	v_mfma_f32_16x16x32_bf16 v[40:43], v[140:143], v[210:213], v[40:43]
	v_mfma_f32_16x16x32_bf16 v[32:35], v[132:135], v[218:221], v[32:35]
	v_mfma_f32_16x16x32_bf16 v[24:27], v[140:143], v[218:221], v[24:27]
	v_mfma_f32_16x16x32_bf16 v[16:19], v[132:135], v[226:229], v[16:19]
	v_mfma_f32_16x16x32_bf16 v[8:11], v[140:143], v[226:229], v[8:11]
	v_mfma_f32_16x16x32_bf16 v[52:55], v[168:171], v[198:201], v[52:55]
	v_mfma_f32_16x16x32_bf16 v[44:47], v[190:193], v[198:201], v[44:47]
	v_mfma_f32_16x16x32_bf16 v[36:39], v[168:171], v[206:209], v[36:39]
	v_mfma_f32_16x16x32_bf16 v[28:31], v[190:193], v[206:209], v[28:31]
	v_mfma_f32_16x16x32_bf16 v[20:23], v[168:171], v[214:217], v[20:23]
	v_mfma_f32_16x16x32_bf16 v[12:15], v[190:193], v[214:217], v[12:15]
	v_mfma_f32_16x16x32_bf16 v[4:7], v[168:171], v[222:225], v[4:7]
	v_mfma_f32_16x16x32_bf16 v[0:3], v[190:193], v[222:225], v[0:3]
	v_mfma_f32_16x16x32_bf16 v[52:55], v[182:185], v[202:205], v[52:55]
	v_mfma_f32_16x16x32_bf16 v[44:47], v[194:197], v[202:205], v[44:47]
	v_mfma_f32_16x16x32_bf16 v[36:39], v[182:185], v[210:213], v[36:39]
	v_mfma_f32_16x16x32_bf16 v[28:31], v[194:197], v[210:213], v[28:31]
	v_mfma_f32_16x16x32_bf16 v[20:23], v[182:185], v[218:221], v[20:23]
	v_mfma_f32_16x16x32_bf16 v[12:15], v[194:197], v[218:221], v[12:15]
	v_mfma_f32_16x16x32_bf16 v[4:7], v[182:185], v[226:229], v[4:7]
	v_mfma_f32_16x16x32_bf16 v[0:3], v[194:197], v[226:229], v[0:3]
	s_setprio 0
	s_barrier
	s_add_i32 vcc_hi, vcc_hi, 2
	s_add_u32 s40, s40, 0x100
	s_addc_u32 s41, s41, 0
	s_add_u32 s97, s97, 0x100
	s_addc_u32 vcc_lo, vcc_lo, 0
	s_cmp_gt_u32 vcc_hi, 13
	s_cbranch_scc0 .LBB0_126
	s_and_b64 vcc, exec, s[14:15]
	s_cbranch_vccz .LBB0_129
	s_barrier

; #define PG8_STAGE(bufoff, gbase, voff) do { _Pragma("unroll") for (int _i = 0; _i < 2; ++_i) \
;         __builtin_amdgcn_global_load_lds((const unsigned*)((const char*)(gbase) + (voff)[_i]), (PG8_LAS unsigned*)(lds + (bufoff) + ldsw + _i * 8192), 16, 0, 0); } while (0)
; #define PG8_LDA(dst, b, h) do { _Pragma("unroll") for (int m = 0; m < 4; ++m) _Pragma("unroll") for (int k = 0; k < 2; ++k) dst[m][k] = *(const PG8_LAS bf16x8*)(lds + PG8_SA(b, h) + aoff + m * 2048 + k * 1024); } while (0)
; #define PG8_LDB(dst, b, h) do { _Pragma("unroll") for (int n = 0; n < 2; ++n) _Pragma("unroll") for (int k = 0; k < 2; ++k) dst[n][k] = *(const PG8_LAS bf16x8*)(lds + PG8_SB(b, h) + boff + n * 2048 + k * 1024); } while (0)
; #define PG8_MMA(ai, bj, At, Bt) do { __builtin_amdgcn_s_setprio(1); _Pragma("unroll") for (int m = 0; m < 4; ++m) _Pragma("unroll") for (int n = 0; n < 2; ++n) _Pragma("unroll") for (int k = 0; k < 2; ++k) \
;         acc[ai][bj][m][n] = __builtin_amdgcn_mfma_f32_16x16x32_bf16(Bt[n][k], At[m][k], acc[ai][bj][m][n], 0, 0, 0); __builtin_amdgcn_s_setprio(0); } while (0)
; #define PG8_WAIT_V(n) asm volatile("s_waitcnt vmcnt(" #n ")" ::: "memory")
; #define PG8_WAIT_L(n) asm volatile("s_waitcnt lgkmcnt(" #n ")" ::: "memory")
; #define PG8_BAR __builtin_amdgcn_s_barrier()
; #define PG8_SCHED __builtin_amdgcn_sched_barrier(0)
; template <class Epi, class Sched, bool ALIGN_EPI = false, bool SP2 = false>
; __device__ __forceinline__ void gemm_phase(PG8_LAS unsigned char* lds, const Gemm g, const Sched& S, const Epi& E) {
;     ...
;             const bool last = (t == nt - 2);
;             const char* a1 = cA + (size_t)(t + 1) * kstep;
;             const char* a2 = last ? nA : cA + (size_t)(t + 2) * kstep; const char* b2 = last ? nB : cB + (size_t)(t + 2) * kstep;
;             const char* a3 = a2 + kstep; const char* b3 = b2 + kstep;
;             if (last && has_next) S.a_ready(nxt);
;             if constexpr (SP2) {
;             PG8_LDB(B0, 0, 0); PG8_LDB(B1, 0, 1); PG8_SCHED; PG8_LDA(At, 0, 0); PG8_STAGE(PG8_SA(1, 1), a1 + hstep, voffA);
;             PG8_WAIT_V(8); PG8_WAIT_L(0); PG8_BAR; PG8_MMA(0, 0, At, B0); PG8_MMA(0, 1, At, B1); PG8_BAR; PG8_SCHED;
;             PG8_LDA(At, 0, 1); PG8_STAGE(PG8_SB(0, 0), b2, voffB); PG8_STAGE(PG8_SB(0, 1), b2 + hstep, voffB); PG8_STAGE(PG8_SA(0, 0), a2, voffA);
.LBB0_327:
	ds_read_b128 v[152:155], v193
	ds_read_b128 v[156:159], v193 offset:1024
	ds_read_b128 v[160:163], v193 offset:2048
	ds_read_b128 v[164:167], v193 offset:3072
	ds_read_b128 v[168:171], v194
	ds_read_b128 v[172:175], v194 offset:1024
	ds_read_b128 v[176:179], v194 offset:2048
	ds_read_b128 v[180:183], v194 offset:3072
	s_add_u32 s44, s42, 0xfffc0080
	s_addc_u32 s45, s43, -1
	s_cmp_eq_u32 vcc_hi, 12
	s_cselect_b32 s47, s35, s45
	s_cselect_b32 s46, s41, s44
	s_cselect_b32 s45, s31, vcc_lo
	s_cselect_b32 s44, s96, s97
	v_lshl_add_u64 v[224:225], s[42:43], 0, v[144:145]
	s_add_i32 m0, s53, 0xc000
	ds_read_b128 v[184:187], v195
	ds_read_b128 v[196:199], v195 offset:1024
	ds_read_b128 v[200:203], v195 offset:2048
	ds_read_b128 v[204:207], v195 offset:3072
	ds_read_b128 v[208:211], v195 offset:4096
	ds_read_b128 v[212:215], v195 offset:5120
	ds_read_b128 v[216:219], v195 offset:6144
	ds_read_b128 v[220:223], v195 offset:7168
	global_load_lds_dwordx4 v[224:225], off
	v_lshl_add_u64 v[224:225], s[42:43], 0, v[146:147]
	s_add_i32 m0, s53, 0xe000
	s_nop 0
	global_load_lds_dwordx4 v[224:225], off
	s_waitcnt vmcnt(8)
	s_waitcnt lgkmcnt(0)
	s_barrier
	s_setprio 1
	s_waitcnt lgkmcnt(0)
	v_mfma_f32_16x16x32_bf16 v[124:127], v[152:155], v[184:187], v[124:127]
	v_mfma_f32_16x16x32_bf16 v[120:123], v[160:163], v[184:187], v[120:123]
	v_mfma_f32_16x16x32_bf16 v[108:111], v[152:155], v[200:203], v[108:111]
	v_mfma_f32_16x16x32_bf16 v[104:107], v[160:163], v[200:203], v[104:107]
	v_mfma_f32_16x16x32_bf16 v[92:95], v[152:155], v[208:211], v[92:95]
	v_mfma_f32_16x16x32_bf16 v[88:91], v[160:163], v[208:211], v[88:91]
	v_mfma_f32_16x16x32_bf16 v[76:79], v[152:155], v[216:219], v[76:79]
	v_mfma_f32_16x16x32_bf16 v[72:75], v[160:163], v[216:219], v[72:75]
	v_mfma_f32_16x16x32_bf16 v[124:127], v[156:159], v[196:199], v[124:127]
	v_mfma_f32_16x16x32_bf16 v[120:123], v[164:167], v[196:199], v[120:123]
	v_mfma_f32_16x16x32_bf16 v[108:111], v[156:159], v[204:207], v[108:111]
	v_mfma_f32_16x16x32_bf16 v[104:107], v[164:167], v[204:207], v[104:107]
	v_mfma_f32_16x16x32_bf16 v[92:95], v[156:159], v[212:215], v[92:95]
	v_mfma_f32_16x16x32_bf16 v[88:91], v[164:167], v[212:215], v[88:91]
	v_mfma_f32_16x16x32_bf16 v[76:79], v[156:159], v[220:223], v[76:79]
	v_mfma_f32_16x16x32_bf16 v[72:75], v[164:167], v[220:223], v[72:75]
	v_mfma_f32_16x16x32_bf16 v[116:119], v[168:171], v[184:187], v[116:119]
	v_mfma_f32_16x16x32_bf16 v[112:115], v[176:179], v[184:187], v[112:115]
	v_mfma_f32_16x16x32_bf16 v[100:103], v[168:171], v[200:203], v[100:103]
	v_mfma_f32_16x16x32_bf16 v[96:99], v[176:179], v[200:203], v[96:99]
	v_mfma_f32_16x16x32_bf16 v[84:87], v[168:171], v[208:211], v[84:87]
	v_mfma_f32_16x16x32_bf16 v[80:83], v[176:179], v[208:211], v[80:83]
	v_mfma_f32_16x16x32_bf16 v[68:71], v[168:171], v[216:219], v[68:71]
	v_mfma_f32_16x16x32_bf16 v[64:67], v[176:179], v[216:219], v[64:67]
	v_mfma_f32_16x16x32_bf16 v[116:119], v[172:175], v[196:199], v[116:119]
	v_mfma_f32_16x16x32_bf16 v[112:115], v[180:183], v[196:199], v[112:115]
	v_mfma_f32_16x16x32_bf16 v[100:103], v[172:175], v[204:207], v[100:103]
	v_mfma_f32_16x16x32_bf16 v[96:99], v[180:183], v[204:207], v[96:99]
	v_mfma_f32_16x16x32_bf16 v[84:87], v[172:175], v[212:215], v[84:87]
	v_mfma_f32_16x16x32_bf16 v[80:83], v[180:183], v[212:215], v[80:83]
	v_mfma_f32_16x16x32_bf16 v[68:71], v[172:175], v[220:223], v[68:71]
	v_mfma_f32_16x16x32_bf16 v[64:67], v[180:183], v[220:223], v[64:67]
	s_setprio 0
	s_barrier
	s_add_i32 s54, s72, s50
	v_lshl_add_u64 v[224:225], s[44:45], 0, v[132:133]
	s_mov_b32 m0, s54
	ds_read_b128 v[184:187], v195 offset:16384
	ds_read_b128 v[196:199], v195 offset:17408
	ds_read_b128 v[200:203], v195 offset:18432
	ds_read_b128 v[204:207], v195 offset:19456
	ds_read_b128 v[208:211], v195 offset:20480
	ds_read_b128 v[212:215], v195 offset:21504
	ds_read_b128 v[216:219], v195 offset:22528
	ds_read_b128 v[220:223], v195 offset:23552
	global_load_lds_dwordx4 v[224:225], off
	s_add_i32 m0, s54, 0x2000
	s_add_u32 s84, s44, 0x40000
	v_lshl_add_u64 v[226:227], s[44:45], 0, v[128:129]
	s_addc_u32 s85, s45, 0
	s_add_i32 s54, s73, s50
	global_load_lds_dwordx4 v[226:227], off
	v_lshl_add_u64 v[228:229], s[84:85], 0, v[132:133]
	s_mov_b32 m0, s54
	v_lshl_add_u64 v[230:231], s[46:47], 0, v[130:131]
	global_load_lds_dwordx4 v[228:229], off
	v_lshl_add_u64 v[228:229], s[84:85], 0, v[128:129]
	s_add_i32 m0, s54, 0x2000
	s_nop 0
	global_load_lds_dwordx4 v[228:229], off
	v_lshl_add_u64 v[228:229], s[46:47], 0, v[134:135]
	s_mov_b32 m0, s53
	s_nop 0
	global_load_lds_dwordx4 v[228:229], off
	s_mov_b32 m0, s58
	s_nop 0
	global_load_lds_dwordx4 v[230:231], off
	s_waitcnt vmcnt(8)
	s_waitcnt lgkmcnt(0)
	s_barrier
; #define PG8_STAGE(bufoff, gbase, voff) do { _Pragma("unroll") for (int _i = 0; _i < 2; ++_i) \
;         __builtin_amdgcn_global_load_lds((const unsigned*)((const char*)(gbase) + (voff)[_i]), (PG8_LAS unsigned*)(lds + (bufoff) + ldsw + _i * 8192), 16, 0, 0); } while (0)
; #define PG8_LDA(dst, b, h) do { _Pragma("unroll") for (int m = 0; m < 4; ++m) _Pragma("unroll") for (int k = 0; k < 2; ++k) dst[m][k] = *(const PG8_LAS bf16x8*)(lds + PG8_SA(b, h) + aoff + m * 2048 + k * 1024); } while (0)
; #define PG8_LDB(dst, b, h) do { _Pragma("unroll") for (int n = 0; n < 2; ++n) _Pragma("unroll") for (int k = 0; k < 2; ++k) dst[n][k] = *(const PG8_LAS bf16x8*)(lds + PG8_SB(b, h) + boff + n * 2048 + k * 1024); } while (0)
; #define PG8_MMA(ai, bj, At, Bt) do { __builtin_amdgcn_s_setprio(1); _Pragma("unroll") for (int m = 0; m < 4; ++m) _Pragma("unroll") for (int n = 0; n < 2; ++n) _Pragma("unroll") for (int k = 0; k < 2; ++k) \
;         acc[ai][bj][m][n] = __builtin_amdgcn_mfma_f32_16x16x32_bf16(Bt[n][k], At[m][k], acc[ai][bj][m][n], 0, 0, 0); __builtin_amdgcn_s_setprio(0); } while (0)
; #define PG8_WAIT_V(n) asm volatile("s_waitcnt vmcnt(" #n ")" ::: "memory")
; #define PG8_WAIT_L(n) asm volatile("s_waitcnt lgkmcnt(" #n ")" ::: "memory")
; #define PG8_BAR __builtin_amdgcn_s_barrier()
; #define PG8_SCHED __builtin_amdgcn_sched_barrier(0)
; template <class Epi, class Sched, bool ALIGN_EPI = false, bool SP2 = false>
; __device__ __forceinline__ void gemm_phase(PG8_LAS unsigned char* lds, const Gemm g, const Sched& S, const Epi& E) {
;     ...
;             PG8_WAIT_V(8); PG8_WAIT_L(0); PG8_BAR; PG8_MMA(1, 0, At, B0); PG8_MMA(1, 1, At, B1); PG8_BAR; PG8_SCHED;
;             PG8_LDB(B0, 1, 0); PG8_LDB(B1, 1, 1); PG8_SCHED; PG8_LDA(At, 1, 0); PG8_STAGE(PG8_SA(0, 1), a2 + hstep, voffA);
;             PG8_WAIT_V(8); PG8_WAIT_L(0); PG8_BAR; PG8_MMA(0, 0, At, B0); PG8_MMA(0, 1, At, B1); PG8_BAR; PG8_SCHED;
	s_setprio 1
	s_waitcnt lgkmcnt(0)
	v_mfma_f32_16x16x32_bf16 v[60:63], v[152:155], v[184:187], v[60:63]
	v_mfma_f32_16x16x32_bf16 v[56:59], v[160:163], v[184:187], v[56:59]
	v_mfma_f32_16x16x32_bf16 v[44:47], v[152:155], v[200:203], v[44:47]
	v_mfma_f32_16x16x32_bf16 v[40:43], v[160:163], v[200:203], v[40:43]
	v_mfma_f32_16x16x32_bf16 v[28:31], v[152:155], v[208:211], v[28:31]
	v_mfma_f32_16x16x32_bf16 v[24:27], v[160:163], v[208:211], v[24:27]
	v_mfma_f32_16x16x32_bf16 v[12:15], v[152:155], v[216:219], v[12:15]
	v_mfma_f32_16x16x32_bf16 v[8:11], v[160:163], v[216:219], v[8:11]
	v_mfma_f32_16x16x32_bf16 v[60:63], v[156:159], v[196:199], v[60:63]
	v_mfma_f32_16x16x32_bf16 v[56:59], v[164:167], v[196:199], v[56:59]
	v_mfma_f32_16x16x32_bf16 v[44:47], v[156:159], v[204:207], v[44:47]
	v_mfma_f32_16x16x32_bf16 v[40:43], v[164:167], v[204:207], v[40:43]
	v_mfma_f32_16x16x32_bf16 v[28:31], v[156:159], v[212:215], v[28:31]
	v_mfma_f32_16x16x32_bf16 v[24:27], v[164:167], v[212:215], v[24:27]
	v_mfma_f32_16x16x32_bf16 v[12:15], v[156:159], v[220:223], v[12:15]
	v_mfma_f32_16x16x32_bf16 v[8:11], v[164:167], v[220:223], v[8:11]
	v_mfma_f32_16x16x32_bf16 v[52:55], v[168:171], v[184:187], v[52:55]
	v_mfma_f32_16x16x32_bf16 v[48:51], v[176:179], v[184:187], v[48:51]
	v_mfma_f32_16x16x32_bf16 v[36:39], v[168:171], v[200:203], v[36:39]
	v_mfma_f32_16x16x32_bf16 v[32:35], v[176:179], v[200:203], v[32:35]
	v_mfma_f32_16x16x32_bf16 v[20:23], v[168:171], v[208:211], v[20:23]
	v_mfma_f32_16x16x32_bf16 v[16:19], v[176:179], v[208:211], v[16:19]
	v_mfma_f32_16x16x32_bf16 v[4:7], v[168:171], v[216:219], v[4:7]
	v_mfma_f32_16x16x32_bf16 v[0:3], v[176:179], v[216:219], v[0:3]
	v_mfma_f32_16x16x32_bf16 v[52:55], v[172:175], v[196:199], v[52:55]
	v_mfma_f32_16x16x32_bf16 v[48:51], v[180:183], v[196:199], v[48:51]
	v_mfma_f32_16x16x32_bf16 v[36:39], v[172:175], v[204:207], v[36:39]
	v_mfma_f32_16x16x32_bf16 v[32:35], v[180:183], v[204:207], v[32:35]
	v_mfma_f32_16x16x32_bf16 v[20:23], v[172:175], v[212:215], v[20:23]
	v_mfma_f32_16x16x32_bf16 v[16:19], v[180:183], v[212:215], v[16:19]
	v_mfma_f32_16x16x32_bf16 v[4:7], v[172:175], v[220:223], v[4:7]
	v_mfma_f32_16x16x32_bf16 v[0:3], v[180:183], v[220:223], v[0:3]
	s_setprio 0
	s_barrier
	s_add_i32 s54, 0, 0x18000
	v_add_u32_e32 v136, s54, v190
	s_add_i32 s55, 0, 0x1c000
	ds_read_b128 v[152:155], v136
	ds_read_b128 v[156:159], v136 offset:1024
	ds_read_b128 v[160:163], v136 offset:2048
	ds_read_b128 v[164:167], v136 offset:3072
	v_add_u32_e32 v136, s55, v190
	ds_read_b128 v[168:171], v136
	ds_read_b128 v[172:175], v136 offset:1024
	ds_read_b128 v[176:179], v136 offset:2048
	ds_read_b128 v[180:183], v136 offset:3072
	s_add_u32 s46, s46, 0x40000
	s_addc_u32 s47, s47, 0
	s_mov_b32 m0, s59
	v_lshl_add_u64 v[232:233], s[46:47], 0, v[134:135]
	ds_read_b128 v[184:187], v195 offset:32768
	ds_read_b128 v[196:199], v195 offset:33792
	ds_read_b128 v[200:203], v195 offset:34816
	ds_read_b128 v[204:207], v195 offset:35840
	ds_read_b128 v[208:211], v195 offset:36864
	ds_read_b128 v[212:215], v195 offset:37888
	ds_read_b128 v[216:219], v195 offset:38912
	ds_read_b128 v[220:223], v195 offset:39936
	global_load_lds_dwordx4 v[232:233], off
	v_lshl_add_u64 v[232:233], s[46:47], 0, v[130:131]
	s_mov_b32 m0, s60
	s_nop 0
	global_load_lds_dwordx4 v[232:233], off
	s_waitcnt vmcnt(8)
	s_waitcnt lgkmcnt(0)
	s_barrier
	s_setprio 1
	s_waitcnt lgkmcnt(0)
	v_mfma_f32_16x16x32_bf16 v[124:127], v[152:155], v[184:187], v[124:127]
	v_mfma_f32_16x16x32_bf16 v[120:123], v[160:163], v[184:187], v[120:123]
	v_mfma_f32_16x16x32_bf16 v[108:111], v[152:155], v[200:203], v[108:111]
	v_mfma_f32_16x16x32_bf16 v[104:107], v[160:163], v[200:203], v[104:107]
	v_mfma_f32_16x16x32_bf16 v[92:95], v[152:155], v[208:211], v[92:95]
	v_mfma_f32_16x16x32_bf16 v[88:91], v[160:163], v[208:211], v[88:91]
	v_mfma_f32_16x16x32_bf16 v[76:79], v[152:155], v[216:219], v[76:79]
	v_mfma_f32_16x16x32_bf16 v[72:75], v[160:163], v[216:219], v[72:75]
	v_mfma_f32_16x16x32_bf16 v[124:127], v[156:159], v[196:199], v[124:127]
	v_mfma_f32_16x16x32_bf16 v[120:123], v[164:167], v[196:199], v[120:123]
	v_mfma_f32_16x16x32_bf16 v[108:111], v[156:159], v[204:207], v[108:111]
	v_mfma_f32_16x16x32_bf16 v[104:107], v[164:167], v[204:207], v[104:107]
	v_mfma_f32_16x16x32_bf16 v[92:95], v[156:159], v[212:215], v[92:95]
	v_mfma_f32_16x16x32_bf16 v[88:91], v[164:167], v[212:215], v[88:91]
	v_mfma_f32_16x16x32_bf16 v[76:79], v[156:159], v[220:223], v[76:79]
	v_mfma_f32_16x16x32_bf16 v[72:75], v[164:167], v[220:223], v[72:75]
	v_mfma_f32_16x16x32_bf16 v[116:119], v[168:171], v[184:187], v[116:119]
	v_mfma_f32_16x16x32_bf16 v[112:115], v[176:179], v[184:187], v[112:115]
	v_mfma_f32_16x16x32_bf16 v[100:103], v[168:171], v[200:203], v[100:103]
	v_mfma_f32_16x16x32_bf16 v[96:99], v[176:179], v[200:203], v[96:99]
	v_mfma_f32_16x16x32_bf16 v[84:87], v[168:171], v[208:211], v[84:87]
	v_mfma_f32_16x16x32_bf16 v[80:83], v[176:179], v[208:211], v[80:83]
	v_mfma_f32_16x16x32_bf16 v[68:71], v[168:171], v[216:219], v[68:71]
	v_mfma_f32_16x16x32_bf16 v[64:67], v[176:179], v[216:219], v[64:67]
	v_mfma_f32_16x16x32_bf16 v[116:119], v[172:175], v[196:199], v[116:119]
	v_mfma_f32_16x16x32_bf16 v[112:115], v[180:183], v[196:199], v[112:115]
	v_mfma_f32_16x16x32_bf16 v[100:103], v[172:175], v[204:207], v[100:103]
	v_mfma_f32_16x16x32_bf16 v[96:99], v[180:183], v[204:207], v[96:99]
	v_mfma_f32_16x16x32_bf16 v[84:87], v[172:175], v[212:215], v[84:87]
	v_mfma_f32_16x16x32_bf16 v[80:83], v[180:183], v[212:215], v[80:83]
	v_mfma_f32_16x16x32_bf16 v[68:71], v[172:175], v[220:223], v[68:71]
	v_mfma_f32_16x16x32_bf16 v[64:67], v[180:183], v[220:223], v[64:67]
	s_setprio 0
	s_barrier
; #define PG8_STAGE(bufoff, gbase, voff) do { _Pragma("unroll") for (int _i = 0; _i < 2; ++_i) \
;         __builtin_amdgcn_global_load_lds((const unsigned*)((const char*)(gbase) + (voff)[_i]), (PG8_LAS unsigned*)(lds + (bufoff) + ldsw + _i * 8192), 16, 0, 0); } while (0)
; #define PG8_LDA(dst, b, h) do { _Pragma("unroll") for (int m = 0; m < 4; ++m) _Pragma("unroll") for (int k = 0; k < 2; ++k) dst[m][k] = *(const PG8_LAS bf16x8*)(lds + PG8_SA(b, h) + aoff + m * 2048 + k * 1024); } while (0)
; #define PG8_MMA(ai, bj, At, Bt) do { __builtin_amdgcn_s_setprio(1); _Pragma("unroll") for (int m = 0; m < 4; ++m) _Pragma("unroll") for (int n = 0; n < 2; ++n) _Pragma("unroll") for (int k = 0; k < 2; ++k) \
;         acc[ai][bj][m][n] = __builtin_amdgcn_mfma_f32_16x16x32_bf16(Bt[n][k], At[m][k], acc[ai][bj][m][n], 0, 0, 0); __builtin_amdgcn_s_setprio(0); } while (0)
; #define PG8_WAIT_V(n) asm volatile("s_waitcnt vmcnt(" #n ")" ::: "memory")
; #define PG8_WAIT_L(n) asm volatile("s_waitcnt lgkmcnt(" #n ")" ::: "memory")
; #define PG8_BAR __builtin_amdgcn_s_barrier()
; #define PG8_SCHED __builtin_amdgcn_sched_barrier(0)
; template <class Epi, class Sched, bool ALIGN_EPI = false, bool SP2 = false>
; __device__ __forceinline__ void gemm_phase(PG8_LAS unsigned char* lds, const Gemm g, const Sched& S, const Epi& E) {
;     ...
;             PG8_LDA(At, 1, 1); PG8_STAGE(PG8_SB(1, 0), b3, voffB); PG8_STAGE(PG8_SB(1, 1), b3 + hstep, voffB); PG8_STAGE(PG8_SA(1, 0), a3, voffA);
;             PG8_WAIT_V(8); PG8_WAIT_L(0); PG8_BAR; PG8_MMA(1, 0, At, B0); PG8_MMA(1, 1, At, B1); PG8_BAR; PG8_SCHED;
;     ...
;         if constexpr (ALIGN_EPI) { if (wr == 0) PG8_BAR; }
	s_add_i32 s46, s54, s50
	v_lshl_add_u64 v[224:225], v[224:225], 0, s[8:9]
	s_mov_b32 m0, s46
	ds_read_b128 v[184:187], v195 offset:49152
	ds_read_b128 v[196:199], v195 offset:50176
	ds_read_b128 v[200:203], v195 offset:51200
	ds_read_b128 v[204:207], v195 offset:52224
	ds_read_b128 v[208:211], v195 offset:53248
	ds_read_b128 v[212:215], v195 offset:54272
	ds_read_b128 v[216:219], v195 offset:55296
	ds_read_b128 v[220:223], v195 offset:56320
	global_load_lds_dwordx4 v[224:225], off
	s_add_i32 m0, s46, 0x2000
	s_add_u32 s44, s44, 0x40080
	v_lshl_add_u64 v[224:225], v[226:227], 0, s[8:9]
	s_addc_u32 s45, s45, 0
	s_add_i32 s46, s55, s50
	global_load_lds_dwordx4 v[224:225], off
	v_lshl_add_u64 v[224:225], s[44:45], 0, v[132:133]
	s_mov_b32 m0, s46
	s_nop 0
	global_load_lds_dwordx4 v[224:225], off
	v_lshl_add_u64 v[224:225], s[44:45], 0, v[128:129]
	s_add_i32 m0, s46, 0x2000
	s_nop 0
	global_load_lds_dwordx4 v[224:225], off
	v_lshl_add_u64 v[224:225], v[228:229], 0, s[8:9]
	s_mov_b32 m0, s68
	s_nop 0
	global_load_lds_dwordx4 v[224:225], off
	v_lshl_add_u64 v[224:225], v[230:231], 0, s[8:9]
	s_mov_b32 m0, s69
	s_nop 0
	global_load_lds_dwordx4 v[224:225], off
	s_waitcnt vmcnt(8)
	s_waitcnt lgkmcnt(0)
	s_barrier
	s_setprio 1
	s_waitcnt lgkmcnt(0)
	v_mfma_f32_16x16x32_bf16 v[60:63], v[152:155], v[184:187], v[60:63]
	v_mfma_f32_16x16x32_bf16 v[56:59], v[160:163], v[184:187], v[56:59]
	v_mfma_f32_16x16x32_bf16 v[44:47], v[152:155], v[200:203], v[44:47]
	v_mfma_f32_16x16x32_bf16 v[40:43], v[160:163], v[200:203], v[40:43]
	v_mfma_f32_16x16x32_bf16 v[28:31], v[152:155], v[208:211], v[28:31]
	v_mfma_f32_16x16x32_bf16 v[24:27], v[160:163], v[208:211], v[24:27]
	v_mfma_f32_16x16x32_bf16 v[12:15], v[152:155], v[216:219], v[12:15]
	v_mfma_f32_16x16x32_bf16 v[8:11], v[160:163], v[216:219], v[8:11]
	v_mfma_f32_16x16x32_bf16 v[60:63], v[156:159], v[196:199], v[60:63]
	v_mfma_f32_16x16x32_bf16 v[56:59], v[164:167], v[196:199], v[56:59]
	v_mfma_f32_16x16x32_bf16 v[44:47], v[156:159], v[204:207], v[44:47]
	v_mfma_f32_16x16x32_bf16 v[40:43], v[164:167], v[204:207], v[40:43]
	v_mfma_f32_16x16x32_bf16 v[28:31], v[156:159], v[212:215], v[28:31]
	v_mfma_f32_16x16x32_bf16 v[24:27], v[164:167], v[212:215], v[24:27]
	v_mfma_f32_16x16x32_bf16 v[12:15], v[156:159], v[220:223], v[12:15]
	v_mfma_f32_16x16x32_bf16 v[8:11], v[164:167], v[220:223], v[8:11]
	v_mfma_f32_16x16x32_bf16 v[52:55], v[168:171], v[184:187], v[52:55]
	v_mfma_f32_16x16x32_bf16 v[48:51], v[176:179], v[184:187], v[48:51]
	v_mfma_f32_16x16x32_bf16 v[36:39], v[168:171], v[200:203], v[36:39]
	v_mfma_f32_16x16x32_bf16 v[32:35], v[176:179], v[200:203], v[32:35]
	v_mfma_f32_16x16x32_bf16 v[20:23], v[168:171], v[208:211], v[20:23]
	v_mfma_f32_16x16x32_bf16 v[16:19], v[176:179], v[208:211], v[16:19]
	v_mfma_f32_16x16x32_bf16 v[4:7], v[168:171], v[216:219], v[4:7]
	v_mfma_f32_16x16x32_bf16 v[0:3], v[176:179], v[216:219], v[0:3]
	v_mfma_f32_16x16x32_bf16 v[52:55], v[172:175], v[196:199], v[52:55]
	v_mfma_f32_16x16x32_bf16 v[48:51], v[180:183], v[196:199], v[48:51]
	v_mfma_f32_16x16x32_bf16 v[36:39], v[172:175], v[204:207], v[36:39]
	v_mfma_f32_16x16x32_bf16 v[32:35], v[180:183], v[204:207], v[32:35]
	v_mfma_f32_16x16x32_bf16 v[20:23], v[172:175], v[212:215], v[20:23]
	v_mfma_f32_16x16x32_bf16 v[16:19], v[180:183], v[212:215], v[16:19]
	v_mfma_f32_16x16x32_bf16 v[4:7], v[172:175], v[220:223], v[4:7]
	v_mfma_f32_16x16x32_bf16 v[0:3], v[180:183], v[220:223], v[0:3]
	s_setprio 0
	s_barrier
	s_add_i32 vcc_hi, vcc_hi, 2
	s_add_u32 s42, s42, 0x100
	s_addc_u32 s43, s43, 0
	s_add_u32 s97, s97, 0x100
	s_addc_u32 vcc_lo, vcc_lo, 0
	s_cmp_gt_u32 vcc_hi, 13
	s_cbranch_scc0 .LBB0_327
	s_and_b64 vcc, exec, s[10:11]
	s_cbranch_vccz .LBB0_330
	s_barrier

; #define PG8_STAGE(bufoff, gbase, voff) do { _Pragma("unroll") for (int _i = 0; _i < 2; ++_i) \
;         __builtin_amdgcn_global_load_lds((const unsigned*)((const char*)(gbase) + (voff)[_i]), (PG8_LAS unsigned*)(lds + (bufoff) + ldsw + _i * 8192), 16, 0, 0); } while (0)
; #define PG8_LDA(dst, b, h) do { _Pragma("unroll") for (int m = 0; m < 4; ++m) _Pragma("unroll") for (int k = 0; k < 2; ++k) dst[m][k] = *(const PG8_LAS bf16x8*)(lds + PG8_SA(b, h) + aoff + m * 2048 + k * 1024); } while (0)
; #define PG8_LDB(dst, b, h) do { _Pragma("unroll") for (int n = 0; n < 2; ++n) _Pragma("unroll") for (int k = 0; k < 2; ++k) dst[n][k] = *(const PG8_LAS bf16x8*)(lds + PG8_SB(b, h) + boff + n * 2048 + k * 1024); } while (0)
; #define PG8_MMA(ai, bj, At, Bt) do { __builtin_amdgcn_s_setprio(1); _Pragma("unroll") for (int m = 0; m < 4; ++m) _Pragma("unroll") for (int n = 0; n < 2; ++n) _Pragma("unroll") for (int k = 0; k < 2; ++k) \
;         acc[ai][bj][m][n] = __builtin_amdgcn_mfma_f32_16x16x32_bf16(Bt[n][k], At[m][k], acc[ai][bj][m][n], 0, 0, 0); __builtin_amdgcn_s_setprio(0); } while (0)
; #define PG8_WAIT_V(n) asm volatile("s_waitcnt vmcnt(" #n ")" ::: "memory")
; #define PG8_WAIT_L(n) asm volatile("s_waitcnt lgkmcnt(" #n ")" ::: "memory")
; #define PG8_BAR __builtin_amdgcn_s_barrier()
; #define PG8_SCHED __builtin_amdgcn_sched_barrier(0)
; template <class Epi, class Sched, bool ALIGN_EPI = false, bool SP2 = false>
; __device__ __forceinline__ void gemm_phase(PG8_LAS unsigned char* lds, const Gemm g, const Sched& S, const Epi& E) {
;     ...
;             const bool last = (t == nt - 2);
;             const char* a1 = cA + (size_t)(t + 1) * kstep;
;             const char* a2 = last ? nA : cA + (size_t)(t + 2) * kstep; const char* b2 = last ? nB : cB + (size_t)(t + 2) * kstep;
;             const char* a3 = a2 + kstep; const char* b3 = b2 + kstep;
;             if (last && has_next) S.a_ready(nxt);
;             if constexpr (SP2) {
;             PG8_LDB(B0, 0, 0); PG8_LDB(B1, 0, 1); PG8_SCHED; PG8_LDA(At, 0, 0); PG8_STAGE(PG8_SA(1, 1), a1 + hstep, voffA);
;             PG8_WAIT_V(8); PG8_WAIT_L(0); PG8_BAR; PG8_MMA(0, 0, At, B0); PG8_MMA(0, 1, At, B1); PG8_BAR; PG8_SCHED;
;             PG8_LDA(At, 0, 1); PG8_STAGE(PG8_SB(0, 0), b2, voffB); PG8_STAGE(PG8_SB(0, 1), b2 + hstep, voffB); PG8_STAGE(PG8_SA(0, 0), a2, voffA);
.LBB0_421:
	ds_read_b128 v[150:153], v139
	ds_read_b128 v[154:157], v139 offset:1024
	ds_read_b128 v[158:161], v139 offset:2048
	ds_read_b128 v[162:165], v139 offset:3072
	ds_read_b128 v[166:169], v196
	ds_read_b128 v[170:173], v196 offset:1024
	ds_read_b128 v[174:177], v196 offset:2048
	ds_read_b128 v[178:181], v196 offset:3072
	s_add_u32 s44, s42, 0xfffc0080
	s_addc_u32 s45, s43, -1
	s_cmp_eq_u32 s96, 12
	s_cselect_b32 s47, s90, s45
	s_cselect_b32 s46, s91, s44
	s_cselect_b32 s45, s92, s95
	s_cselect_b32 s44, s93, s94
	v_lshl_add_u64 v[226:227], s[42:43], 0, v[146:147]
	s_add_i32 m0, s63, 0xc000
	ds_read_b128 v[182:185], v197
	ds_read_b128 v[198:201], v197 offset:1024
	ds_read_b128 v[202:205], v197 offset:2048
	ds_read_b128 v[206:209], v197 offset:3072
	ds_read_b128 v[210:213], v197 offset:4096
	ds_read_b128 v[214:217], v197 offset:5120
	ds_read_b128 v[218:221], v197 offset:6144
	ds_read_b128 v[222:225], v197 offset:7168
	global_load_lds_dwordx4 v[226:227], off
	v_lshl_add_u64 v[226:227], s[42:43], 0, v[148:149]
	s_add_i32 m0, s63, 0xe000
	s_nop 0
	global_load_lds_dwordx4 v[226:227], off
	s_waitcnt vmcnt(8)
	s_waitcnt lgkmcnt(0)
	s_barrier
	s_setprio 1
	s_waitcnt lgkmcnt(0)
	v_mfma_f32_16x16x32_bf16 v[124:127], v[150:153], v[182:185], v[124:127]
	v_mfma_f32_16x16x32_bf16 v[120:123], v[158:161], v[182:185], v[120:123]
	v_mfma_f32_16x16x32_bf16 v[108:111], v[150:153], v[202:205], v[108:111]
	v_mfma_f32_16x16x32_bf16 v[104:107], v[158:161], v[202:205], v[104:107]
	v_mfma_f32_16x16x32_bf16 v[92:95], v[150:153], v[210:213], v[92:95]
	v_mfma_f32_16x16x32_bf16 v[88:91], v[158:161], v[210:213], v[88:91]
	v_mfma_f32_16x16x32_bf16 v[76:79], v[150:153], v[218:221], v[76:79]
	v_mfma_f32_16x16x32_bf16 v[72:75], v[158:161], v[218:221], v[72:75]
	v_mfma_f32_16x16x32_bf16 v[124:127], v[154:157], v[198:201], v[124:127]
	v_mfma_f32_16x16x32_bf16 v[120:123], v[162:165], v[198:201], v[120:123]
	v_mfma_f32_16x16x32_bf16 v[108:111], v[154:157], v[206:209], v[108:111]
	v_mfma_f32_16x16x32_bf16 v[104:107], v[162:165], v[206:209], v[104:107]
	v_mfma_f32_16x16x32_bf16 v[92:95], v[154:157], v[214:217], v[92:95]
	v_mfma_f32_16x16x32_bf16 v[88:91], v[162:165], v[214:217], v[88:91]
	v_mfma_f32_16x16x32_bf16 v[76:79], v[154:157], v[222:225], v[76:79]
	v_mfma_f32_16x16x32_bf16 v[72:75], v[162:165], v[222:225], v[72:75]
	v_mfma_f32_16x16x32_bf16 v[116:119], v[166:169], v[182:185], v[116:119]
	v_mfma_f32_16x16x32_bf16 v[112:115], v[174:177], v[182:185], v[112:115]
	v_mfma_f32_16x16x32_bf16 v[100:103], v[166:169], v[202:205], v[100:103]
	v_mfma_f32_16x16x32_bf16 v[96:99], v[174:177], v[202:205], v[96:99]
	v_mfma_f32_16x16x32_bf16 v[84:87], v[166:169], v[210:213], v[84:87]
	v_mfma_f32_16x16x32_bf16 v[80:83], v[174:177], v[210:213], v[80:83]
	v_mfma_f32_16x16x32_bf16 v[68:71], v[166:169], v[218:221], v[68:71]
	v_mfma_f32_16x16x32_bf16 v[64:67], v[174:177], v[218:221], v[64:67]
	v_mfma_f32_16x16x32_bf16 v[116:119], v[170:173], v[198:201], v[116:119]
	v_mfma_f32_16x16x32_bf16 v[112:115], v[178:181], v[198:201], v[112:115]
	v_mfma_f32_16x16x32_bf16 v[100:103], v[170:173], v[206:209], v[100:103]
	v_mfma_f32_16x16x32_bf16 v[96:99], v[178:181], v[206:209], v[96:99]
	v_mfma_f32_16x16x32_bf16 v[84:87], v[170:173], v[214:217], v[84:87]
	v_mfma_f32_16x16x32_bf16 v[80:83], v[178:181], v[214:217], v[80:83]
	v_mfma_f32_16x16x32_bf16 v[68:71], v[170:173], v[222:225], v[68:71]
	v_mfma_f32_16x16x32_bf16 v[64:67], v[178:181], v[222:225], v[64:67]
	s_setprio 0
	s_barrier
	s_add_i32 s54, s86, s60
	v_lshl_add_u64 v[226:227], s[44:45], 0, v[132:133]
	s_mov_b32 m0, s54
	ds_read_b128 v[182:185], v197 offset:16384
	ds_read_b128 v[198:201], v197 offset:17408
	ds_read_b128 v[202:205], v197 offset:18432
	ds_read_b128 v[206:209], v197 offset:19456
	ds_read_b128 v[210:213], v197 offset:20480
	ds_read_b128 v[214:217], v197 offset:21504
	ds_read_b128 v[218:221], v197 offset:22528
	ds_read_b128 v[222:225], v197 offset:23552
	global_load_lds_dwordx4 v[226:227], off
	s_add_i32 m0, s54, 0x2000
	s_add_u32 s54, s44, 0x40000
	v_lshl_add_u64 v[228:229], s[44:45], 0, v[128:129]
	s_addc_u32 s55, s45, 0
	s_add_i32 s58, s87, s60
	global_load_lds_dwordx4 v[228:229], off
	v_lshl_add_u64 v[230:231], s[54:55], 0, v[132:133]
	s_mov_b32 m0, s58
	v_lshl_add_u64 v[232:233], s[46:47], 0, v[130:131]
	global_load_lds_dwordx4 v[230:231], off
	v_lshl_add_u64 v[230:231], s[54:55], 0, v[128:129]
	s_add_i32 m0, s58, 0x2000
	s_nop 0
	global_load_lds_dwordx4 v[230:231], off
	v_lshl_add_u64 v[230:231], s[46:47], 0, v[134:135]
	s_mov_b32 m0, s63
	s_nop 0
	global_load_lds_dwordx4 v[230:231], off
	s_mov_b32 m0, s68
	s_nop 0
	global_load_lds_dwordx4 v[232:233], off
	s_waitcnt vmcnt(8)
	s_waitcnt lgkmcnt(0)
	s_barrier
; #define PG8_STAGE(bufoff, gbase, voff) do { _Pragma("unroll") for (int _i = 0; _i < 2; ++_i) \
;         __builtin_amdgcn_global_load_lds((const unsigned*)((const char*)(gbase) + (voff)[_i]), (PG8_LAS unsigned*)(lds + (bufoff) + ldsw + _i * 8192), 16, 0, 0); } while (0)
; #define PG8_LDA(dst, b, h) do { _Pragma("unroll") for (int m = 0; m < 4; ++m) _Pragma("unroll") for (int k = 0; k < 2; ++k) dst[m][k] = *(const PG8_LAS bf16x8*)(lds + PG8_SA(b, h) + aoff + m * 2048 + k * 1024); } while (0)
; #define PG8_LDB(dst, b, h) do { _Pragma("unroll") for (int n = 0; n < 2; ++n) _Pragma("unroll") for (int k = 0; k < 2; ++k) dst[n][k] = *(const PG8_LAS bf16x8*)(lds + PG8_SB(b, h) + boff + n * 2048 + k * 1024); } while (0)
; #define PG8_MMA(ai, bj, At, Bt) do { __builtin_amdgcn_s_setprio(1); _Pragma("unroll") for (int m = 0; m < 4; ++m) _Pragma("unroll") for (int n = 0; n < 2; ++n) _Pragma("unroll") for (int k = 0; k < 2; ++k) \
;         acc[ai][bj][m][n] = __builtin_amdgcn_mfma_f32_16x16x32_bf16(Bt[n][k], At[m][k], acc[ai][bj][m][n], 0, 0, 0); __builtin_amdgcn_s_setprio(0); } while (0)
; #define PG8_WAIT_V(n) asm volatile("s_waitcnt vmcnt(" #n ")" ::: "memory")
; #define PG8_WAIT_L(n) asm volatile("s_waitcnt lgkmcnt(" #n ")" ::: "memory")
; #define PG8_BAR __builtin_amdgcn_s_barrier()
; #define PG8_SCHED __builtin_amdgcn_sched_barrier(0)
; template <class Epi, class Sched, bool ALIGN_EPI = false, bool SP2 = false>
; __device__ __forceinline__ void gemm_phase(PG8_LAS unsigned char* lds, const Gemm g, const Sched& S, const Epi& E) {
;     ...
;             PG8_WAIT_V(8); PG8_WAIT_L(0); PG8_BAR; PG8_MMA(1, 0, At, B0); PG8_MMA(1, 1, At, B1); PG8_BAR; PG8_SCHED;
;             PG8_LDB(B0, 1, 0); PG8_LDB(B1, 1, 1); PG8_SCHED; PG8_LDA(At, 1, 0); PG8_STAGE(PG8_SA(0, 1), a2 + hstep, voffA);
;             PG8_WAIT_V(8); PG8_WAIT_L(0); PG8_BAR; PG8_MMA(0, 0, At, B0); PG8_MMA(0, 1, At, B1); PG8_BAR; PG8_SCHED;
	s_setprio 1
	s_waitcnt lgkmcnt(0)
	v_mfma_f32_16x16x32_bf16 v[60:63], v[150:153], v[182:185], v[60:63]
	v_mfma_f32_16x16x32_bf16 v[56:59], v[158:161], v[182:185], v[56:59]
	v_mfma_f32_16x16x32_bf16 v[44:47], v[150:153], v[202:205], v[44:47]
	v_mfma_f32_16x16x32_bf16 v[40:43], v[158:161], v[202:205], v[40:43]
	v_mfma_f32_16x16x32_bf16 v[28:31], v[150:153], v[210:213], v[28:31]
	v_mfma_f32_16x16x32_bf16 v[24:27], v[158:161], v[210:213], v[24:27]
	v_mfma_f32_16x16x32_bf16 v[12:15], v[150:153], v[218:221], v[12:15]
	v_mfma_f32_16x16x32_bf16 v[8:11], v[158:161], v[218:221], v[8:11]
	v_mfma_f32_16x16x32_bf16 v[60:63], v[154:157], v[198:201], v[60:63]
	v_mfma_f32_16x16x32_bf16 v[56:59], v[162:165], v[198:201], v[56:59]
	v_mfma_f32_16x16x32_bf16 v[44:47], v[154:157], v[206:209], v[44:47]
	v_mfma_f32_16x16x32_bf16 v[40:43], v[162:165], v[206:209], v[40:43]
	v_mfma_f32_16x16x32_bf16 v[28:31], v[154:157], v[214:217], v[28:31]
	v_mfma_f32_16x16x32_bf16 v[24:27], v[162:165], v[214:217], v[24:27]
	v_mfma_f32_16x16x32_bf16 v[12:15], v[154:157], v[222:225], v[12:15]
	v_mfma_f32_16x16x32_bf16 v[8:11], v[162:165], v[222:225], v[8:11]
	v_mfma_f32_16x16x32_bf16 v[52:55], v[166:169], v[182:185], v[52:55]
	v_mfma_f32_16x16x32_bf16 v[48:51], v[174:177], v[182:185], v[48:51]
	v_mfma_f32_16x16x32_bf16 v[36:39], v[166:169], v[202:205], v[36:39]
	v_mfma_f32_16x16x32_bf16 v[32:35], v[174:177], v[202:205], v[32:35]
	v_mfma_f32_16x16x32_bf16 v[20:23], v[166:169], v[210:213], v[20:23]
	v_mfma_f32_16x16x32_bf16 v[16:19], v[174:177], v[210:213], v[16:19]
	v_mfma_f32_16x16x32_bf16 v[4:7], v[166:169], v[218:221], v[4:7]
	v_mfma_f32_16x16x32_bf16 v[0:3], v[174:177], v[218:221], v[0:3]
	v_mfma_f32_16x16x32_bf16 v[52:55], v[170:173], v[198:201], v[52:55]
	v_mfma_f32_16x16x32_bf16 v[48:51], v[178:181], v[198:201], v[48:51]
	v_mfma_f32_16x16x32_bf16 v[36:39], v[170:173], v[206:209], v[36:39]
	v_mfma_f32_16x16x32_bf16 v[32:35], v[178:181], v[206:209], v[32:35]
	v_mfma_f32_16x16x32_bf16 v[20:23], v[170:173], v[214:217], v[20:23]
	v_mfma_f32_16x16x32_bf16 v[16:19], v[178:181], v[214:217], v[16:19]
	v_mfma_f32_16x16x32_bf16 v[4:7], v[170:173], v[222:225], v[4:7]
	v_mfma_f32_16x16x32_bf16 v[0:3], v[178:181], v[222:225], v[0:3]
	s_setprio 0
	s_barrier
	s_add_i32 s54, 0, 0x18000
	v_add_u32_e32 v136, s54, v193
	s_add_i32 s55, 0, 0x1c000
	ds_read_b128 v[150:153], v136
	ds_read_b128 v[154:157], v136 offset:1024
	ds_read_b128 v[158:161], v136 offset:2048
	ds_read_b128 v[162:165], v136 offset:3072
	v_add_u32_e32 v136, s55, v193
	ds_read_b128 v[166:169], v136
	ds_read_b128 v[170:173], v136 offset:1024
	ds_read_b128 v[174:177], v136 offset:2048
	ds_read_b128 v[178:181], v136 offset:3072
	s_add_u32 s46, s46, 0x40000
	s_addc_u32 s47, s47, 0
	s_mov_b32 m0, s69
	v_lshl_add_u64 v[234:235], s[46:47], 0, v[134:135]
	ds_read_b128 v[182:185], v197 offset:32768
	ds_read_b128 v[198:201], v197 offset:33792
	ds_read_b128 v[202:205], v197 offset:34816
	ds_read_b128 v[206:209], v197 offset:35840
	ds_read_b128 v[210:213], v197 offset:36864
	ds_read_b128 v[214:217], v197 offset:37888
	ds_read_b128 v[218:221], v197 offset:38912
	ds_read_b128 v[222:225], v197 offset:39936
	global_load_lds_dwordx4 v[234:235], off
	v_lshl_add_u64 v[234:235], s[46:47], 0, v[130:131]
	s_mov_b32 m0, s70
	s_nop 0
	global_load_lds_dwordx4 v[234:235], off
	s_waitcnt vmcnt(8)
	s_waitcnt lgkmcnt(0)
	s_barrier
	s_setprio 1
	s_waitcnt lgkmcnt(0)
	v_mfma_f32_16x16x32_bf16 v[124:127], v[150:153], v[182:185], v[124:127]
	v_mfma_f32_16x16x32_bf16 v[120:123], v[158:161], v[182:185], v[120:123]
	v_mfma_f32_16x16x32_bf16 v[108:111], v[150:153], v[202:205], v[108:111]
	v_mfma_f32_16x16x32_bf16 v[104:107], v[158:161], v[202:205], v[104:107]
	v_mfma_f32_16x16x32_bf16 v[92:95], v[150:153], v[210:213], v[92:95]
	v_mfma_f32_16x16x32_bf16 v[88:91], v[158:161], v[210:213], v[88:91]
	v_mfma_f32_16x16x32_bf16 v[76:79], v[150:153], v[218:221], v[76:79]
	v_mfma_f32_16x16x32_bf16 v[72:75], v[158:161], v[218:221], v[72:75]
	v_mfma_f32_16x16x32_bf16 v[124:127], v[154:157], v[198:201], v[124:127]
	v_mfma_f32_16x16x32_bf16 v[120:123], v[162:165], v[198:201], v[120:123]
	v_mfma_f32_16x16x32_bf16 v[108:111], v[154:157], v[206:209], v[108:111]
	v_mfma_f32_16x16x32_bf16 v[104:107], v[162:165], v[206:209], v[104:107]
	v_mfma_f32_16x16x32_bf16 v[92:95], v[154:157], v[214:217], v[92:95]
	v_mfma_f32_16x16x32_bf16 v[88:91], v[162:165], v[214:217], v[88:91]
	v_mfma_f32_16x16x32_bf16 v[76:79], v[154:157], v[222:225], v[76:79]
	v_mfma_f32_16x16x32_bf16 v[72:75], v[162:165], v[222:225], v[72:75]
	v_mfma_f32_16x16x32_bf16 v[116:119], v[166:169], v[182:185], v[116:119]
	v_mfma_f32_16x16x32_bf16 v[112:115], v[174:177], v[182:185], v[112:115]
	v_mfma_f32_16x16x32_bf16 v[100:103], v[166:169], v[202:205], v[100:103]
	v_mfma_f32_16x16x32_bf16 v[96:99], v[174:177], v[202:205], v[96:99]
	v_mfma_f32_16x16x32_bf16 v[84:87], v[166:169], v[210:213], v[84:87]
	v_mfma_f32_16x16x32_bf16 v[80:83], v[174:177], v[210:213], v[80:83]
	v_mfma_f32_16x16x32_bf16 v[68:71], v[166:169], v[218:221], v[68:71]
	v_mfma_f32_16x16x32_bf16 v[64:67], v[174:177], v[218:221], v[64:67]
	v_mfma_f32_16x16x32_bf16 v[116:119], v[170:173], v[198:201], v[116:119]
	v_mfma_f32_16x16x32_bf16 v[112:115], v[178:181], v[198:201], v[112:115]
	v_mfma_f32_16x16x32_bf16 v[100:103], v[170:173], v[206:209], v[100:103]
	v_mfma_f32_16x16x32_bf16 v[96:99], v[178:181], v[206:209], v[96:99]
	v_mfma_f32_16x16x32_bf16 v[84:87], v[170:173], v[214:217], v[84:87]
	v_mfma_f32_16x16x32_bf16 v[80:83], v[178:181], v[214:217], v[80:83]
	v_mfma_f32_16x16x32_bf16 v[68:71], v[170:173], v[222:225], v[68:71]
	v_mfma_f32_16x16x32_bf16 v[64:67], v[178:181], v[222:225], v[64:67]
	s_setprio 0
	s_barrier
; #define PG8_STAGE(bufoff, gbase, voff) do { _Pragma("unroll") for (int _i = 0; _i < 2; ++_i) \
;         __builtin_amdgcn_global_load_lds((const unsigned*)((const char*)(gbase) + (voff)[_i]), (PG8_LAS unsigned*)(lds + (bufoff) + ldsw + _i * 8192), 16, 0, 0); } while (0)
; #define PG8_LDA(dst, b, h) do { _Pragma("unroll") for (int m = 0; m < 4; ++m) _Pragma("unroll") for (int k = 0; k < 2; ++k) dst[m][k] = *(const PG8_LAS bf16x8*)(lds + PG8_SA(b, h) + aoff + m * 2048 + k * 1024); } while (0)
; #define PG8_MMA(ai, bj, At, Bt) do { __builtin_amdgcn_s_setprio(1); _Pragma("unroll") for (int m = 0; m < 4; ++m) _Pragma("unroll") for (int n = 0; n < 2; ++n) _Pragma("unroll") for (int k = 0; k < 2; ++k) \
;         acc[ai][bj][m][n] = __builtin_amdgcn_mfma_f32_16x16x32_bf16(Bt[n][k], At[m][k], acc[ai][bj][m][n], 0, 0, 0); __builtin_amdgcn_s_setprio(0); } while (0)
; #define PG8_WAIT_V(n) asm volatile("s_waitcnt vmcnt(" #n ")" ::: "memory")
; #define PG8_WAIT_L(n) asm volatile("s_waitcnt lgkmcnt(" #n ")" ::: "memory")
; #define PG8_BAR __builtin_amdgcn_s_barrier()
; #define PG8_SCHED __builtin_amdgcn_sched_barrier(0)
; template <class Epi, class Sched, bool ALIGN_EPI = false, bool SP2 = false>
; __device__ __forceinline__ void gemm_phase(PG8_LAS unsigned char* lds, const Gemm g, const Sched& S, const Epi& E) {
;     ...
;             PG8_LDA(At, 1, 1); PG8_STAGE(PG8_SB(1, 0), b3, voffB); PG8_STAGE(PG8_SB(1, 1), b3 + hstep, voffB); PG8_STAGE(PG8_SA(1, 0), a3, voffA);
;             PG8_WAIT_V(8); PG8_WAIT_L(0); PG8_BAR; PG8_MMA(1, 0, At, B0); PG8_MMA(1, 1, At, B1); PG8_BAR; PG8_SCHED;
;     ...
;         if constexpr (ALIGN_EPI) { if (wr == 0) PG8_BAR; }
	s_add_i32 s46, s54, s60
	v_lshl_add_u64 v[226:227], v[226:227], 0, s[14:15]
	s_mov_b32 m0, s46
	ds_read_b128 v[182:185], v197 offset:49152
	ds_read_b128 v[198:201], v197 offset:50176
	ds_read_b128 v[202:205], v197 offset:51200
	ds_read_b128 v[206:209], v197 offset:52224
	ds_read_b128 v[210:213], v197 offset:53248
	ds_read_b128 v[214:217], v197 offset:54272
	ds_read_b128 v[218:221], v197 offset:55296
	ds_read_b128 v[222:225], v197 offset:56320
	global_load_lds_dwordx4 v[226:227], off
	s_add_i32 m0, s46, 0x2000
	s_add_u32 s44, s44, 0x40080
	v_lshl_add_u64 v[226:227], v[228:229], 0, s[14:15]
	s_addc_u32 s45, s45, 0
	s_add_i32 s46, s55, s60
	global_load_lds_dwordx4 v[226:227], off
	v_lshl_add_u64 v[226:227], s[44:45], 0, v[132:133]
	s_mov_b32 m0, s46
	s_nop 0
	global_load_lds_dwordx4 v[226:227], off
	v_lshl_add_u64 v[226:227], s[44:45], 0, v[128:129]
	s_add_i32 m0, s46, 0x2000
	s_nop 0
	global_load_lds_dwordx4 v[226:227], off
	v_lshl_add_u64 v[226:227], v[230:231], 0, s[14:15]
	s_mov_b32 m0, s72
	s_nop 0
	global_load_lds_dwordx4 v[226:227], off
	v_lshl_add_u64 v[226:227], v[232:233], 0, s[14:15]
	s_mov_b32 m0, s73
	s_nop 0
	global_load_lds_dwordx4 v[226:227], off
	s_waitcnt vmcnt(8)
	s_waitcnt lgkmcnt(0)
	s_barrier
	s_setprio 1
	s_waitcnt lgkmcnt(0)
	v_mfma_f32_16x16x32_bf16 v[60:63], v[150:153], v[182:185], v[60:63]
	v_mfma_f32_16x16x32_bf16 v[56:59], v[158:161], v[182:185], v[56:59]
	v_mfma_f32_16x16x32_bf16 v[44:47], v[150:153], v[202:205], v[44:47]
	v_mfma_f32_16x16x32_bf16 v[40:43], v[158:161], v[202:205], v[40:43]
	v_mfma_f32_16x16x32_bf16 v[28:31], v[150:153], v[210:213], v[28:31]
	v_mfma_f32_16x16x32_bf16 v[24:27], v[158:161], v[210:213], v[24:27]
	v_mfma_f32_16x16x32_bf16 v[12:15], v[150:153], v[218:221], v[12:15]
	v_mfma_f32_16x16x32_bf16 v[8:11], v[158:161], v[218:221], v[8:11]
	v_mfma_f32_16x16x32_bf16 v[60:63], v[154:157], v[198:201], v[60:63]
	v_mfma_f32_16x16x32_bf16 v[56:59], v[162:165], v[198:201], v[56:59]
	v_mfma_f32_16x16x32_bf16 v[44:47], v[154:157], v[206:209], v[44:47]
	v_mfma_f32_16x16x32_bf16 v[40:43], v[162:165], v[206:209], v[40:43]
	v_mfma_f32_16x16x32_bf16 v[28:31], v[154:157], v[214:217], v[28:31]
	v_mfma_f32_16x16x32_bf16 v[24:27], v[162:165], v[214:217], v[24:27]
	v_mfma_f32_16x16x32_bf16 v[12:15], v[154:157], v[222:225], v[12:15]
	v_mfma_f32_16x16x32_bf16 v[8:11], v[162:165], v[222:225], v[8:11]
	v_mfma_f32_16x16x32_bf16 v[52:55], v[166:169], v[182:185], v[52:55]
	v_mfma_f32_16x16x32_bf16 v[48:51], v[174:177], v[182:185], v[48:51]
	v_mfma_f32_16x16x32_bf16 v[36:39], v[166:169], v[202:205], v[36:39]
	v_mfma_f32_16x16x32_bf16 v[32:35], v[174:177], v[202:205], v[32:35]
	v_mfma_f32_16x16x32_bf16 v[20:23], v[166:169], v[210:213], v[20:23]
	v_mfma_f32_16x16x32_bf16 v[16:19], v[174:177], v[210:213], v[16:19]
	v_mfma_f32_16x16x32_bf16 v[4:7], v[166:169], v[218:221], v[4:7]
	v_mfma_f32_16x16x32_bf16 v[0:3], v[174:177], v[218:221], v[0:3]
	v_mfma_f32_16x16x32_bf16 v[52:55], v[170:173], v[198:201], v[52:55]
	v_mfma_f32_16x16x32_bf16 v[48:51], v[178:181], v[198:201], v[48:51]
	v_mfma_f32_16x16x32_bf16 v[36:39], v[170:173], v[206:209], v[36:39]
	v_mfma_f32_16x16x32_bf16 v[32:35], v[178:181], v[206:209], v[32:35]
	v_mfma_f32_16x16x32_bf16 v[20:23], v[170:173], v[214:217], v[20:23]
	v_mfma_f32_16x16x32_bf16 v[16:19], v[178:181], v[214:217], v[16:19]
	v_mfma_f32_16x16x32_bf16 v[4:7], v[170:173], v[222:225], v[4:7]
	v_mfma_f32_16x16x32_bf16 v[0:3], v[178:181], v[222:225], v[0:3]
	s_setprio 0
	s_barrier
	s_add_i32 s96, s96, 2
	s_add_u32 s42, s42, 0x100
	s_addc_u32 s43, s43, 0
	s_add_u32 s94, s94, 0x100
	s_addc_u32 s95, s95, 0
	s_cmp_gt_u32 s96, 13
	s_cbranch_scc0 .LBB0_421
	s_and_b64 vcc, exec, s[16:17]
	s_cbranch_vccz .LBB0_424
	s_barrier

; #define PG8_STAGE(bufoff, gbase, voff) do { _Pragma("unroll") for (int _i = 0; _i < 2; ++_i) \
;         __builtin_amdgcn_global_load_lds((const unsigned*)((const char*)(gbase) + (voff)[_i]), (PG8_LAS unsigned*)(lds + (bufoff) + ldsw + _i * 8192), 16, 0, 0); } while (0)
; #define PG8_LDA(dst, b, h) do { _Pragma("unroll") for (int m = 0; m < 4; ++m) _Pragma("unroll") for (int k = 0; k < 2; ++k) dst[m][k] = *(const PG8_LAS bf16x8*)(lds + PG8_SA(b, h) + aoff + m * 2048 + k * 1024); } while (0)
; #define PG8_LDB(dst, b, h) do { _Pragma("unroll") for (int n = 0; n < 2; ++n) _Pragma("unroll") for (int k = 0; k < 2; ++k) dst[n][k] = *(const PG8_LAS bf16x8*)(lds + PG8_SB(b, h) + boff + n * 2048 + k * 1024); } while (0)
; #define PG8_MMA(ai, bj, At, Bt) do { __builtin_amdgcn_s_setprio(1); _Pragma("unroll") for (int m = 0; m < 4; ++m) _Pragma("unroll") for (int n = 0; n < 2; ++n) _Pragma("unroll") for (int k = 0; k < 2; ++k) \
;         acc[ai][bj][m][n] = __builtin_amdgcn_mfma_f32_16x16x32_bf16(Bt[n][k], At[m][k], acc[ai][bj][m][n], 0, 0, 0); __builtin_amdgcn_s_setprio(0); } while (0)
; #define PG8_WAIT_V(n) asm volatile("s_waitcnt vmcnt(" #n ")" ::: "memory")
; #define PG8_WAIT_L(n) asm volatile("s_waitcnt lgkmcnt(" #n ")" ::: "memory")
; #define PG8_BAR __builtin_amdgcn_s_barrier()
; #define PG8_SCHED __builtin_amdgcn_sched_barrier(0)
; template <class Epi, class Sched, bool ALIGN_EPI = false, bool SP2 = false>
; __device__ __forceinline__ void gemm_phase(PG8_LAS unsigned char* lds, const Gemm g, const Sched& S, const Epi& E) {
;     ...
;             const bool last = (t == nt - 2);
;             const char* a1 = cA + (size_t)(t + 1) * kstep;
;             const char* a2 = last ? nA : cA + (size_t)(t + 2) * kstep; const char* b2 = last ? nB : cB + (size_t)(t + 2) * kstep;
;             const char* a3 = a2 + kstep; const char* b3 = b2 + kstep;
;             if (last && has_next) S.a_ready(nxt);
;             if constexpr (SP2) {
;             PG8_LDB(B0, 0, 0); PG8_LDB(B1, 0, 1); PG8_SCHED; PG8_LDA(At, 0, 0); PG8_STAGE(PG8_SA(1, 1), a1 + hstep, voffA);
;             PG8_WAIT_V(8); PG8_WAIT_L(0); PG8_BAR; PG8_MMA(0, 0, At, B0); PG8_MMA(0, 1, At, B1); PG8_BAR; PG8_SCHED;
;             PG8_LDA(At, 0, 1); PG8_STAGE(PG8_SB(0, 0), b2, voffB); PG8_STAGE(PG8_SB(0, 1), b2 + hstep, voffB); PG8_STAGE(PG8_SA(0, 0), a2, voffA);
.LBB0_460:
	ds_read_b128 v[142:145], v148
	ds_read_b128 v[152:155], v148 offset:1024
	ds_read_b128 v[156:159], v148 offset:2048
	ds_read_b128 v[160:163], v148 offset:3072
	ds_read_b128 v[164:167], v149
	ds_read_b128 v[168:171], v149 offset:1024
	ds_read_b128 v[172:175], v149 offset:2048
	ds_read_b128 v[176:179], v149 offset:3072
	s_add_u32 s22, s20, 0xfffc0080
	s_addc_u32 s23, s21, -1
	s_cmp_eq_u32 s65, 12
	s_cselect_b32 s25, s53, s23
	s_cselect_b32 s24, s60, s22
	s_cselect_b32 s23, s61, s64
	s_cselect_b32 s22, s62, s63
	s_mov_b32 m0, s40
	v_lshl_add_u64 v[184:185], s[20:21], 0, v[138:139]
	ds_read_b128 v[180:183], v150
	ds_read_b128 v[190:193], v150 offset:1024
	ds_read_b128 v[194:197], v150 offset:2048
	ds_read_b128 v[198:201], v150 offset:3072
	ds_read_b128 v[202:205], v150 offset:4096
	ds_read_b128 v[206:209], v150 offset:5120
	ds_read_b128 v[210:213], v150 offset:6144
	ds_read_b128 v[214:217], v150 offset:7168
	global_load_lds_dwordx4 v[184:185], off
	v_lshl_add_u64 v[184:185], s[20:21], 0, v[140:141]
	s_mov_b32 m0, s41
	s_nop 0
	global_load_lds_dwordx4 v[184:185], off
	s_waitcnt vmcnt(8)
	s_waitcnt lgkmcnt(0)
	s_barrier
	s_setprio 1
	s_waitcnt lgkmcnt(0)
	v_mfma_f32_16x16x32_bf16 v[124:127], v[142:145], v[180:183], v[124:127]
	v_mfma_f32_16x16x32_bf16 v[120:123], v[156:159], v[180:183], v[120:123]
	v_mfma_f32_16x16x32_bf16 v[108:111], v[142:145], v[194:197], v[108:111]
	v_mfma_f32_16x16x32_bf16 v[104:107], v[156:159], v[194:197], v[104:107]
	v_mfma_f32_16x16x32_bf16 v[92:95], v[142:145], v[202:205], v[92:95]
	v_mfma_f32_16x16x32_bf16 v[88:91], v[156:159], v[202:205], v[88:91]
	v_mfma_f32_16x16x32_bf16 v[76:79], v[142:145], v[210:213], v[76:79]
	v_mfma_f32_16x16x32_bf16 v[72:75], v[156:159], v[210:213], v[72:75]
	v_mfma_f32_16x16x32_bf16 v[124:127], v[152:155], v[190:193], v[124:127]
	v_mfma_f32_16x16x32_bf16 v[120:123], v[160:163], v[190:193], v[120:123]
	v_mfma_f32_16x16x32_bf16 v[108:111], v[152:155], v[198:201], v[108:111]
	v_mfma_f32_16x16x32_bf16 v[104:107], v[160:163], v[198:201], v[104:107]
	v_mfma_f32_16x16x32_bf16 v[92:95], v[152:155], v[206:209], v[92:95]
	v_mfma_f32_16x16x32_bf16 v[88:91], v[160:163], v[206:209], v[88:91]
	v_mfma_f32_16x16x32_bf16 v[76:79], v[152:155], v[214:217], v[76:79]
	v_mfma_f32_16x16x32_bf16 v[72:75], v[160:163], v[214:217], v[72:75]
	v_mfma_f32_16x16x32_bf16 v[116:119], v[164:167], v[180:183], v[116:119]
	v_mfma_f32_16x16x32_bf16 v[112:115], v[172:175], v[180:183], v[112:115]
	v_mfma_f32_16x16x32_bf16 v[100:103], v[164:167], v[194:197], v[100:103]
	v_mfma_f32_16x16x32_bf16 v[96:99], v[172:175], v[194:197], v[96:99]
	v_mfma_f32_16x16x32_bf16 v[84:87], v[164:167], v[202:205], v[84:87]
	v_mfma_f32_16x16x32_bf16 v[80:83], v[172:175], v[202:205], v[80:83]
	v_mfma_f32_16x16x32_bf16 v[68:71], v[164:167], v[210:213], v[68:71]
	v_mfma_f32_16x16x32_bf16 v[64:67], v[172:175], v[210:213], v[64:67]
	v_mfma_f32_16x16x32_bf16 v[116:119], v[168:171], v[190:193], v[116:119]
	v_mfma_f32_16x16x32_bf16 v[112:115], v[176:179], v[190:193], v[112:115]
	v_mfma_f32_16x16x32_bf16 v[100:103], v[168:171], v[198:201], v[100:103]
	v_mfma_f32_16x16x32_bf16 v[96:99], v[176:179], v[198:201], v[96:99]
	v_mfma_f32_16x16x32_bf16 v[84:87], v[168:171], v[206:209], v[84:87]
	v_mfma_f32_16x16x32_bf16 v[80:83], v[176:179], v[206:209], v[80:83]
	v_mfma_f32_16x16x32_bf16 v[68:71], v[168:171], v[214:217], v[68:71]
	v_mfma_f32_16x16x32_bf16 v[64:67], v[176:179], v[214:217], v[64:67]
	s_setprio 0
	s_barrier
	s_mov_b32 m0, s42
	v_lshl_add_u64 v[184:185], s[22:23], 0, v[132:133]
	s_add_u32 s54, s22, 0x40000
	ds_read_b128 v[180:183], v150 offset:16384
	ds_read_b128 v[190:193], v150 offset:17408
	ds_read_b128 v[194:197], v150 offset:18432
	ds_read_b128 v[198:201], v150 offset:19456
	ds_read_b128 v[202:205], v150 offset:20480
	ds_read_b128 v[206:209], v150 offset:21504
	ds_read_b128 v[210:213], v150 offset:22528
	ds_read_b128 v[214:217], v150 offset:23552
	global_load_lds_dwordx4 v[184:185], off
	v_lshl_add_u64 v[218:219], s[22:23], 0, v[128:129]
	s_mov_b32 m0, s43
	s_addc_u32 s55, s23, 0
	global_load_lds_dwordx4 v[218:219], off
	v_lshl_add_u64 v[220:221], s[54:55], 0, v[132:133]
	s_mov_b32 m0, s44
	v_lshl_add_u64 v[222:223], s[24:25], 0, v[130:131]
	global_load_lds_dwordx4 v[220:221], off
	v_lshl_add_u64 v[220:221], s[54:55], 0, v[128:129]
	s_mov_b32 m0, s45
	s_nop 0
	global_load_lds_dwordx4 v[220:221], off
	v_lshl_add_u64 v[220:221], s[24:25], 0, v[134:135]
	s_mov_b32 m0, s31
	s_nop 0
	global_load_lds_dwordx4 v[220:221], off
	s_mov_b32 m0, s34
	s_nop 0
	global_load_lds_dwordx4 v[222:223], off
	s_waitcnt vmcnt(8)
	s_waitcnt lgkmcnt(0)
	s_barrier
; #define PG8_STAGE(bufoff, gbase, voff) do { _Pragma("unroll") for (int _i = 0; _i < 2; ++_i) \
;         __builtin_amdgcn_global_load_lds((const unsigned*)((const char*)(gbase) + (voff)[_i]), (PG8_LAS unsigned*)(lds + (bufoff) + ldsw + _i * 8192), 16, 0, 0); } while (0)
; #define PG8_LDA(dst, b, h) do { _Pragma("unroll") for (int m = 0; m < 4; ++m) _Pragma("unroll") for (int k = 0; k < 2; ++k) dst[m][k] = *(const PG8_LAS bf16x8*)(lds + PG8_SA(b, h) + aoff + m * 2048 + k * 1024); } while (0)
; #define PG8_LDB(dst, b, h) do { _Pragma("unroll") for (int n = 0; n < 2; ++n) _Pragma("unroll") for (int k = 0; k < 2; ++k) dst[n][k] = *(const PG8_LAS bf16x8*)(lds + PG8_SB(b, h) + boff + n * 2048 + k * 1024); } while (0)
; #define PG8_MMA(ai, bj, At, Bt) do { __builtin_amdgcn_s_setprio(1); _Pragma("unroll") for (int m = 0; m < 4; ++m) _Pragma("unroll") for (int n = 0; n < 2; ++n) _Pragma("unroll") for (int k = 0; k < 2; ++k) \
;         acc[ai][bj][m][n] = __builtin_amdgcn_mfma_f32_16x16x32_bf16(Bt[n][k], At[m][k], acc[ai][bj][m][n], 0, 0, 0); __builtin_amdgcn_s_setprio(0); } while (0)
; #define PG8_WAIT_V(n) asm volatile("s_waitcnt vmcnt(" #n ")" ::: "memory")
; #define PG8_WAIT_L(n) asm volatile("s_waitcnt lgkmcnt(" #n ")" ::: "memory")
; #define PG8_BAR __builtin_amdgcn_s_barrier()
; #define PG8_SCHED __builtin_amdgcn_sched_barrier(0)
; template <class Epi, class Sched, bool ALIGN_EPI = false, bool SP2 = false>
; __device__ __forceinline__ void gemm_phase(PG8_LAS unsigned char* lds, const Gemm g, const Sched& S, const Epi& E) {
;     ...
;             PG8_WAIT_V(8); PG8_WAIT_L(0); PG8_BAR; PG8_MMA(1, 0, At, B0); PG8_MMA(1, 1, At, B1); PG8_BAR; PG8_SCHED;
;             PG8_LDB(B0, 1, 0); PG8_LDB(B1, 1, 1); PG8_SCHED; PG8_LDA(At, 1, 0); PG8_STAGE(PG8_SA(0, 1), a2 + hstep, voffA);
;             PG8_WAIT_V(8); PG8_WAIT_L(0); PG8_BAR; PG8_MMA(0, 0, At, B0); PG8_MMA(0, 1, At, B1); PG8_BAR; PG8_SCHED;
	s_setprio 1
	s_waitcnt lgkmcnt(0)
	v_mfma_f32_16x16x32_bf16 v[60:63], v[142:145], v[180:183], v[60:63]
	v_mfma_f32_16x16x32_bf16 v[56:59], v[156:159], v[180:183], v[56:59]
	v_mfma_f32_16x16x32_bf16 v[44:47], v[142:145], v[194:197], v[44:47]
	v_mfma_f32_16x16x32_bf16 v[40:43], v[156:159], v[194:197], v[40:43]
	v_mfma_f32_16x16x32_bf16 v[28:31], v[142:145], v[202:205], v[28:31]
	v_mfma_f32_16x16x32_bf16 v[24:27], v[156:159], v[202:205], v[24:27]
	v_mfma_f32_16x16x32_bf16 v[12:15], v[142:145], v[210:213], v[12:15]
	v_mfma_f32_16x16x32_bf16 v[8:11], v[156:159], v[210:213], v[8:11]
	v_mfma_f32_16x16x32_bf16 v[60:63], v[152:155], v[190:193], v[60:63]
	v_mfma_f32_16x16x32_bf16 v[56:59], v[160:163], v[190:193], v[56:59]
	v_mfma_f32_16x16x32_bf16 v[44:47], v[152:155], v[198:201], v[44:47]
	v_mfma_f32_16x16x32_bf16 v[40:43], v[160:163], v[198:201], v[40:43]
	v_mfma_f32_16x16x32_bf16 v[28:31], v[152:155], v[206:209], v[28:31]
	v_mfma_f32_16x16x32_bf16 v[24:27], v[160:163], v[206:209], v[24:27]
	v_mfma_f32_16x16x32_bf16 v[12:15], v[152:155], v[214:217], v[12:15]
	v_mfma_f32_16x16x32_bf16 v[8:11], v[160:163], v[214:217], v[8:11]
	v_mfma_f32_16x16x32_bf16 v[52:55], v[164:167], v[180:183], v[52:55]
	v_mfma_f32_16x16x32_bf16 v[48:51], v[172:175], v[180:183], v[48:51]
	v_mfma_f32_16x16x32_bf16 v[36:39], v[164:167], v[194:197], v[36:39]
	v_mfma_f32_16x16x32_bf16 v[32:35], v[172:175], v[194:197], v[32:35]
	v_mfma_f32_16x16x32_bf16 v[20:23], v[164:167], v[202:205], v[20:23]
	v_mfma_f32_16x16x32_bf16 v[16:19], v[172:175], v[202:205], v[16:19]
	v_mfma_f32_16x16x32_bf16 v[4:7], v[164:167], v[210:213], v[4:7]
	v_mfma_f32_16x16x32_bf16 v[0:3], v[172:175], v[210:213], v[0:3]
	v_mfma_f32_16x16x32_bf16 v[52:55], v[168:171], v[190:193], v[52:55]
	v_mfma_f32_16x16x32_bf16 v[48:51], v[176:179], v[190:193], v[48:51]
	v_mfma_f32_16x16x32_bf16 v[36:39], v[168:171], v[198:201], v[36:39]
	v_mfma_f32_16x16x32_bf16 v[32:35], v[176:179], v[198:201], v[32:35]
	v_mfma_f32_16x16x32_bf16 v[20:23], v[168:171], v[206:209], v[20:23]
	v_mfma_f32_16x16x32_bf16 v[16:19], v[176:179], v[206:209], v[16:19]
	v_mfma_f32_16x16x32_bf16 v[4:7], v[168:171], v[214:217], v[4:7]
	v_mfma_f32_16x16x32_bf16 v[0:3], v[176:179], v[214:217], v[0:3]
	s_setprio 0
	s_barrier
	s_add_i32 s54, 0, 0x18000
	v_add_u32_e32 v136, s54, v147
	s_add_i32 s55, 0, 0x1c000
	ds_read_b128 v[142:145], v136
	ds_read_b128 v[152:155], v136 offset:1024
	ds_read_b128 v[156:159], v136 offset:2048
	ds_read_b128 v[160:163], v136 offset:3072
	v_add_u32_e32 v136, s55, v147
	ds_read_b128 v[164:167], v136
	ds_read_b128 v[168:171], v136 offset:1024
	ds_read_b128 v[172:175], v136 offset:2048
	ds_read_b128 v[176:179], v136 offset:3072
	s_add_u32 s24, s24, 0x40000
	s_addc_u32 s25, s25, 0
	s_mov_b32 m0, s35
	v_lshl_add_u64 v[224:225], s[24:25], 0, v[134:135]
	ds_read_b128 v[180:183], v150 offset:32768
	ds_read_b128 v[190:193], v150 offset:33792
	ds_read_b128 v[194:197], v150 offset:34816
	ds_read_b128 v[198:201], v150 offset:35840
	ds_read_b128 v[202:205], v150 offset:36864
	ds_read_b128 v[206:209], v150 offset:37888
	ds_read_b128 v[210:213], v150 offset:38912
	ds_read_b128 v[214:217], v150 offset:39936
	global_load_lds_dwordx4 v[224:225], off
	v_lshl_add_u64 v[224:225], s[24:25], 0, v[130:131]
	s_mov_b32 m0, s36
	s_nop 0
	global_load_lds_dwordx4 v[224:225], off
	s_waitcnt vmcnt(8)
	s_waitcnt lgkmcnt(0)
	s_barrier
	s_setprio 1
	s_waitcnt lgkmcnt(0)
	v_mfma_f32_16x16x32_bf16 v[124:127], v[142:145], v[180:183], v[124:127]
	v_mfma_f32_16x16x32_bf16 v[120:123], v[156:159], v[180:183], v[120:123]
	v_mfma_f32_16x16x32_bf16 v[108:111], v[142:145], v[194:197], v[108:111]
	v_mfma_f32_16x16x32_bf16 v[104:107], v[156:159], v[194:197], v[104:107]
	v_mfma_f32_16x16x32_bf16 v[92:95], v[142:145], v[202:205], v[92:95]
	v_mfma_f32_16x16x32_bf16 v[88:91], v[156:159], v[202:205], v[88:91]
	v_mfma_f32_16x16x32_bf16 v[76:79], v[142:145], v[210:213], v[76:79]
	v_mfma_f32_16x16x32_bf16 v[72:75], v[156:159], v[210:213], v[72:75]
	v_mfma_f32_16x16x32_bf16 v[124:127], v[152:155], v[190:193], v[124:127]
	v_mfma_f32_16x16x32_bf16 v[120:123], v[160:163], v[190:193], v[120:123]
	v_mfma_f32_16x16x32_bf16 v[108:111], v[152:155], v[198:201], v[108:111]
	v_mfma_f32_16x16x32_bf16 v[104:107], v[160:163], v[198:201], v[104:107]
	v_mfma_f32_16x16x32_bf16 v[92:95], v[152:155], v[206:209], v[92:95]
	v_mfma_f32_16x16x32_bf16 v[88:91], v[160:163], v[206:209], v[88:91]
	v_mfma_f32_16x16x32_bf16 v[76:79], v[152:155], v[214:217], v[76:79]
	v_mfma_f32_16x16x32_bf16 v[72:75], v[160:163], v[214:217], v[72:75]
	v_mfma_f32_16x16x32_bf16 v[116:119], v[164:167], v[180:183], v[116:119]
	v_mfma_f32_16x16x32_bf16 v[112:115], v[172:175], v[180:183], v[112:115]
	v_mfma_f32_16x16x32_bf16 v[100:103], v[164:167], v[194:197], v[100:103]
	v_mfma_f32_16x16x32_bf16 v[96:99], v[172:175], v[194:197], v[96:99]
	v_mfma_f32_16x16x32_bf16 v[84:87], v[164:167], v[202:205], v[84:87]
	v_mfma_f32_16x16x32_bf16 v[80:83], v[172:175], v[202:205], v[80:83]
	v_mfma_f32_16x16x32_bf16 v[68:71], v[164:167], v[210:213], v[68:71]
	v_mfma_f32_16x16x32_bf16 v[64:67], v[172:175], v[210:213], v[64:67]
	v_mfma_f32_16x16x32_bf16 v[116:119], v[168:171], v[190:193], v[116:119]
	v_mfma_f32_16x16x32_bf16 v[112:115], v[176:179], v[190:193], v[112:115]
	v_mfma_f32_16x16x32_bf16 v[100:103], v[168:171], v[198:201], v[100:103]
	v_mfma_f32_16x16x32_bf16 v[96:99], v[176:179], v[198:201], v[96:99]
	v_mfma_f32_16x16x32_bf16 v[84:87], v[168:171], v[206:209], v[84:87]
	v_mfma_f32_16x16x32_bf16 v[80:83], v[176:179], v[206:209], v[80:83]
	v_mfma_f32_16x16x32_bf16 v[68:71], v[168:171], v[214:217], v[68:71]
	v_mfma_f32_16x16x32_bf16 v[64:67], v[176:179], v[214:217], v[64:67]
	s_setprio 0
	s_barrier
; #define PG8_STAGE(bufoff, gbase, voff) do { _Pragma("unroll") for (int _i = 0; _i < 2; ++_i) \
;         __builtin_amdgcn_global_load_lds((const unsigned*)((const char*)(gbase) + (voff)[_i]), (PG8_LAS unsigned*)(lds + (bufoff) + ldsw + _i * 8192), 16, 0, 0); } while (0)
; #define PG8_LDA(dst, b, h) do { _Pragma("unroll") for (int m = 0; m < 4; ++m) _Pragma("unroll") for (int k = 0; k < 2; ++k) dst[m][k] = *(const PG8_LAS bf16x8*)(lds + PG8_SA(b, h) + aoff + m * 2048 + k * 1024); } while (0)
; #define PG8_MMA(ai, bj, At, Bt) do { __builtin_amdgcn_s_setprio(1); _Pragma("unroll") for (int m = 0; m < 4; ++m) _Pragma("unroll") for (int n = 0; n < 2; ++n) _Pragma("unroll") for (int k = 0; k < 2; ++k) \
;         acc[ai][bj][m][n] = __builtin_amdgcn_mfma_f32_16x16x32_bf16(Bt[n][k], At[m][k], acc[ai][bj][m][n], 0, 0, 0); __builtin_amdgcn_s_setprio(0); } while (0)
; #define PG8_WAIT_V(n) asm volatile("s_waitcnt vmcnt(" #n ")" ::: "memory")
; #define PG8_WAIT_L(n) asm volatile("s_waitcnt lgkmcnt(" #n ")" ::: "memory")
; #define PG8_BAR __builtin_amdgcn_s_barrier()
; #define PG8_SCHED __builtin_amdgcn_sched_barrier(0)
; template <class Epi, class Sched, bool ALIGN_EPI = false, bool SP2 = false>
; __device__ __forceinline__ void gemm_phase(PG8_LAS unsigned char* lds, const Gemm g, const Sched& S, const Epi& E) {
;     ...
;             PG8_LDA(At, 1, 1); PG8_STAGE(PG8_SB(1, 0), b3, voffB); PG8_STAGE(PG8_SB(1, 1), b3 + hstep, voffB); PG8_STAGE(PG8_SA(1, 0), a3, voffA);
;             PG8_WAIT_V(8); PG8_WAIT_L(0); PG8_BAR; PG8_MMA(1, 0, At, B0); PG8_MMA(1, 1, At, B1); PG8_BAR; PG8_SCHED;
;     ...
;         if constexpr (ALIGN_EPI) { if (wr == 0) PG8_BAR; }
	s_add_i32 s24, s54, s26
	v_lshl_add_u64 v[184:185], v[184:185], 0, s[14:15]
	s_mov_b32 m0, s24
	ds_read_b128 v[180:183], v150 offset:49152
	ds_read_b128 v[190:193], v150 offset:50176
	ds_read_b128 v[194:197], v150 offset:51200
	ds_read_b128 v[198:201], v150 offset:52224
	ds_read_b128 v[202:205], v150 offset:53248
	ds_read_b128 v[206:209], v150 offset:54272
	ds_read_b128 v[210:213], v150 offset:55296
	ds_read_b128 v[214:217], v150 offset:56320
	global_load_lds_dwordx4 v[184:185], off
	s_add_i32 m0, s24, 0x2000
	s_add_u32 s22, s22, 0x40080
	v_lshl_add_u64 v[184:185], v[218:219], 0, s[14:15]
	s_addc_u32 s23, s23, 0
	s_add_i32 s24, s55, s26
	global_load_lds_dwordx4 v[184:185], off
	v_lshl_add_u64 v[184:185], s[22:23], 0, v[132:133]
	s_mov_b32 m0, s24
	s_nop 0
	global_load_lds_dwordx4 v[184:185], off
	v_lshl_add_u64 v[184:185], s[22:23], 0, v[128:129]
	s_add_i32 m0, s24, 0x2000
	s_nop 0
	global_load_lds_dwordx4 v[184:185], off
	v_lshl_add_u64 v[184:185], v[220:221], 0, s[14:15]
	s_mov_b32 m0, s38
	s_nop 0
	global_load_lds_dwordx4 v[184:185], off
	v_lshl_add_u64 v[184:185], v[222:223], 0, s[14:15]
	s_mov_b32 m0, s39
	s_nop 0
	global_load_lds_dwordx4 v[184:185], off
	s_waitcnt vmcnt(8)
	s_waitcnt lgkmcnt(0)
	s_barrier
	s_setprio 1
	s_waitcnt lgkmcnt(0)
	v_mfma_f32_16x16x32_bf16 v[60:63], v[142:145], v[180:183], v[60:63]
	v_mfma_f32_16x16x32_bf16 v[56:59], v[156:159], v[180:183], v[56:59]
	v_mfma_f32_16x16x32_bf16 v[44:47], v[142:145], v[194:197], v[44:47]
	v_mfma_f32_16x16x32_bf16 v[40:43], v[156:159], v[194:197], v[40:43]
	v_mfma_f32_16x16x32_bf16 v[28:31], v[142:145], v[202:205], v[28:31]
	v_mfma_f32_16x16x32_bf16 v[24:27], v[156:159], v[202:205], v[24:27]
	v_mfma_f32_16x16x32_bf16 v[12:15], v[142:145], v[210:213], v[12:15]
	v_mfma_f32_16x16x32_bf16 v[8:11], v[156:159], v[210:213], v[8:11]
	v_mfma_f32_16x16x32_bf16 v[60:63], v[152:155], v[190:193], v[60:63]
	v_mfma_f32_16x16x32_bf16 v[56:59], v[160:163], v[190:193], v[56:59]
	v_mfma_f32_16x16x32_bf16 v[44:47], v[152:155], v[198:201], v[44:47]
	v_mfma_f32_16x16x32_bf16 v[40:43], v[160:163], v[198:201], v[40:43]
	v_mfma_f32_16x16x32_bf16 v[28:31], v[152:155], v[206:209], v[28:31]
	v_mfma_f32_16x16x32_bf16 v[24:27], v[160:163], v[206:209], v[24:27]
	v_mfma_f32_16x16x32_bf16 v[12:15], v[152:155], v[214:217], v[12:15]
	v_mfma_f32_16x16x32_bf16 v[8:11], v[160:163], v[214:217], v[8:11]
	v_mfma_f32_16x16x32_bf16 v[52:55], v[164:167], v[180:183], v[52:55]
	v_mfma_f32_16x16x32_bf16 v[48:51], v[172:175], v[180:183], v[48:51]
	v_mfma_f32_16x16x32_bf16 v[36:39], v[164:167], v[194:197], v[36:39]
	v_mfma_f32_16x16x32_bf16 v[32:35], v[172:175], v[194:197], v[32:35]
	v_mfma_f32_16x16x32_bf16 v[20:23], v[164:167], v[202:205], v[20:23]
	v_mfma_f32_16x16x32_bf16 v[16:19], v[172:175], v[202:205], v[16:19]
	v_mfma_f32_16x16x32_bf16 v[4:7], v[164:167], v[210:213], v[4:7]
	v_mfma_f32_16x16x32_bf16 v[0:3], v[172:175], v[210:213], v[0:3]
	v_mfma_f32_16x16x32_bf16 v[52:55], v[168:171], v[190:193], v[52:55]
	v_mfma_f32_16x16x32_bf16 v[48:51], v[176:179], v[190:193], v[48:51]
	v_mfma_f32_16x16x32_bf16 v[36:39], v[168:171], v[198:201], v[36:39]
	v_mfma_f32_16x16x32_bf16 v[32:35], v[176:179], v[198:201], v[32:35]
	v_mfma_f32_16x16x32_bf16 v[20:23], v[168:171], v[206:209], v[20:23]
	v_mfma_f32_16x16x32_bf16 v[16:19], v[176:179], v[206:209], v[16:19]
	v_mfma_f32_16x16x32_bf16 v[4:7], v[168:171], v[214:217], v[4:7]
	v_mfma_f32_16x16x32_bf16 v[0:3], v[176:179], v[214:217], v[0:3]
	s_setprio 0
	s_barrier
	s_add_i32 s65, s65, 2
	s_add_u32 s20, s20, 0x100
	s_addc_u32 s21, s21, 0
	s_add_u32 s63, s63, 0x100
	s_addc_u32 s64, s64, 0
	s_cmp_gt_u32 s65, 13
	s_cbranch_scc0 .LBB0_460
	s_and_b64 vcc, exec, s[16:17]
	s_cbranch_vccz .LBB0_463
	s_barrier

; #define PG8_STAGE(bufoff, gbase, voff) do { _Pragma("unroll") for (int _i = 0; _i < 2; ++_i) \
;         __builtin_amdgcn_global_load_lds((const unsigned*)((const char*)(gbase) + (voff)[_i]), (PG8_LAS unsigned*)(lds + (bufoff) + ldsw + _i * 8192), 16, 0, 0); } while (0)
; #define PG8_LDA(dst, b, h) do { _Pragma("unroll") for (int m = 0; m < 4; ++m) _Pragma("unroll") for (int k = 0; k < 2; ++k) dst[m][k] = *(const PG8_LAS bf16x8*)(lds + PG8_SA(b, h) + aoff + m * 2048 + k * 1024); } while (0)
; #define PG8_LDB(dst, b, h) do { _Pragma("unroll") for (int n = 0; n < 2; ++n) _Pragma("unroll") for (int k = 0; k < 2; ++k) dst[n][k] = *(const PG8_LAS bf16x8*)(lds + PG8_SB(b, h) + boff + n * 2048 + k * 1024); } while (0)
; #define PG8_MMA(ai, bj, At, Bt) do { __builtin_amdgcn_s_setprio(1); _Pragma("unroll") for (int m = 0; m < 4; ++m) _Pragma("unroll") for (int n = 0; n < 2; ++n) _Pragma("unroll") for (int k = 0; k < 2; ++k) \
;         acc[ai][bj][m][n] = __builtin_amdgcn_mfma_f32_16x16x32_bf16(Bt[n][k], At[m][k], acc[ai][bj][m][n], 0, 0, 0); __builtin_amdgcn_s_setprio(0); } while (0)
; #define PG8_WAIT_V(n) asm volatile("s_waitcnt vmcnt(" #n ")" ::: "memory")
; #define PG8_WAIT_L(n) asm volatile("s_waitcnt lgkmcnt(" #n ")" ::: "memory")
; #define PG8_BAR __builtin_amdgcn_s_barrier()
; #define PG8_SCHED __builtin_amdgcn_sched_barrier(0)
; template <class Epi, class Sched, bool ALIGN_EPI = false, bool SP2 = false>
; __device__ __forceinline__ void gemm_phase(PG8_LAS unsigned char* lds, const Gemm g, const Sched& S, const Epi& E) {
;     ...
;             const bool last = (t == nt - 2);
;             const char* a1 = cA + (size_t)(t + 1) * kstep;
;             const char* a2 = last ? nA : cA + (size_t)(t + 2) * kstep; const char* b2 = last ? nB : cB + (size_t)(t + 2) * kstep;
;             const char* a3 = a2 + kstep; const char* b3 = b2 + kstep;
;             if (last && has_next) S.a_ready(nxt);
;             if constexpr (SP2) {
;             PG8_LDB(B0, 0, 0); PG8_LDB(B1, 0, 1); PG8_SCHED; PG8_LDA(At, 0, 0); PG8_STAGE(PG8_SA(1, 1), a1 + hstep, voffA);
;             PG8_WAIT_V(8); PG8_WAIT_L(0); PG8_BAR; PG8_MMA(0, 0, At, B0); PG8_MMA(0, 1, At, B1); PG8_BAR; PG8_SCHED;
;             PG8_LDA(At, 0, 1); PG8_STAGE(PG8_SB(0, 0), b2, voffB); PG8_STAGE(PG8_SB(0, 1), b2 + hstep, voffB); PG8_STAGE(PG8_SA(0, 0), a2, voffA);
.LBB0_484:
	ds_read_b128 v[142:145], v148
	ds_read_b128 v[154:157], v148 offset:1024
	ds_read_b128 v[158:161], v148 offset:2048
	ds_read_b128 v[162:165], v148 offset:3072
	ds_read_b128 v[166:169], v149
	ds_read_b128 v[170:173], v149 offset:1024
	ds_read_b128 v[174:177], v149 offset:2048
	ds_read_b128 v[178:181], v149 offset:3072
	s_add_u32 s20, s18, 0xfffe0080
	s_addc_u32 s21, s19, -1
	s_cmp_eq_u32 s61, 4
	s_cselect_b32 s23, s47, s21
	s_cselect_b32 s22, s50, s20
	s_cselect_b32 s21, s51, s60
	s_cselect_b32 s20, s52, s53
	s_mov_b32 m0, s38
	v_lshl_add_u64 v[186:187], s[18:19], 0, v[138:139]
	ds_read_b128 v[182:185], v150
	ds_read_b128 v[190:193], v150 offset:1024
	ds_read_b128 v[194:197], v150 offset:2048
	ds_read_b128 v[198:201], v150 offset:3072
	ds_read_b128 v[202:205], v150 offset:4096
	ds_read_b128 v[206:209], v150 offset:5120
	ds_read_b128 v[210:213], v150 offset:6144
	ds_read_b128 v[214:217], v150 offset:7168
	global_load_lds_dwordx4 v[186:187], off
	v_lshl_add_u64 v[186:187], s[18:19], 0, v[140:141]
	s_mov_b32 m0, s39
	s_nop 0
	global_load_lds_dwordx4 v[186:187], off
	s_waitcnt vmcnt(8)
	s_waitcnt lgkmcnt(0)
	s_barrier
	s_setprio 1
	s_waitcnt lgkmcnt(0)
	v_mfma_f32_16x16x32_bf16 v[124:127], v[142:145], v[182:185], v[124:127]
	v_mfma_f32_16x16x32_bf16 v[120:123], v[158:161], v[182:185], v[120:123]
	v_mfma_f32_16x16x32_bf16 v[116:119], v[142:145], v[194:197], v[116:119]
	v_mfma_f32_16x16x32_bf16 v[108:111], v[158:161], v[194:197], v[108:111]
	v_mfma_f32_16x16x32_bf16 v[96:99], v[142:145], v[202:205], v[96:99]
	v_mfma_f32_16x16x32_bf16 v[88:91], v[158:161], v[202:205], v[88:91]
	v_mfma_f32_16x16x32_bf16 v[80:83], v[142:145], v[210:213], v[80:83]
	v_mfma_f32_16x16x32_bf16 v[72:75], v[158:161], v[210:213], v[72:75]
	v_mfma_f32_16x16x32_bf16 v[124:127], v[154:157], v[190:193], v[124:127]
	v_mfma_f32_16x16x32_bf16 v[120:123], v[162:165], v[190:193], v[120:123]
	v_mfma_f32_16x16x32_bf16 v[116:119], v[154:157], v[198:201], v[116:119]
	v_mfma_f32_16x16x32_bf16 v[108:111], v[162:165], v[198:201], v[108:111]
	v_mfma_f32_16x16x32_bf16 v[96:99], v[154:157], v[206:209], v[96:99]
	v_mfma_f32_16x16x32_bf16 v[88:91], v[162:165], v[206:209], v[88:91]
	v_mfma_f32_16x16x32_bf16 v[80:83], v[154:157], v[214:217], v[80:83]
	v_mfma_f32_16x16x32_bf16 v[72:75], v[162:165], v[214:217], v[72:75]
	v_mfma_f32_16x16x32_bf16 v[112:115], v[166:169], v[182:185], v[112:115]
	v_mfma_f32_16x16x32_bf16 v[104:107], v[174:177], v[182:185], v[104:107]
	v_mfma_f32_16x16x32_bf16 v[100:103], v[166:169], v[194:197], v[100:103]
	v_mfma_f32_16x16x32_bf16 v[92:95], v[174:177], v[194:197], v[92:95]
	v_mfma_f32_16x16x32_bf16 v[84:87], v[166:169], v[202:205], v[84:87]
	v_mfma_f32_16x16x32_bf16 v[76:79], v[174:177], v[202:205], v[76:79]
	v_mfma_f32_16x16x32_bf16 v[68:71], v[166:169], v[210:213], v[68:71]
	v_mfma_f32_16x16x32_bf16 v[64:67], v[174:177], v[210:213], v[64:67]
	v_mfma_f32_16x16x32_bf16 v[112:115], v[170:173], v[190:193], v[112:115]
	v_mfma_f32_16x16x32_bf16 v[104:107], v[178:181], v[190:193], v[104:107]
	v_mfma_f32_16x16x32_bf16 v[100:103], v[170:173], v[198:201], v[100:103]
	v_mfma_f32_16x16x32_bf16 v[92:95], v[178:181], v[198:201], v[92:95]
	v_mfma_f32_16x16x32_bf16 v[84:87], v[170:173], v[206:209], v[84:87]
	v_mfma_f32_16x16x32_bf16 v[76:79], v[178:181], v[206:209], v[76:79]
	v_mfma_f32_16x16x32_bf16 v[68:71], v[170:173], v[214:217], v[68:71]
	v_mfma_f32_16x16x32_bf16 v[64:67], v[178:181], v[214:217], v[64:67]
	s_setprio 0
	s_barrier
	s_mov_b32 m0, s40
	v_lshl_add_u64 v[186:187], s[20:21], 0, v[132:133]
	s_add_u32 s54, s20, 0x20000
	ds_read_b128 v[182:185], v150 offset:16384
	ds_read_b128 v[190:193], v150 offset:17408
	ds_read_b128 v[194:197], v150 offset:18432
	ds_read_b128 v[198:201], v150 offset:19456
	ds_read_b128 v[202:205], v150 offset:20480
	ds_read_b128 v[206:209], v150 offset:21504
	ds_read_b128 v[210:213], v150 offset:22528
	ds_read_b128 v[214:217], v150 offset:23552
	global_load_lds_dwordx4 v[186:187], off
	v_lshl_add_u64 v[218:219], s[20:21], 0, v[128:129]
	s_mov_b32 m0, s41
	s_addc_u32 s55, s21, 0
	global_load_lds_dwordx4 v[218:219], off
	v_lshl_add_u64 v[220:221], s[54:55], 0, v[132:133]
	s_mov_b32 m0, s42
	v_lshl_add_u64 v[222:223], s[22:23], 0, v[130:131]
	global_load_lds_dwordx4 v[220:221], off
	v_lshl_add_u64 v[220:221], s[54:55], 0, v[128:129]
	s_mov_b32 m0, s43
	s_nop 0
	global_load_lds_dwordx4 v[220:221], off
	v_lshl_add_u64 v[220:221], s[22:23], 0, v[134:135]
	s_mov_b32 m0, s29
	s_nop 0
	global_load_lds_dwordx4 v[220:221], off
	s_mov_b32 m0, s30
	s_nop 0
	global_load_lds_dwordx4 v[222:223], off
	s_waitcnt vmcnt(8)
	s_waitcnt lgkmcnt(0)
	s_barrier
; #define PG8_STAGE(bufoff, gbase, voff) do { _Pragma("unroll") for (int _i = 0; _i < 2; ++_i) \
;         __builtin_amdgcn_global_load_lds((const unsigned*)((const char*)(gbase) + (voff)[_i]), (PG8_LAS unsigned*)(lds + (bufoff) + ldsw + _i * 8192), 16, 0, 0); } while (0)
; #define PG8_LDA(dst, b, h) do { _Pragma("unroll") for (int m = 0; m < 4; ++m) _Pragma("unroll") for (int k = 0; k < 2; ++k) dst[m][k] = *(const PG8_LAS bf16x8*)(lds + PG8_SA(b, h) + aoff + m * 2048 + k * 1024); } while (0)
; #define PG8_LDB(dst, b, h) do { _Pragma("unroll") for (int n = 0; n < 2; ++n) _Pragma("unroll") for (int k = 0; k < 2; ++k) dst[n][k] = *(const PG8_LAS bf16x8*)(lds + PG8_SB(b, h) + boff + n * 2048 + k * 1024); } while (0)
; #define PG8_MMA(ai, bj, At, Bt) do { __builtin_amdgcn_s_setprio(1); _Pragma("unroll") for (int m = 0; m < 4; ++m) _Pragma("unroll") for (int n = 0; n < 2; ++n) _Pragma("unroll") for (int k = 0; k < 2; ++k) \
;         acc[ai][bj][m][n] = __builtin_amdgcn_mfma_f32_16x16x32_bf16(Bt[n][k], At[m][k], acc[ai][bj][m][n], 0, 0, 0); __builtin_amdgcn_s_setprio(0); } while (0)
; #define PG8_WAIT_V(n) asm volatile("s_waitcnt vmcnt(" #n ")" ::: "memory")
; #define PG8_WAIT_L(n) asm volatile("s_waitcnt lgkmcnt(" #n ")" ::: "memory")
; #define PG8_BAR __builtin_amdgcn_s_barrier()
; #define PG8_SCHED __builtin_amdgcn_sched_barrier(0)
; template <class Epi, class Sched, bool ALIGN_EPI = false, bool SP2 = false>
; __device__ __forceinline__ void gemm_phase(PG8_LAS unsigned char* lds, const Gemm g, const Sched& S, const Epi& E) {
;     ...
;             PG8_WAIT_V(8); PG8_WAIT_L(0); PG8_BAR; PG8_MMA(1, 0, At, B0); PG8_MMA(1, 1, At, B1); PG8_BAR; PG8_SCHED;
;             PG8_LDB(B0, 1, 0); PG8_LDB(B1, 1, 1); PG8_SCHED; PG8_LDA(At, 1, 0); PG8_STAGE(PG8_SA(0, 1), a2 + hstep, voffA);
;             PG8_WAIT_V(8); PG8_WAIT_L(0); PG8_BAR; PG8_MMA(0, 0, At, B0); PG8_MMA(0, 1, At, B1); PG8_BAR; PG8_SCHED;
	s_setprio 1
	s_waitcnt lgkmcnt(0)
	v_mfma_f32_16x16x32_bf16 v[60:63], v[142:145], v[182:185], v[60:63]
	v_mfma_f32_16x16x32_bf16 v[56:59], v[158:161], v[182:185], v[56:59]
	v_mfma_f32_16x16x32_bf16 v[48:51], v[142:145], v[194:197], v[48:51]
	v_mfma_f32_16x16x32_bf16 v[40:43], v[158:161], v[194:197], v[40:43]
	v_mfma_f32_16x16x32_bf16 v[32:35], v[142:145], v[202:205], v[32:35]
	v_mfma_f32_16x16x32_bf16 v[24:27], v[158:161], v[202:205], v[24:27]
	v_mfma_f32_16x16x32_bf16 v[16:19], v[142:145], v[210:213], v[16:19]
	v_mfma_f32_16x16x32_bf16 v[8:11], v[158:161], v[210:213], v[8:11]
	v_mfma_f32_16x16x32_bf16 v[60:63], v[154:157], v[190:193], v[60:63]
	v_mfma_f32_16x16x32_bf16 v[56:59], v[162:165], v[190:193], v[56:59]
	v_mfma_f32_16x16x32_bf16 v[48:51], v[154:157], v[198:201], v[48:51]
	v_mfma_f32_16x16x32_bf16 v[40:43], v[162:165], v[198:201], v[40:43]
	v_mfma_f32_16x16x32_bf16 v[32:35], v[154:157], v[206:209], v[32:35]
	v_mfma_f32_16x16x32_bf16 v[24:27], v[162:165], v[206:209], v[24:27]
	v_mfma_f32_16x16x32_bf16 v[16:19], v[154:157], v[214:217], v[16:19]
	v_mfma_f32_16x16x32_bf16 v[8:11], v[162:165], v[214:217], v[8:11]
	v_mfma_f32_16x16x32_bf16 v[52:55], v[166:169], v[182:185], v[52:55]
	v_mfma_f32_16x16x32_bf16 v[44:47], v[174:177], v[182:185], v[44:47]
	v_mfma_f32_16x16x32_bf16 v[36:39], v[166:169], v[194:197], v[36:39]
	v_mfma_f32_16x16x32_bf16 v[28:31], v[174:177], v[194:197], v[28:31]
	v_mfma_f32_16x16x32_bf16 v[20:23], v[166:169], v[202:205], v[20:23]
	v_mfma_f32_16x16x32_bf16 v[12:15], v[174:177], v[202:205], v[12:15]
	v_mfma_f32_16x16x32_bf16 v[4:7], v[166:169], v[210:213], v[4:7]
	v_mfma_f32_16x16x32_bf16 v[0:3], v[174:177], v[210:213], v[0:3]
	v_mfma_f32_16x16x32_bf16 v[52:55], v[170:173], v[190:193], v[52:55]
	v_mfma_f32_16x16x32_bf16 v[44:47], v[178:181], v[190:193], v[44:47]
	v_mfma_f32_16x16x32_bf16 v[36:39], v[170:173], v[198:201], v[36:39]
	v_mfma_f32_16x16x32_bf16 v[28:31], v[178:181], v[198:201], v[28:31]
	v_mfma_f32_16x16x32_bf16 v[20:23], v[170:173], v[206:209], v[20:23]
	v_mfma_f32_16x16x32_bf16 v[12:15], v[178:181], v[206:209], v[12:15]
	v_mfma_f32_16x16x32_bf16 v[4:7], v[170:173], v[214:217], v[4:7]
	v_mfma_f32_16x16x32_bf16 v[0:3], v[178:181], v[214:217], v[0:3]
	s_setprio 0
	s_barrier
	s_add_i32 s54, 0, 0x1c000
	v_add_u32_e32 v136, s54, v147
	ds_read_b128 v[142:145], v152
	ds_read_b128 v[154:157], v152 offset:1024
	ds_read_b128 v[158:161], v152 offset:2048
	ds_read_b128 v[162:165], v152 offset:3072
	ds_read_b128 v[166:169], v136
	ds_read_b128 v[170:173], v136 offset:1024
	ds_read_b128 v[174:177], v136 offset:2048
	ds_read_b128 v[178:181], v136 offset:3072
	s_add_u32 s22, s22, 0x20000
	s_addc_u32 s23, s23, 0
	s_mov_b32 m0, s31
	v_lshl_add_u64 v[224:225], s[22:23], 0, v[134:135]
	ds_read_b128 v[182:185], v150 offset:32768
	ds_read_b128 v[190:193], v150 offset:33792
	ds_read_b128 v[194:197], v150 offset:34816
	ds_read_b128 v[198:201], v150 offset:35840
	ds_read_b128 v[202:205], v150 offset:36864
	ds_read_b128 v[206:209], v150 offset:37888
	ds_read_b128 v[210:213], v150 offset:38912
	ds_read_b128 v[214:217], v150 offset:39936
	global_load_lds_dwordx4 v[224:225], off
	v_lshl_add_u64 v[224:225], s[22:23], 0, v[130:131]
	s_mov_b32 m0, s34
	s_nop 0
	global_load_lds_dwordx4 v[224:225], off
	s_waitcnt vmcnt(8)
	s_waitcnt lgkmcnt(0)
	s_barrier
	s_setprio 1
	s_waitcnt lgkmcnt(0)
	v_mfma_f32_16x16x32_bf16 v[124:127], v[142:145], v[182:185], v[124:127]
	v_mfma_f32_16x16x32_bf16 v[120:123], v[158:161], v[182:185], v[120:123]
	v_mfma_f32_16x16x32_bf16 v[116:119], v[142:145], v[194:197], v[116:119]
	v_mfma_f32_16x16x32_bf16 v[108:111], v[158:161], v[194:197], v[108:111]
	v_mfma_f32_16x16x32_bf16 v[96:99], v[142:145], v[202:205], v[96:99]
	v_mfma_f32_16x16x32_bf16 v[88:91], v[158:161], v[202:205], v[88:91]
	v_mfma_f32_16x16x32_bf16 v[80:83], v[142:145], v[210:213], v[80:83]
	v_mfma_f32_16x16x32_bf16 v[72:75], v[158:161], v[210:213], v[72:75]
	v_mfma_f32_16x16x32_bf16 v[124:127], v[154:157], v[190:193], v[124:127]
	v_mfma_f32_16x16x32_bf16 v[120:123], v[162:165], v[190:193], v[120:123]
	v_mfma_f32_16x16x32_bf16 v[116:119], v[154:157], v[198:201], v[116:119]
	v_mfma_f32_16x16x32_bf16 v[108:111], v[162:165], v[198:201], v[108:111]
	v_mfma_f32_16x16x32_bf16 v[96:99], v[154:157], v[206:209], v[96:99]
	v_mfma_f32_16x16x32_bf16 v[88:91], v[162:165], v[206:209], v[88:91]
	v_mfma_f32_16x16x32_bf16 v[80:83], v[154:157], v[214:217], v[80:83]
	v_mfma_f32_16x16x32_bf16 v[72:75], v[162:165], v[214:217], v[72:75]
	v_mfma_f32_16x16x32_bf16 v[112:115], v[166:169], v[182:185], v[112:115]
	v_mfma_f32_16x16x32_bf16 v[104:107], v[174:177], v[182:185], v[104:107]
	v_mfma_f32_16x16x32_bf16 v[100:103], v[166:169], v[194:197], v[100:103]
	v_mfma_f32_16x16x32_bf16 v[92:95], v[174:177], v[194:197], v[92:95]
	v_mfma_f32_16x16x32_bf16 v[84:87], v[166:169], v[202:205], v[84:87]
	v_mfma_f32_16x16x32_bf16 v[76:79], v[174:177], v[202:205], v[76:79]
	v_mfma_f32_16x16x32_bf16 v[68:71], v[166:169], v[210:213], v[68:71]
	v_mfma_f32_16x16x32_bf16 v[64:67], v[174:177], v[210:213], v[64:67]
	v_mfma_f32_16x16x32_bf16 v[112:115], v[170:173], v[190:193], v[112:115]
	v_mfma_f32_16x16x32_bf16 v[104:107], v[178:181], v[190:193], v[104:107]
	v_mfma_f32_16x16x32_bf16 v[100:103], v[170:173], v[198:201], v[100:103]
	v_mfma_f32_16x16x32_bf16 v[92:95], v[178:181], v[198:201], v[92:95]
	v_mfma_f32_16x16x32_bf16 v[84:87], v[170:173], v[206:209], v[84:87]
	v_mfma_f32_16x16x32_bf16 v[76:79], v[178:181], v[206:209], v[76:79]
	v_mfma_f32_16x16x32_bf16 v[68:71], v[170:173], v[214:217], v[68:71]
	v_mfma_f32_16x16x32_bf16 v[64:67], v[178:181], v[214:217], v[64:67]
	s_setprio 0
	s_barrier
; #define PG8_STAGE(bufoff, gbase, voff) do { _Pragma("unroll") for (int _i = 0; _i < 2; ++_i) \
;         __builtin_amdgcn_global_load_lds((const unsigned*)((const char*)(gbase) + (voff)[_i]), (PG8_LAS unsigned*)(lds + (bufoff) + ldsw + _i * 8192), 16, 0, 0); } while (0)
; #define PG8_LDA(dst, b, h) do { _Pragma("unroll") for (int m = 0; m < 4; ++m) _Pragma("unroll") for (int k = 0; k < 2; ++k) dst[m][k] = *(const PG8_LAS bf16x8*)(lds + PG8_SA(b, h) + aoff + m * 2048 + k * 1024); } while (0)
; #define PG8_MMA(ai, bj, At, Bt) do { __builtin_amdgcn_s_setprio(1); _Pragma("unroll") for (int m = 0; m < 4; ++m) _Pragma("unroll") for (int n = 0; n < 2; ++n) _Pragma("unroll") for (int k = 0; k < 2; ++k) \
;         acc[ai][bj][m][n] = __builtin_amdgcn_mfma_f32_16x16x32_bf16(Bt[n][k], At[m][k], acc[ai][bj][m][n], 0, 0, 0); __builtin_amdgcn_s_setprio(0); } while (0)
; #define PG8_WAIT_V(n) asm volatile("s_waitcnt vmcnt(" #n ")" ::: "memory")
; #define PG8_WAIT_L(n) asm volatile("s_waitcnt lgkmcnt(" #n ")" ::: "memory")
; #define PG8_BAR __builtin_amdgcn_s_barrier()
; #define PG8_SCHED __builtin_amdgcn_sched_barrier(0)
; template <class Epi, class Sched, bool ALIGN_EPI = false, bool SP2 = false>
; __device__ __forceinline__ void gemm_phase(PG8_LAS unsigned char* lds, const Gemm g, const Sched& S, const Epi& E) {
;     ...
;             PG8_LDA(At, 1, 1); PG8_STAGE(PG8_SB(1, 0), b3, voffB); PG8_STAGE(PG8_SB(1, 1), b3 + hstep, voffB); PG8_STAGE(PG8_SA(1, 0), a3, voffA);
;             PG8_WAIT_V(8); PG8_WAIT_L(0); PG8_BAR; PG8_MMA(1, 0, At, B0); PG8_MMA(1, 1, At, B1); PG8_BAR; PG8_SCHED;
;     ...
;         if constexpr (ALIGN_EPI) { if (wr == 0) PG8_BAR; }
	s_add_i32 s22, s44, s24
	v_lshl_add_u64 v[186:187], v[186:187], 0, s[12:13]
	s_mov_b32 m0, s22
	ds_read_b128 v[182:185], v150 offset:49152
	ds_read_b128 v[190:193], v150 offset:50176
	ds_read_b128 v[194:197], v150 offset:51200
	ds_read_b128 v[198:201], v150 offset:52224
	ds_read_b128 v[202:205], v150 offset:53248
	ds_read_b128 v[206:209], v150 offset:54272
	ds_read_b128 v[210:213], v150 offset:55296
	ds_read_b128 v[214:217], v150 offset:56320
	global_load_lds_dwordx4 v[186:187], off
	s_add_i32 m0, s22, 0x2000
	s_add_u32 s20, s20, 0x20080
	v_lshl_add_u64 v[186:187], v[218:219], 0, s[12:13]
	s_addc_u32 s21, s21, 0
	s_add_i32 s22, s54, s24
	global_load_lds_dwordx4 v[186:187], off
	v_lshl_add_u64 v[186:187], s[20:21], 0, v[132:133]
	s_mov_b32 m0, s22
	s_nop 0
	global_load_lds_dwordx4 v[186:187], off
	v_lshl_add_u64 v[186:187], s[20:21], 0, v[128:129]
	s_add_i32 m0, s22, 0x2000
	s_nop 0
	global_load_lds_dwordx4 v[186:187], off
	v_lshl_add_u64 v[186:187], v[220:221], 0, s[12:13]
	s_mov_b32 m0, s36
	s_nop 0
	global_load_lds_dwordx4 v[186:187], off
	v_lshl_add_u64 v[186:187], v[222:223], 0, s[12:13]
	s_mov_b32 m0, s37
	s_nop 0
	global_load_lds_dwordx4 v[186:187], off
	s_waitcnt vmcnt(8)
	s_waitcnt lgkmcnt(0)
	s_barrier
	s_setprio 1
	s_waitcnt lgkmcnt(0)
	v_mfma_f32_16x16x32_bf16 v[60:63], v[142:145], v[182:185], v[60:63]
	v_mfma_f32_16x16x32_bf16 v[56:59], v[158:161], v[182:185], v[56:59]
	v_mfma_f32_16x16x32_bf16 v[48:51], v[142:145], v[194:197], v[48:51]
	v_mfma_f32_16x16x32_bf16 v[40:43], v[158:161], v[194:197], v[40:43]
	v_mfma_f32_16x16x32_bf16 v[32:35], v[142:145], v[202:205], v[32:35]
	v_mfma_f32_16x16x32_bf16 v[24:27], v[158:161], v[202:205], v[24:27]
	v_mfma_f32_16x16x32_bf16 v[16:19], v[142:145], v[210:213], v[16:19]
	v_mfma_f32_16x16x32_bf16 v[8:11], v[158:161], v[210:213], v[8:11]
	v_mfma_f32_16x16x32_bf16 v[60:63], v[154:157], v[190:193], v[60:63]
	v_mfma_f32_16x16x32_bf16 v[56:59], v[162:165], v[190:193], v[56:59]
	v_mfma_f32_16x16x32_bf16 v[48:51], v[154:157], v[198:201], v[48:51]
	v_mfma_f32_16x16x32_bf16 v[40:43], v[162:165], v[198:201], v[40:43]
	v_mfma_f32_16x16x32_bf16 v[32:35], v[154:157], v[206:209], v[32:35]
	v_mfma_f32_16x16x32_bf16 v[24:27], v[162:165], v[206:209], v[24:27]
	v_mfma_f32_16x16x32_bf16 v[16:19], v[154:157], v[214:217], v[16:19]
	v_mfma_f32_16x16x32_bf16 v[8:11], v[162:165], v[214:217], v[8:11]
	v_mfma_f32_16x16x32_bf16 v[52:55], v[166:169], v[182:185], v[52:55]
	v_mfma_f32_16x16x32_bf16 v[44:47], v[174:177], v[182:185], v[44:47]
	v_mfma_f32_16x16x32_bf16 v[36:39], v[166:169], v[194:197], v[36:39]
	v_mfma_f32_16x16x32_bf16 v[28:31], v[174:177], v[194:197], v[28:31]
	v_mfma_f32_16x16x32_bf16 v[20:23], v[166:169], v[202:205], v[20:23]
	v_mfma_f32_16x16x32_bf16 v[12:15], v[174:177], v[202:205], v[12:15]
	v_mfma_f32_16x16x32_bf16 v[4:7], v[166:169], v[210:213], v[4:7]
	v_mfma_f32_16x16x32_bf16 v[0:3], v[174:177], v[210:213], v[0:3]
	v_mfma_f32_16x16x32_bf16 v[52:55], v[170:173], v[190:193], v[52:55]
	v_mfma_f32_16x16x32_bf16 v[44:47], v[178:181], v[190:193], v[44:47]
	v_mfma_f32_16x16x32_bf16 v[36:39], v[170:173], v[198:201], v[36:39]
	v_mfma_f32_16x16x32_bf16 v[28:31], v[178:181], v[198:201], v[28:31]
	v_mfma_f32_16x16x32_bf16 v[20:23], v[170:173], v[206:209], v[20:23]
	v_mfma_f32_16x16x32_bf16 v[12:15], v[178:181], v[206:209], v[12:15]
	v_mfma_f32_16x16x32_bf16 v[4:7], v[170:173], v[214:217], v[4:7]
	v_mfma_f32_16x16x32_bf16 v[0:3], v[178:181], v[214:217], v[0:3]
	s_setprio 0
	s_barrier
	s_add_i32 s61, s61, 2
	s_add_u32 s18, s18, 0x100
	s_addc_u32 s19, s19, 0
	s_add_u32 s53, s53, 0x100
	s_addc_u32 s60, s60, 0
	s_cmp_gt_u32 s61, 5
	s_cbranch_scc0 .LBB0_484
	s_and_b64 vcc, exec, s[14:15]
	s_cbranch_vccz .LBB0_487
	s_barrier

; #define PG8_STAGE(bufoff, gbase, voff) do { _Pragma("unroll") for (int _i = 0; _i < 2; ++_i) \
;         __builtin_amdgcn_global_load_lds((const unsigned*)((const char*)(gbase) + (voff)[_i]), (PG8_LAS unsigned*)(lds + (bufoff) + ldsw + _i * 8192), 16, 0, 0); } while (0)
; #define PG8_LDA(dst, b, h) do { _Pragma("unroll") for (int m = 0; m < 4; ++m) _Pragma("unroll") for (int k = 0; k < 2; ++k) dst[m][k] = *(const PG8_LAS bf16x8*)(lds + PG8_SA(b, h) + aoff + m * 2048 + k * 1024); } while (0)
; #define PG8_LDB(dst, b, h) do { _Pragma("unroll") for (int n = 0; n < 2; ++n) _Pragma("unroll") for (int k = 0; k < 2; ++k) dst[n][k] = *(const PG8_LAS bf16x8*)(lds + PG8_SB(b, h) + boff + n * 2048 + k * 1024); } while (0)
; #define PG8_MMA(ai, bj, At, Bt) do { __builtin_amdgcn_s_setprio(1); _Pragma("unroll") for (int m = 0; m < 4; ++m) _Pragma("unroll") for (int n = 0; n < 2; ++n) _Pragma("unroll") for (int k = 0; k < 2; ++k) \
;         acc[ai][bj][m][n] = __builtin_amdgcn_mfma_f32_16x16x32_bf16(Bt[n][k], At[m][k], acc[ai][bj][m][n], 0, 0, 0); __builtin_amdgcn_s_setprio(0); } while (0)
; #define PG8_WAIT_V(n) asm volatile("s_waitcnt vmcnt(" #n ")" ::: "memory")
; #define PG8_WAIT_L(n) asm volatile("s_waitcnt lgkmcnt(" #n ")" ::: "memory")
; #define PG8_BAR __builtin_amdgcn_s_barrier()
; #define PG8_SCHED __builtin_amdgcn_sched_barrier(0)
; template <class Epi, class Sched, bool ALIGN_EPI = false, bool SP2 = false>
; __device__ __forceinline__ void gemm_phase(PG8_LAS unsigned char* lds, const Gemm g, const Sched& S, const Epi& E) {
;     ...
;             const bool last = (t == nt - 2);
;             const char* a1 = cA + (size_t)(t + 1) * kstep;
;             const char* a2 = last ? nA : cA + (size_t)(t + 2) * kstep; const char* b2 = last ? nB : cB + (size_t)(t + 2) * kstep;
;             const char* a3 = a2 + kstep; const char* b3 = b2 + kstep;
;             if (last && has_next) S.a_ready(nxt);
;             if constexpr (SP2) {
;             PG8_LDB(B0, 0, 0); PG8_LDB(B1, 0, 1); PG8_SCHED; PG8_LDA(At, 0, 0); PG8_STAGE(PG8_SA(1, 1), a1 + hstep, voffA);
;             PG8_WAIT_V(8); PG8_WAIT_L(0); PG8_BAR; PG8_MMA(0, 0, At, B0); PG8_MMA(0, 1, At, B1); PG8_BAR; PG8_SCHED;
;             PG8_LDA(At, 0, 1); PG8_STAGE(PG8_SB(0, 0), b2, voffB); PG8_STAGE(PG8_SB(0, 1), b2 + hstep, voffB); PG8_STAGE(PG8_SA(0, 0), a2, voffA);
.LBB0_604:
	ds_read_b128 v[128:131], v183
	ds_read_b128 v[132:135], v183 offset:1024
	ds_read_b128 v[136:139], v183 offset:2048
	ds_read_b128 v[140:143], v183 offset:3072
	ds_read_b128 v[144:147], v184
	ds_read_b128 v[148:151], v184 offset:1024
	ds_read_b128 v[168:171], v184 offset:2048
	ds_read_b128 v[172:175], v184 offset:3072
	s_add_u32 s30, s28, 0xfffc0080
	s_addc_u32 s31, s29, -1
	s_cmp_eq_u32 s61, 12
	s_cselect_b32 s35, s21, s31
	s_cselect_b32 s34, s53, s30
	s_cselect_b32 s31, s19, s60
	s_cselect_b32 s30, s58, s59
	v_lshl_add_u64 v[186:187], s[28:29], 0, v[160:161]
	s_add_i32 m0, s27, 0xc000
	ds_read_b128 v[176:179], v185
	ds_read_b128 v[190:193], v185 offset:1024
	ds_read_b128 v[194:197], v185 offset:2048
	ds_read_b128 v[198:201], v185 offset:3072
	ds_read_b128 v[202:205], v185 offset:4096
	ds_read_b128 v[206:209], v185 offset:5120
	ds_read_b128 v[210:213], v185 offset:6144
	ds_read_b128 v[214:217], v185 offset:7168
	global_load_lds_dwordx4 v[186:187], off
	v_lshl_add_u64 v[186:187], s[28:29], 0, v[162:163]
	s_add_i32 m0, s27, 0xe000
	s_nop 0
	global_load_lds_dwordx4 v[186:187], off
	s_waitcnt vmcnt(8)
	s_waitcnt lgkmcnt(0)
	s_barrier
	s_setprio 1
	s_waitcnt lgkmcnt(0)
	v_mfma_f32_16x16x32_bf16 v[124:127], v[128:131], v[176:179], v[124:127]
	v_mfma_f32_16x16x32_bf16 v[120:123], v[136:139], v[176:179], v[120:123]
	v_mfma_f32_16x16x32_bf16 v[112:115], v[128:131], v[194:197], v[112:115]
	v_mfma_f32_16x16x32_bf16 v[104:107], v[136:139], v[194:197], v[104:107]
	v_mfma_f32_16x16x32_bf16 v[96:99], v[128:131], v[202:205], v[96:99]
	v_mfma_f32_16x16x32_bf16 v[88:91], v[136:139], v[202:205], v[88:91]
	v_mfma_f32_16x16x32_bf16 v[80:83], v[128:131], v[210:213], v[80:83]
	v_mfma_f32_16x16x32_bf16 v[72:75], v[136:139], v[210:213], v[72:75]
	v_mfma_f32_16x16x32_bf16 v[124:127], v[132:135], v[190:193], v[124:127]
	v_mfma_f32_16x16x32_bf16 v[120:123], v[140:143], v[190:193], v[120:123]
	v_mfma_f32_16x16x32_bf16 v[112:115], v[132:135], v[198:201], v[112:115]
	v_mfma_f32_16x16x32_bf16 v[104:107], v[140:143], v[198:201], v[104:107]
	v_mfma_f32_16x16x32_bf16 v[96:99], v[132:135], v[206:209], v[96:99]
	v_mfma_f32_16x16x32_bf16 v[88:91], v[140:143], v[206:209], v[88:91]
	v_mfma_f32_16x16x32_bf16 v[80:83], v[132:135], v[214:217], v[80:83]
	v_mfma_f32_16x16x32_bf16 v[72:75], v[140:143], v[214:217], v[72:75]
	v_mfma_f32_16x16x32_bf16 v[116:119], v[144:147], v[176:179], v[116:119]
	v_mfma_f32_16x16x32_bf16 v[108:111], v[168:171], v[176:179], v[108:111]
	v_mfma_f32_16x16x32_bf16 v[100:103], v[144:147], v[194:197], v[100:103]
	v_mfma_f32_16x16x32_bf16 v[92:95], v[168:171], v[194:197], v[92:95]
	v_mfma_f32_16x16x32_bf16 v[84:87], v[144:147], v[202:205], v[84:87]
	v_mfma_f32_16x16x32_bf16 v[76:79], v[168:171], v[202:205], v[76:79]
	v_mfma_f32_16x16x32_bf16 v[68:71], v[144:147], v[210:213], v[68:71]
	v_mfma_f32_16x16x32_bf16 v[64:67], v[168:171], v[210:213], v[64:67]
	v_mfma_f32_16x16x32_bf16 v[116:119], v[148:151], v[190:193], v[116:119]
	v_mfma_f32_16x16x32_bf16 v[108:111], v[172:175], v[190:193], v[108:111]
	v_mfma_f32_16x16x32_bf16 v[100:103], v[148:151], v[198:201], v[100:103]
	v_mfma_f32_16x16x32_bf16 v[92:95], v[172:175], v[198:201], v[92:95]
	v_mfma_f32_16x16x32_bf16 v[84:87], v[148:151], v[206:209], v[84:87]
	v_mfma_f32_16x16x32_bf16 v[76:79], v[172:175], v[206:209], v[76:79]
	v_mfma_f32_16x16x32_bf16 v[68:71], v[148:151], v[214:217], v[68:71]
	v_mfma_f32_16x16x32_bf16 v[64:67], v[172:175], v[214:217], v[64:67]
	s_setprio 0
	s_barrier
	s_add_i32 s54, s50, s41
	v_lshl_add_u64 v[186:187], s[30:31], 0, v[154:155]
	s_mov_b32 m0, s54
	ds_read_b128 v[176:179], v185 offset:16384
	ds_read_b128 v[190:193], v185 offset:17408
	ds_read_b128 v[194:197], v185 offset:18432
	ds_read_b128 v[198:201], v185 offset:19456
	ds_read_b128 v[202:205], v185 offset:20480
	ds_read_b128 v[206:209], v185 offset:21504
	ds_read_b128 v[210:213], v185 offset:22528
	ds_read_b128 v[214:217], v185 offset:23552
	global_load_lds_dwordx4 v[186:187], off
	s_add_i32 m0, s54, 0x2000
	s_add_u32 s54, s30, 0x40000
	v_lshl_add_u64 v[218:219], s[30:31], 0, v[158:159]
	s_addc_u32 s55, s31, 0
	s_add_i32 s62, s51, s41
	global_load_lds_dwordx4 v[218:219], off
	v_lshl_add_u64 v[220:221], s[54:55], 0, v[154:155]
	s_mov_b32 m0, s62
	v_lshl_add_u64 v[222:223], s[34:35], 0, v[156:157]
	global_load_lds_dwordx4 v[220:221], off
	v_lshl_add_u64 v[220:221], s[54:55], 0, v[158:159]
	s_add_i32 m0, s62, 0x2000
	s_nop 0
	global_load_lds_dwordx4 v[220:221], off
	v_lshl_add_u64 v[220:221], s[34:35], 0, v[152:153]
	s_mov_b32 m0, s27
	s_nop 0
	global_load_lds_dwordx4 v[220:221], off
	s_mov_b32 m0, s42
	s_nop 0
	global_load_lds_dwordx4 v[222:223], off
	s_waitcnt vmcnt(8)
	s_waitcnt lgkmcnt(0)
	s_barrier
; #define PG8_STAGE(bufoff, gbase, voff) do { _Pragma("unroll") for (int _i = 0; _i < 2; ++_i) \
;         __builtin_amdgcn_global_load_lds((const unsigned*)((const char*)(gbase) + (voff)[_i]), (PG8_LAS unsigned*)(lds + (bufoff) + ldsw + _i * 8192), 16, 0, 0); } while (0)
; #define PG8_LDA(dst, b, h) do { _Pragma("unroll") for (int m = 0; m < 4; ++m) _Pragma("unroll") for (int k = 0; k < 2; ++k) dst[m][k] = *(const PG8_LAS bf16x8*)(lds + PG8_SA(b, h) + aoff + m * 2048 + k * 1024); } while (0)
; #define PG8_LDB(dst, b, h) do { _Pragma("unroll") for (int n = 0; n < 2; ++n) _Pragma("unroll") for (int k = 0; k < 2; ++k) dst[n][k] = *(const PG8_LAS bf16x8*)(lds + PG8_SB(b, h) + boff + n * 2048 + k * 1024); } while (0)
; #define PG8_MMA(ai, bj, At, Bt) do { __builtin_amdgcn_s_setprio(1); _Pragma("unroll") for (int m = 0; m < 4; ++m) _Pragma("unroll") for (int n = 0; n < 2; ++n) _Pragma("unroll") for (int k = 0; k < 2; ++k) \
;         acc[ai][bj][m][n] = __builtin_amdgcn_mfma_f32_16x16x32_bf16(Bt[n][k], At[m][k], acc[ai][bj][m][n], 0, 0, 0); __builtin_amdgcn_s_setprio(0); } while (0)
; #define PG8_WAIT_V(n) asm volatile("s_waitcnt vmcnt(" #n ")" ::: "memory")
; #define PG8_WAIT_L(n) asm volatile("s_waitcnt lgkmcnt(" #n ")" ::: "memory")
; #define PG8_BAR __builtin_amdgcn_s_barrier()
; #define PG8_SCHED __builtin_amdgcn_sched_barrier(0)
; template <class Epi, class Sched, bool ALIGN_EPI = false, bool SP2 = false>
; __device__ __forceinline__ void gemm_phase(PG8_LAS unsigned char* lds, const Gemm g, const Sched& S, const Epi& E) {
;     ...
;             PG8_WAIT_V(8); PG8_WAIT_L(0); PG8_BAR; PG8_MMA(1, 0, At, B0); PG8_MMA(1, 1, At, B1); PG8_BAR; PG8_SCHED;
;             PG8_LDB(B0, 1, 0); PG8_LDB(B1, 1, 1); PG8_SCHED; PG8_LDA(At, 1, 0); PG8_STAGE(PG8_SA(0, 1), a2 + hstep, voffA);
;             PG8_WAIT_V(8); PG8_WAIT_L(0); PG8_BAR; PG8_MMA(0, 0, At, B0); PG8_MMA(0, 1, At, B1); PG8_BAR; PG8_SCHED;
	s_setprio 1
	s_waitcnt lgkmcnt(0)
	v_mfma_f32_16x16x32_bf16 v[60:63], v[128:131], v[176:179], v[60:63]
	v_mfma_f32_16x16x32_bf16 v[56:59], v[136:139], v[176:179], v[56:59]
	v_mfma_f32_16x16x32_bf16 v[48:51], v[128:131], v[194:197], v[48:51]
	v_mfma_f32_16x16x32_bf16 v[40:43], v[136:139], v[194:197], v[40:43]
	v_mfma_f32_16x16x32_bf16 v[32:35], v[128:131], v[202:205], v[32:35]
	v_mfma_f32_16x16x32_bf16 v[24:27], v[136:139], v[202:205], v[24:27]
	v_mfma_f32_16x16x32_bf16 v[16:19], v[128:131], v[210:213], v[16:19]
	v_mfma_f32_16x16x32_bf16 v[8:11], v[136:139], v[210:213], v[8:11]
	v_mfma_f32_16x16x32_bf16 v[60:63], v[132:135], v[190:193], v[60:63]
	v_mfma_f32_16x16x32_bf16 v[56:59], v[140:143], v[190:193], v[56:59]
	v_mfma_f32_16x16x32_bf16 v[48:51], v[132:135], v[198:201], v[48:51]
	v_mfma_f32_16x16x32_bf16 v[40:43], v[140:143], v[198:201], v[40:43]
	v_mfma_f32_16x16x32_bf16 v[32:35], v[132:135], v[206:209], v[32:35]
	v_mfma_f32_16x16x32_bf16 v[24:27], v[140:143], v[206:209], v[24:27]
	v_mfma_f32_16x16x32_bf16 v[16:19], v[132:135], v[214:217], v[16:19]
	v_mfma_f32_16x16x32_bf16 v[8:11], v[140:143], v[214:217], v[8:11]
	v_mfma_f32_16x16x32_bf16 v[52:55], v[144:147], v[176:179], v[52:55]
	v_mfma_f32_16x16x32_bf16 v[44:47], v[168:171], v[176:179], v[44:47]
	v_mfma_f32_16x16x32_bf16 v[36:39], v[144:147], v[194:197], v[36:39]
	v_mfma_f32_16x16x32_bf16 v[28:31], v[168:171], v[194:197], v[28:31]
	v_mfma_f32_16x16x32_bf16 v[20:23], v[144:147], v[202:205], v[20:23]
	v_mfma_f32_16x16x32_bf16 v[12:15], v[168:171], v[202:205], v[12:15]
	v_mfma_f32_16x16x32_bf16 v[4:7], v[144:147], v[210:213], v[4:7]
	v_mfma_f32_16x16x32_bf16 v[0:3], v[168:171], v[210:213], v[0:3]
	v_mfma_f32_16x16x32_bf16 v[52:55], v[148:151], v[190:193], v[52:55]
	v_mfma_f32_16x16x32_bf16 v[44:47], v[172:175], v[190:193], v[44:47]
	v_mfma_f32_16x16x32_bf16 v[36:39], v[148:151], v[198:201], v[36:39]
	v_mfma_f32_16x16x32_bf16 v[28:31], v[172:175], v[198:201], v[28:31]
	v_mfma_f32_16x16x32_bf16 v[20:23], v[148:151], v[206:209], v[20:23]
	v_mfma_f32_16x16x32_bf16 v[12:15], v[172:175], v[206:209], v[12:15]
	v_mfma_f32_16x16x32_bf16 v[4:7], v[148:151], v[214:217], v[4:7]
	v_mfma_f32_16x16x32_bf16 v[0:3], v[172:175], v[214:217], v[0:3]
	s_setprio 0
	s_barrier
	s_add_i32 s54, 0, 0x18000
	s_add_i32 s55, 0, 0x1c000
	v_add_u32_e32 v140, s54, v181
	v_add_u32_e32 v172, s55, v181
	ds_read_b128 v[128:131], v140
	ds_read_b128 v[132:135], v140 offset:1024
	ds_read_b128 v[136:139], v140 offset:2048
	ds_read_b128 v[140:143], v140 offset:3072
	ds_read_b128 v[144:147], v172
	ds_read_b128 v[148:151], v172 offset:1024
	ds_read_b128 v[168:171], v172 offset:2048
	ds_read_b128 v[172:175], v172 offset:3072
	s_add_u32 s34, s34, 0x40000
	s_addc_u32 s35, s35, 0
	s_mov_b32 m0, s43
	v_lshl_add_u64 v[224:225], s[34:35], 0, v[152:153]
	ds_read_b128 v[176:179], v185 offset:32768
	ds_read_b128 v[190:193], v185 offset:33792
	ds_read_b128 v[194:197], v185 offset:34816
	ds_read_b128 v[198:201], v185 offset:35840
	ds_read_b128 v[202:205], v185 offset:36864
	ds_read_b128 v[206:209], v185 offset:37888
	ds_read_b128 v[210:213], v185 offset:38912
	ds_read_b128 v[214:217], v185 offset:39936
	global_load_lds_dwordx4 v[224:225], off
	v_lshl_add_u64 v[224:225], s[34:35], 0, v[156:157]
	s_mov_b32 m0, s44
	s_nop 0
	global_load_lds_dwordx4 v[224:225], off
	s_waitcnt vmcnt(8)
	s_waitcnt lgkmcnt(0)
	s_barrier
	s_setprio 1
	s_waitcnt lgkmcnt(0)
	v_mfma_f32_16x16x32_bf16 v[124:127], v[128:131], v[176:179], v[124:127]
	v_mfma_f32_16x16x32_bf16 v[120:123], v[136:139], v[176:179], v[120:123]
	v_mfma_f32_16x16x32_bf16 v[112:115], v[128:131], v[194:197], v[112:115]
	v_mfma_f32_16x16x32_bf16 v[104:107], v[136:139], v[194:197], v[104:107]
	v_mfma_f32_16x16x32_bf16 v[96:99], v[128:131], v[202:205], v[96:99]
	v_mfma_f32_16x16x32_bf16 v[88:91], v[136:139], v[202:205], v[88:91]
	v_mfma_f32_16x16x32_bf16 v[80:83], v[128:131], v[210:213], v[80:83]
	v_mfma_f32_16x16x32_bf16 v[72:75], v[136:139], v[210:213], v[72:75]
	v_mfma_f32_16x16x32_bf16 v[124:127], v[132:135], v[190:193], v[124:127]
	v_mfma_f32_16x16x32_bf16 v[120:123], v[140:143], v[190:193], v[120:123]
	v_mfma_f32_16x16x32_bf16 v[112:115], v[132:135], v[198:201], v[112:115]
	v_mfma_f32_16x16x32_bf16 v[104:107], v[140:143], v[198:201], v[104:107]
	v_mfma_f32_16x16x32_bf16 v[96:99], v[132:135], v[206:209], v[96:99]
	v_mfma_f32_16x16x32_bf16 v[88:91], v[140:143], v[206:209], v[88:91]
	v_mfma_f32_16x16x32_bf16 v[80:83], v[132:135], v[214:217], v[80:83]
	v_mfma_f32_16x16x32_bf16 v[72:75], v[140:143], v[214:217], v[72:75]
	v_mfma_f32_16x16x32_bf16 v[116:119], v[144:147], v[176:179], v[116:119]
	v_mfma_f32_16x16x32_bf16 v[108:111], v[168:171], v[176:179], v[108:111]
	v_mfma_f32_16x16x32_bf16 v[100:103], v[144:147], v[194:197], v[100:103]
	v_mfma_f32_16x16x32_bf16 v[92:95], v[168:171], v[194:197], v[92:95]
	v_mfma_f32_16x16x32_bf16 v[84:87], v[144:147], v[202:205], v[84:87]
	v_mfma_f32_16x16x32_bf16 v[76:79], v[168:171], v[202:205], v[76:79]
	v_mfma_f32_16x16x32_bf16 v[68:71], v[144:147], v[210:213], v[68:71]
	v_mfma_f32_16x16x32_bf16 v[64:67], v[168:171], v[210:213], v[64:67]
	v_mfma_f32_16x16x32_bf16 v[116:119], v[148:151], v[190:193], v[116:119]
	v_mfma_f32_16x16x32_bf16 v[108:111], v[172:175], v[190:193], v[108:111]
	v_mfma_f32_16x16x32_bf16 v[100:103], v[148:151], v[198:201], v[100:103]
	v_mfma_f32_16x16x32_bf16 v[92:95], v[172:175], v[198:201], v[92:95]
	v_mfma_f32_16x16x32_bf16 v[84:87], v[148:151], v[206:209], v[84:87]
	v_mfma_f32_16x16x32_bf16 v[76:79], v[172:175], v[206:209], v[76:79]
	v_mfma_f32_16x16x32_bf16 v[68:71], v[148:151], v[214:217], v[68:71]
	v_mfma_f32_16x16x32_bf16 v[64:67], v[172:175], v[214:217], v[64:67]
	s_setprio 0
	s_barrier
; #define PG8_STAGE(bufoff, gbase, voff) do { _Pragma("unroll") for (int _i = 0; _i < 2; ++_i) \
;         __builtin_amdgcn_global_load_lds((const unsigned*)((const char*)(gbase) + (voff)[_i]), (PG8_LAS unsigned*)(lds + (bufoff) + ldsw + _i * 8192), 16, 0, 0); } while (0)
; #define PG8_LDA(dst, b, h) do { _Pragma("unroll") for (int m = 0; m < 4; ++m) _Pragma("unroll") for (int k = 0; k < 2; ++k) dst[m][k] = *(const PG8_LAS bf16x8*)(lds + PG8_SA(b, h) + aoff + m * 2048 + k * 1024); } while (0)
; #define PG8_MMA(ai, bj, At, Bt) do { __builtin_amdgcn_s_setprio(1); _Pragma("unroll") for (int m = 0; m < 4; ++m) _Pragma("unroll") for (int n = 0; n < 2; ++n) _Pragma("unroll") for (int k = 0; k < 2; ++k) \
;         acc[ai][bj][m][n] = __builtin_amdgcn_mfma_f32_16x16x32_bf16(Bt[n][k], At[m][k], acc[ai][bj][m][n], 0, 0, 0); __builtin_amdgcn_s_setprio(0); } while (0)
; #define PG8_WAIT_V(n) asm volatile("s_waitcnt vmcnt(" #n ")" ::: "memory")
; #define PG8_WAIT_L(n) asm volatile("s_waitcnt lgkmcnt(" #n ")" ::: "memory")
; #define PG8_BAR __builtin_amdgcn_s_barrier()
; #define PG8_SCHED __builtin_amdgcn_sched_barrier(0)
; template <class Epi, class Sched, bool ALIGN_EPI = false, bool SP2 = false>
; __device__ __forceinline__ void gemm_phase(PG8_LAS unsigned char* lds, const Gemm g, const Sched& S, const Epi& E) {
;     ...
;             PG8_LDA(At, 1, 1); PG8_STAGE(PG8_SB(1, 0), b3, voffB); PG8_STAGE(PG8_SB(1, 1), b3 + hstep, voffB); PG8_STAGE(PG8_SA(1, 0), a3, voffA);
;             PG8_WAIT_V(8); PG8_WAIT_L(0); PG8_BAR; PG8_MMA(1, 0, At, B0); PG8_MMA(1, 1, At, B1); PG8_BAR; PG8_SCHED;
;     ...
;         if constexpr (ALIGN_EPI) { if (wr == 0) PG8_BAR; }
	s_add_i32 s34, s54, s41
	v_lshl_add_u64 v[186:187], v[186:187], 0, s[14:15]
	s_mov_b32 m0, s34
	ds_read_b128 v[176:179], v185 offset:49152
	ds_read_b128 v[190:193], v185 offset:50176
	ds_read_b128 v[194:197], v185 offset:51200
	ds_read_b128 v[198:201], v185 offset:52224
	ds_read_b128 v[202:205], v185 offset:53248
	ds_read_b128 v[206:209], v185 offset:54272
	ds_read_b128 v[210:213], v185 offset:55296
	ds_read_b128 v[214:217], v185 offset:56320
	global_load_lds_dwordx4 v[186:187], off
	s_add_i32 m0, s34, 0x2000
	s_add_u32 s30, s30, 0x40080
	v_lshl_add_u64 v[186:187], v[218:219], 0, s[14:15]
	s_addc_u32 s31, s31, 0
	s_add_i32 s34, s55, s41
	global_load_lds_dwordx4 v[186:187], off
	v_lshl_add_u64 v[186:187], s[30:31], 0, v[154:155]
	s_mov_b32 m0, s34
	s_nop 0
	global_load_lds_dwordx4 v[186:187], off
	v_lshl_add_u64 v[186:187], s[30:31], 0, v[158:159]
	s_add_i32 m0, s34, 0x2000
	s_nop 0
	global_load_lds_dwordx4 v[186:187], off
	v_lshl_add_u64 v[186:187], v[220:221], 0, s[14:15]
	s_mov_b32 m0, s46
	s_nop 0
	global_load_lds_dwordx4 v[186:187], off
	v_lshl_add_u64 v[186:187], v[222:223], 0, s[14:15]
	s_mov_b32 m0, s47
	s_nop 0
	global_load_lds_dwordx4 v[186:187], off
	s_waitcnt vmcnt(8)
	s_waitcnt lgkmcnt(0)
	s_barrier
	s_setprio 1
	s_waitcnt lgkmcnt(0)
	v_mfma_f32_16x16x32_bf16 v[60:63], v[128:131], v[176:179], v[60:63]
	v_mfma_f32_16x16x32_bf16 v[56:59], v[136:139], v[176:179], v[56:59]
	v_mfma_f32_16x16x32_bf16 v[48:51], v[128:131], v[194:197], v[48:51]
	v_mfma_f32_16x16x32_bf16 v[40:43], v[136:139], v[194:197], v[40:43]
	v_mfma_f32_16x16x32_bf16 v[32:35], v[128:131], v[202:205], v[32:35]
	v_mfma_f32_16x16x32_bf16 v[24:27], v[136:139], v[202:205], v[24:27]
	v_mfma_f32_16x16x32_bf16 v[16:19], v[128:131], v[210:213], v[16:19]
	v_mfma_f32_16x16x32_bf16 v[8:11], v[136:139], v[210:213], v[8:11]
	v_mfma_f32_16x16x32_bf16 v[60:63], v[132:135], v[190:193], v[60:63]
	v_mfma_f32_16x16x32_bf16 v[56:59], v[140:143], v[190:193], v[56:59]
	v_mfma_f32_16x16x32_bf16 v[48:51], v[132:135], v[198:201], v[48:51]
	v_mfma_f32_16x16x32_bf16 v[40:43], v[140:143], v[198:201], v[40:43]
	v_mfma_f32_16x16x32_bf16 v[32:35], v[132:135], v[206:209], v[32:35]
	v_mfma_f32_16x16x32_bf16 v[24:27], v[140:143], v[206:209], v[24:27]
	v_mfma_f32_16x16x32_bf16 v[16:19], v[132:135], v[214:217], v[16:19]
	v_mfma_f32_16x16x32_bf16 v[8:11], v[140:143], v[214:217], v[8:11]
	v_mfma_f32_16x16x32_bf16 v[52:55], v[144:147], v[176:179], v[52:55]
	v_mfma_f32_16x16x32_bf16 v[44:47], v[168:171], v[176:179], v[44:47]
	v_mfma_f32_16x16x32_bf16 v[36:39], v[144:147], v[194:197], v[36:39]
	v_mfma_f32_16x16x32_bf16 v[28:31], v[168:171], v[194:197], v[28:31]
	v_mfma_f32_16x16x32_bf16 v[20:23], v[144:147], v[202:205], v[20:23]
	v_mfma_f32_16x16x32_bf16 v[12:15], v[168:171], v[202:205], v[12:15]
	v_mfma_f32_16x16x32_bf16 v[4:7], v[144:147], v[210:213], v[4:7]
	v_mfma_f32_16x16x32_bf16 v[0:3], v[168:171], v[210:213], v[0:3]
	v_mfma_f32_16x16x32_bf16 v[52:55], v[148:151], v[190:193], v[52:55]
	v_mfma_f32_16x16x32_bf16 v[44:47], v[172:175], v[190:193], v[44:47]
	v_mfma_f32_16x16x32_bf16 v[36:39], v[148:151], v[198:201], v[36:39]
	v_mfma_f32_16x16x32_bf16 v[28:31], v[172:175], v[198:201], v[28:31]
	v_mfma_f32_16x16x32_bf16 v[20:23], v[148:151], v[206:209], v[20:23]
	v_mfma_f32_16x16x32_bf16 v[12:15], v[172:175], v[206:209], v[12:15]
	v_mfma_f32_16x16x32_bf16 v[4:7], v[148:151], v[214:217], v[4:7]
	v_mfma_f32_16x16x32_bf16 v[0:3], v[172:175], v[214:217], v[0:3]
	s_setprio 0
	s_barrier
	s_add_i32 s61, s61, 2
	s_add_u32 s28, s28, 0x100
	s_addc_u32 s29, s29, 0
	s_add_u32 s59, s59, 0x100
	s_addc_u32 s60, s60, 0
	s_cmp_gt_u32 s61, 13
	s_cbranch_scc0 .LBB0_604
	s_and_b64 vcc, exec, s[16:17]
	s_cbranch_vccz .LBB0_607
	s_barrier

; #define PG8_STAGE(bufoff, gbase, voff) do { _Pragma("unroll") for (int _i = 0; _i < 2; ++_i) \
;         __builtin_amdgcn_global_load_lds((const unsigned*)((const char*)(gbase) + (voff)[_i]), (PG8_LAS unsigned*)(lds + (bufoff) + ldsw + _i * 8192), 16, 0, 0); } while (0)
; #define PG8_LDA(dst, b, h) do { _Pragma("unroll") for (int m = 0; m < 4; ++m) _Pragma("unroll") for (int k = 0; k < 2; ++k) dst[m][k] = *(const PG8_LAS bf16x8*)(lds + PG8_SA(b, h) + aoff + m * 2048 + k * 1024); } while (0)
; #define PG8_LDB(dst, b, h) do { _Pragma("unroll") for (int n = 0; n < 2; ++n) _Pragma("unroll") for (int k = 0; k < 2; ++k) dst[n][k] = *(const PG8_LAS bf16x8*)(lds + PG8_SB(b, h) + boff + n * 2048 + k * 1024); } while (0)
; #define PG8_MMA(ai, bj, At, Bt) do { __builtin_amdgcn_s_setprio(1); _Pragma("unroll") for (int m = 0; m < 4; ++m) _Pragma("unroll") for (int n = 0; n < 2; ++n) _Pragma("unroll") for (int k = 0; k < 2; ++k) \
;         acc[ai][bj][m][n] = __builtin_amdgcn_mfma_f32_16x16x32_bf16(Bt[n][k], At[m][k], acc[ai][bj][m][n], 0, 0, 0); __builtin_amdgcn_s_setprio(0); } while (0)
; #define PG8_WAIT_V(n) asm volatile("s_waitcnt vmcnt(" #n ")" ::: "memory")
; #define PG8_WAIT_L(n) asm volatile("s_waitcnt lgkmcnt(" #n ")" ::: "memory")
; #define PG8_BAR __builtin_amdgcn_s_barrier()
; #define PG8_SCHED __builtin_amdgcn_sched_barrier(0)
; template <class Epi, class Sched, bool ALIGN_EPI = false, bool SP2 = false>
; __device__ __forceinline__ void gemm_phase(PG8_LAS unsigned char* lds, const Gemm g, const Sched& S, const Epi& E) {
;     ...
;             const bool last = (t == nt - 2);
;             const char* a1 = cA + (size_t)(t + 1) * kstep;
;             const char* a2 = last ? nA : cA + (size_t)(t + 2) * kstep; const char* b2 = last ? nB : cB + (size_t)(t + 2) * kstep;
;             const char* a3 = a2 + kstep; const char* b3 = b2 + kstep;
;             if (last && has_next) S.a_ready(nxt);
;             if constexpr (SP2) {
;             PG8_LDB(B0, 0, 0); PG8_LDB(B1, 0, 1); PG8_SCHED; PG8_LDA(At, 0, 0); PG8_STAGE(PG8_SA(1, 1), a1 + hstep, voffA);
;             PG8_WAIT_V(8); PG8_WAIT_L(0); PG8_BAR; PG8_MMA(0, 0, At, B0); PG8_MMA(0, 1, At, B1); PG8_BAR; PG8_SCHED;
;             PG8_LDA(At, 0, 1); PG8_STAGE(PG8_SB(0, 0), b2, voffB); PG8_STAGE(PG8_SB(0, 1), b2 + hstep, voffB); PG8_STAGE(PG8_SA(0, 0), a2, voffA);
.LBB0_681:
	v_add_u32_e32 v157, s42, v150
	ds_read_b128 v[152:155], v157
	ds_read_b128 v[158:161], v157 offset:1024
	ds_read_b128 v[162:165], v157 offset:2048
	ds_read_b128 v[166:169], v157 offset:3072
	v_add_u32_e32 v157, s43, v150
	s_add_u32 s24, s10, s22
	ds_read_b128 v[170:173], v157
	ds_read_b128 v[174:177], v157 offset:1024
	ds_read_b128 v[178:181], v157 offset:2048
	ds_read_b128 v[182:185], v157 offset:3072
	s_addc_u32 s25, s11, s23
	s_add_u32 s24, s24, 0x100
	s_addc_u32 s25, s25, 0
	s_add_u32 s50, s45, s22
	s_addc_u32 s51, s46, s23
	s_cmpk_eq_i32 s22, 0x700
	s_cselect_b32 s27, s17, s25
	s_cselect_b32 s26, s47, s24
	s_cselect_b32 s25, s15, s51
	s_cselect_b32 s24, s48, s50
	v_lshl_add_u64 v[186:187], v[144:145], 0, s[22:23]
	s_add_i32 m0, s34, 0xc000
	ds_read_b128 v[190:193], v151
	ds_read_b128 v[194:197], v151 offset:1024
	ds_read_b128 v[198:201], v151 offset:2048
	ds_read_b128 v[202:205], v151 offset:3072
	ds_read_b128 v[206:209], v151 offset:4096
	ds_read_b128 v[210:213], v151 offset:5120
	ds_read_b128 v[214:217], v151 offset:6144
	ds_read_b128 v[218:221], v151 offset:7168
	global_load_lds_dwordx4 v[186:187], off
	v_lshl_add_u64 v[186:187], v[146:147], 0, s[22:23]
	s_add_i32 m0, s34, 0xe000
	s_nop 0
	global_load_lds_dwordx4 v[186:187], off
	s_waitcnt vmcnt(8)
	s_waitcnt lgkmcnt(0)
	s_barrier
	s_setprio 1
	s_waitcnt lgkmcnt(0)
	v_mfma_f32_16x16x32_bf16 v[124:127], v[152:155], v[190:193], v[124:127]
	v_mfma_f32_16x16x32_bf16 v[120:123], v[162:165], v[190:193], v[120:123]
	v_mfma_f32_16x16x32_bf16 v[108:111], v[152:155], v[198:201], v[108:111]
	v_mfma_f32_16x16x32_bf16 v[104:107], v[162:165], v[198:201], v[104:107]
	v_mfma_f32_16x16x32_bf16 v[92:95], v[152:155], v[206:209], v[92:95]
	v_mfma_f32_16x16x32_bf16 v[88:91], v[162:165], v[206:209], v[88:91]
	v_mfma_f32_16x16x32_bf16 v[76:79], v[152:155], v[214:217], v[76:79]
	v_mfma_f32_16x16x32_bf16 v[72:75], v[162:165], v[214:217], v[72:75]
	v_mfma_f32_16x16x32_bf16 v[124:127], v[158:161], v[194:197], v[124:127]
	v_mfma_f32_16x16x32_bf16 v[120:123], v[166:169], v[194:197], v[120:123]
	v_mfma_f32_16x16x32_bf16 v[108:111], v[158:161], v[202:205], v[108:111]
	v_mfma_f32_16x16x32_bf16 v[104:107], v[166:169], v[202:205], v[104:107]
	v_mfma_f32_16x16x32_bf16 v[92:95], v[158:161], v[210:213], v[92:95]
	v_mfma_f32_16x16x32_bf16 v[88:91], v[166:169], v[210:213], v[88:91]
	v_mfma_f32_16x16x32_bf16 v[76:79], v[158:161], v[218:221], v[76:79]
	v_mfma_f32_16x16x32_bf16 v[72:75], v[166:169], v[218:221], v[72:75]
	v_mfma_f32_16x16x32_bf16 v[116:119], v[170:173], v[190:193], v[116:119]
	v_mfma_f32_16x16x32_bf16 v[112:115], v[178:181], v[190:193], v[112:115]
	v_mfma_f32_16x16x32_bf16 v[100:103], v[170:173], v[198:201], v[100:103]
	v_mfma_f32_16x16x32_bf16 v[96:99], v[178:181], v[198:201], v[96:99]
	v_mfma_f32_16x16x32_bf16 v[84:87], v[170:173], v[206:209], v[84:87]
	v_mfma_f32_16x16x32_bf16 v[80:83], v[178:181], v[206:209], v[80:83]
	v_mfma_f32_16x16x32_bf16 v[68:71], v[170:173], v[214:217], v[68:71]
	v_mfma_f32_16x16x32_bf16 v[64:67], v[178:181], v[214:217], v[64:67]
	v_mfma_f32_16x16x32_bf16 v[116:119], v[174:177], v[194:197], v[116:119]
	v_mfma_f32_16x16x32_bf16 v[112:115], v[182:185], v[194:197], v[112:115]
	v_mfma_f32_16x16x32_bf16 v[100:103], v[174:177], v[202:205], v[100:103]
	v_mfma_f32_16x16x32_bf16 v[96:99], v[182:185], v[202:205], v[96:99]
	v_mfma_f32_16x16x32_bf16 v[84:87], v[174:177], v[210:213], v[84:87]
	v_mfma_f32_16x16x32_bf16 v[80:83], v[182:185], v[210:213], v[80:83]
	v_mfma_f32_16x16x32_bf16 v[68:71], v[174:177], v[218:221], v[68:71]
	v_mfma_f32_16x16x32_bf16 v[64:67], v[182:185], v[218:221], v[64:67]
	s_setprio 0
	s_barrier
	s_add_i32 s50, s42, s33
	v_lshl_add_u64 v[186:187], s[24:25], 0, v[130:131]
	s_mov_b32 m0, s50
	ds_read_b128 v[190:193], v151 offset:16384
	ds_read_b128 v[194:197], v151 offset:17408
	ds_read_b128 v[198:201], v151 offset:18432
	ds_read_b128 v[202:205], v151 offset:19456
	ds_read_b128 v[206:209], v151 offset:20480
	ds_read_b128 v[210:213], v151 offset:21504
	ds_read_b128 v[214:217], v151 offset:22528
	ds_read_b128 v[218:221], v151 offset:23552
	global_load_lds_dwordx4 v[186:187], off
	s_add_i32 m0, s50, 0x2000
	s_add_u32 s50, s24, 0x40000
	v_lshl_add_u64 v[222:223], s[24:25], 0, v[134:135]
	s_addc_u32 s51, s25, 0
	s_add_i32 s52, s43, s33
	global_load_lds_dwordx4 v[222:223], off
	v_lshl_add_u64 v[224:225], s[50:51], 0, v[130:131]
	s_mov_b32 m0, s52
	v_lshl_add_u64 v[226:227], s[26:27], 0, v[132:133]
	global_load_lds_dwordx4 v[224:225], off
	v_lshl_add_u64 v[224:225], s[50:51], 0, v[134:135]
	s_add_i32 m0, s52, 0x2000
	s_nop 0
	global_load_lds_dwordx4 v[224:225], off
	v_lshl_add_u64 v[224:225], s[26:27], 0, v[128:129]
	s_mov_b32 m0, s34
	s_nop 0
	global_load_lds_dwordx4 v[224:225], off
	s_mov_b32 m0, s35
	s_nop 0
	global_load_lds_dwordx4 v[226:227], off
	s_waitcnt vmcnt(8)
	s_waitcnt lgkmcnt(0)
	s_barrier
; #define PG8_STAGE(bufoff, gbase, voff) do { _Pragma("unroll") for (int _i = 0; _i < 2; ++_i) \
;         __builtin_amdgcn_global_load_lds((const unsigned*)((const char*)(gbase) + (voff)[_i]), (PG8_LAS unsigned*)(lds + (bufoff) + ldsw + _i * 8192), 16, 0, 0); } while (0)
; #define PG8_LDA(dst, b, h) do { _Pragma("unroll") for (int m = 0; m < 4; ++m) _Pragma("unroll") for (int k = 0; k < 2; ++k) dst[m][k] = *(const PG8_LAS bf16x8*)(lds + PG8_SA(b, h) + aoff + m * 2048 + k * 1024); } while (0)
; #define PG8_LDB(dst, b, h) do { _Pragma("unroll") for (int n = 0; n < 2; ++n) _Pragma("unroll") for (int k = 0; k < 2; ++k) dst[n][k] = *(const PG8_LAS bf16x8*)(lds + PG8_SB(b, h) + boff + n * 2048 + k * 1024); } while (0)
; #define PG8_MMA(ai, bj, At, Bt) do { __builtin_amdgcn_s_setprio(1); _Pragma("unroll") for (int m = 0; m < 4; ++m) _Pragma("unroll") for (int n = 0; n < 2; ++n) _Pragma("unroll") for (int k = 0; k < 2; ++k) \
;         acc[ai][bj][m][n] = __builtin_amdgcn_mfma_f32_16x16x32_bf16(Bt[n][k], At[m][k], acc[ai][bj][m][n], 0, 0, 0); __builtin_amdgcn_s_setprio(0); } while (0)
; #define PG8_WAIT_V(n) asm volatile("s_waitcnt vmcnt(" #n ")" ::: "memory")
; #define PG8_WAIT_L(n) asm volatile("s_waitcnt lgkmcnt(" #n ")" ::: "memory")
; #define PG8_BAR __builtin_amdgcn_s_barrier()
; #define PG8_SCHED __builtin_amdgcn_sched_barrier(0)
; template <class Epi, class Sched, bool ALIGN_EPI = false, bool SP2 = false>
; __device__ __forceinline__ void gemm_phase(PG8_LAS unsigned char* lds, const Gemm g, const Sched& S, const Epi& E) {
;     ...
;             PG8_WAIT_V(8); PG8_WAIT_L(0); PG8_BAR; PG8_MMA(1, 0, At, B0); PG8_MMA(1, 1, At, B1); PG8_BAR; PG8_SCHED;
;             PG8_LDB(B0, 1, 0); PG8_LDB(B1, 1, 1); PG8_SCHED; PG8_LDA(At, 1, 0); PG8_STAGE(PG8_SA(0, 1), a2 + hstep, voffA);
;             PG8_WAIT_V(8); PG8_WAIT_L(0); PG8_BAR; PG8_MMA(0, 0, At, B0); PG8_MMA(0, 1, At, B1); PG8_BAR; PG8_SCHED;
	s_setprio 1
	s_waitcnt lgkmcnt(0)
	v_mfma_f32_16x16x32_bf16 v[56:59], v[152:155], v[190:193], v[56:59]
	v_mfma_f32_16x16x32_bf16 v[60:63], v[162:165], v[190:193], v[60:63]
	v_mfma_f32_16x16x32_bf16 v[44:47], v[152:155], v[198:201], v[44:47]
	v_mfma_f32_16x16x32_bf16 v[40:43], v[162:165], v[198:201], v[40:43]
	v_mfma_f32_16x16x32_bf16 v[24:27], v[152:155], v[206:209], v[24:27]
	v_mfma_f32_16x16x32_bf16 v[28:31], v[162:165], v[206:209], v[28:31]
	v_mfma_f32_16x16x32_bf16 v[12:15], v[152:155], v[214:217], v[12:15]
	v_mfma_f32_16x16x32_bf16 v[8:11], v[162:165], v[214:217], v[8:11]
	v_mfma_f32_16x16x32_bf16 v[56:59], v[158:161], v[194:197], v[56:59]
	v_mfma_f32_16x16x32_bf16 v[60:63], v[166:169], v[194:197], v[60:63]
	v_mfma_f32_16x16x32_bf16 v[44:47], v[158:161], v[202:205], v[44:47]
	v_mfma_f32_16x16x32_bf16 v[40:43], v[166:169], v[202:205], v[40:43]
	v_mfma_f32_16x16x32_bf16 v[24:27], v[158:161], v[210:213], v[24:27]
	v_mfma_f32_16x16x32_bf16 v[28:31], v[166:169], v[210:213], v[28:31]
	v_mfma_f32_16x16x32_bf16 v[12:15], v[158:161], v[218:221], v[12:15]
	v_mfma_f32_16x16x32_bf16 v[8:11], v[166:169], v[218:221], v[8:11]
	v_mfma_f32_16x16x32_bf16 v[52:55], v[170:173], v[190:193], v[52:55]
	v_mfma_f32_16x16x32_bf16 v[48:51], v[178:181], v[190:193], v[48:51]
	v_mfma_f32_16x16x32_bf16 v[36:39], v[170:173], v[198:201], v[36:39]
	v_mfma_f32_16x16x32_bf16 v[32:35], v[178:181], v[198:201], v[32:35]
	v_mfma_f32_16x16x32_bf16 v[20:23], v[170:173], v[206:209], v[20:23]
	v_mfma_f32_16x16x32_bf16 v[16:19], v[178:181], v[206:209], v[16:19]
	v_mfma_f32_16x16x32_bf16 v[4:7], v[170:173], v[214:217], v[4:7]
	v_mfma_f32_16x16x32_bf16 v[0:3], v[178:181], v[214:217], v[0:3]
	v_mfma_f32_16x16x32_bf16 v[52:55], v[174:177], v[194:197], v[52:55]
	v_mfma_f32_16x16x32_bf16 v[48:51], v[182:185], v[194:197], v[48:51]
	v_mfma_f32_16x16x32_bf16 v[36:39], v[174:177], v[202:205], v[36:39]
	v_mfma_f32_16x16x32_bf16 v[32:35], v[182:185], v[202:205], v[32:35]
	v_mfma_f32_16x16x32_bf16 v[20:23], v[174:177], v[210:213], v[20:23]
	v_mfma_f32_16x16x32_bf16 v[16:19], v[182:185], v[210:213], v[16:19]
	v_mfma_f32_16x16x32_bf16 v[4:7], v[174:177], v[218:221], v[4:7]
	v_mfma_f32_16x16x32_bf16 v[0:3], v[182:185], v[218:221], v[0:3]
	s_setprio 0
	s_barrier
	s_add_i32 s50, 0, 0x18000
	v_add_u32_e32 v157, s50, v150
	s_add_i32 s51, 0, 0x1c000
	ds_read_b128 v[152:155], v157
	ds_read_b128 v[158:161], v157 offset:1024
	ds_read_b128 v[162:165], v157 offset:2048
	ds_read_b128 v[166:169], v157 offset:3072
	v_add_u32_e32 v157, s51, v150
	ds_read_b128 v[170:173], v157
	ds_read_b128 v[174:177], v157 offset:1024
	ds_read_b128 v[178:181], v157 offset:2048
	ds_read_b128 v[182:185], v157 offset:3072
	s_add_u32 s26, s26, 0x40000
	s_addc_u32 s27, s27, 0
	s_mov_b32 m0, s36
	v_lshl_add_u64 v[228:229], s[26:27], 0, v[128:129]
	ds_read_b128 v[190:193], v151 offset:32768
	ds_read_b128 v[194:197], v151 offset:33792
	ds_read_b128 v[198:201], v151 offset:34816
	ds_read_b128 v[202:205], v151 offset:35840
	ds_read_b128 v[206:209], v151 offset:36864
	ds_read_b128 v[210:213], v151 offset:37888
	ds_read_b128 v[214:217], v151 offset:38912
	ds_read_b128 v[218:221], v151 offset:39936
	global_load_lds_dwordx4 v[228:229], off
	v_lshl_add_u64 v[228:229], s[26:27], 0, v[132:133]
	s_mov_b32 m0, s37
	s_nop 0
	global_load_lds_dwordx4 v[228:229], off
	s_waitcnt vmcnt(8)
	s_waitcnt lgkmcnt(0)
	s_barrier
	s_setprio 1
	s_waitcnt lgkmcnt(0)
	v_mfma_f32_16x16x32_bf16 v[124:127], v[152:155], v[190:193], v[124:127]
	v_mfma_f32_16x16x32_bf16 v[120:123], v[162:165], v[190:193], v[120:123]
	v_mfma_f32_16x16x32_bf16 v[108:111], v[152:155], v[198:201], v[108:111]
	v_mfma_f32_16x16x32_bf16 v[104:107], v[162:165], v[198:201], v[104:107]
	v_mfma_f32_16x16x32_bf16 v[92:95], v[152:155], v[206:209], v[92:95]
	v_mfma_f32_16x16x32_bf16 v[88:91], v[162:165], v[206:209], v[88:91]
	v_mfma_f32_16x16x32_bf16 v[76:79], v[152:155], v[214:217], v[76:79]
	v_mfma_f32_16x16x32_bf16 v[72:75], v[162:165], v[214:217], v[72:75]
	v_mfma_f32_16x16x32_bf16 v[124:127], v[158:161], v[194:197], v[124:127]
	v_mfma_f32_16x16x32_bf16 v[120:123], v[166:169], v[194:197], v[120:123]
	v_mfma_f32_16x16x32_bf16 v[108:111], v[158:161], v[202:205], v[108:111]
	v_mfma_f32_16x16x32_bf16 v[104:107], v[166:169], v[202:205], v[104:107]
	v_mfma_f32_16x16x32_bf16 v[92:95], v[158:161], v[210:213], v[92:95]
	v_mfma_f32_16x16x32_bf16 v[88:91], v[166:169], v[210:213], v[88:91]
	v_mfma_f32_16x16x32_bf16 v[76:79], v[158:161], v[218:221], v[76:79]
	v_mfma_f32_16x16x32_bf16 v[72:75], v[166:169], v[218:221], v[72:75]
	v_mfma_f32_16x16x32_bf16 v[116:119], v[170:173], v[190:193], v[116:119]
	v_mfma_f32_16x16x32_bf16 v[112:115], v[178:181], v[190:193], v[112:115]
	v_mfma_f32_16x16x32_bf16 v[100:103], v[170:173], v[198:201], v[100:103]
	v_mfma_f32_16x16x32_bf16 v[96:99], v[178:181], v[198:201], v[96:99]
	v_mfma_f32_16x16x32_bf16 v[84:87], v[170:173], v[206:209], v[84:87]
	v_mfma_f32_16x16x32_bf16 v[80:83], v[178:181], v[206:209], v[80:83]
	v_mfma_f32_16x16x32_bf16 v[68:71], v[170:173], v[214:217], v[68:71]
	v_mfma_f32_16x16x32_bf16 v[64:67], v[178:181], v[214:217], v[64:67]
	v_mfma_f32_16x16x32_bf16 v[116:119], v[174:177], v[194:197], v[116:119]
	v_mfma_f32_16x16x32_bf16 v[112:115], v[182:185], v[194:197], v[112:115]
	v_mfma_f32_16x16x32_bf16 v[100:103], v[174:177], v[202:205], v[100:103]
	v_mfma_f32_16x16x32_bf16 v[96:99], v[182:185], v[202:205], v[96:99]
	v_mfma_f32_16x16x32_bf16 v[84:87], v[174:177], v[210:213], v[84:87]
	v_mfma_f32_16x16x32_bf16 v[80:83], v[182:185], v[210:213], v[80:83]
	v_mfma_f32_16x16x32_bf16 v[68:71], v[174:177], v[218:221], v[68:71]
	v_mfma_f32_16x16x32_bf16 v[64:67], v[182:185], v[218:221], v[64:67]
	s_setprio 0
	s_barrier
; #define PG8_STAGE(bufoff, gbase, voff) do { _Pragma("unroll") for (int _i = 0; _i < 2; ++_i) \
;         __builtin_amdgcn_global_load_lds((const unsigned*)((const char*)(gbase) + (voff)[_i]), (PG8_LAS unsigned*)(lds + (bufoff) + ldsw + _i * 8192), 16, 0, 0); } while (0)
; #define PG8_LDA(dst, b, h) do { _Pragma("unroll") for (int m = 0; m < 4; ++m) _Pragma("unroll") for (int k = 0; k < 2; ++k) dst[m][k] = *(const PG8_LAS bf16x8*)(lds + PG8_SA(b, h) + aoff + m * 2048 + k * 1024); } while (0)
; #define PG8_MMA(ai, bj, At, Bt) do { __builtin_amdgcn_s_setprio(1); _Pragma("unroll") for (int m = 0; m < 4; ++m) _Pragma("unroll") for (int n = 0; n < 2; ++n) _Pragma("unroll") for (int k = 0; k < 2; ++k) \
;         acc[ai][bj][m][n] = __builtin_amdgcn_mfma_f32_16x16x32_bf16(Bt[n][k], At[m][k], acc[ai][bj][m][n], 0, 0, 0); __builtin_amdgcn_s_setprio(0); } while (0)
; #define PG8_WAIT_V(n) asm volatile("s_waitcnt vmcnt(" #n ")" ::: "memory")
; #define PG8_WAIT_L(n) asm volatile("s_waitcnt lgkmcnt(" #n ")" ::: "memory")
; #define PG8_BAR __builtin_amdgcn_s_barrier()
; #define PG8_SCHED __builtin_amdgcn_sched_barrier(0)
; template <class Epi, class Sched, bool ALIGN_EPI = false, bool SP2 = false>
; __device__ __forceinline__ void gemm_phase(PG8_LAS unsigned char* lds, const Gemm g, const Sched& S, const Epi& E) {
;     ...
;             PG8_LDA(At, 1, 1); PG8_STAGE(PG8_SB(1, 0), b3, voffB); PG8_STAGE(PG8_SB(1, 1), b3 + hstep, voffB); PG8_STAGE(PG8_SA(1, 0), a3, voffA);
;             PG8_WAIT_V(8); PG8_WAIT_L(0); PG8_BAR; PG8_MMA(1, 0, At, B0); PG8_MMA(1, 1, At, B1); PG8_BAR; PG8_SCHED;
;     ...
;         if (!has_next) break;
; #pragma unroll
;         for (int a = 0; a < 2; ++a)
; #pragma unroll
;             for (int b = 0; b < 2; ++b)
; #pragma unroll
;                 for (int m = 0; m < 4; ++m)
; #pragma unroll
;                     for (int n = 0; n < 2; ++n) acc[a][b][m][n] = (f32x4){0.f, 0.f, 0.f, 0.f};
;         cur = nxt; cA = nA; cB = nB; ++ui;
	s_add_i32 s26, s50, s33
	v_lshl_add_u64 v[186:187], v[186:187], 0, s[12:13]
	s_mov_b32 m0, s26
	ds_read_b128 v[190:193], v151 offset:49152
	ds_read_b128 v[194:197], v151 offset:50176
	ds_read_b128 v[198:201], v151 offset:51200
	ds_read_b128 v[202:205], v151 offset:52224
	ds_read_b128 v[206:209], v151 offset:53248
	ds_read_b128 v[210:213], v151 offset:54272
	ds_read_b128 v[214:217], v151 offset:55296
	ds_read_b128 v[218:221], v151 offset:56320
	global_load_lds_dwordx4 v[186:187], off
	s_add_i32 m0, s26, 0x2000
	s_add_u32 s24, s24, 0x40080
	v_lshl_add_u64 v[186:187], v[222:223], 0, s[12:13]
	s_addc_u32 s25, s25, 0
	s_add_i32 s26, s51, s33
	global_load_lds_dwordx4 v[186:187], off
	v_lshl_add_u64 v[186:187], s[24:25], 0, v[130:131]
	s_mov_b32 m0, s26
	s_nop 0
	global_load_lds_dwordx4 v[186:187], off
	v_lshl_add_u64 v[186:187], s[24:25], 0, v[134:135]
	s_add_i32 m0, s26, 0x2000
	s_nop 0
	global_load_lds_dwordx4 v[186:187], off
	v_lshl_add_u64 v[186:187], v[224:225], 0, s[12:13]
	s_mov_b32 m0, s39
	s_nop 0
	global_load_lds_dwordx4 v[186:187], off
	v_lshl_add_u64 v[186:187], v[226:227], 0, s[12:13]
	s_mov_b32 m0, s40
	s_nop 0
	global_load_lds_dwordx4 v[186:187], off
	s_waitcnt vmcnt(8)
	s_waitcnt lgkmcnt(0)
	s_barrier
	s_setprio 1
	s_waitcnt lgkmcnt(0)
	v_mfma_f32_16x16x32_bf16 v[56:59], v[152:155], v[190:193], v[56:59]
	v_mfma_f32_16x16x32_bf16 v[60:63], v[162:165], v[190:193], v[60:63]
	v_mfma_f32_16x16x32_bf16 v[44:47], v[152:155], v[198:201], v[44:47]
	v_mfma_f32_16x16x32_bf16 v[40:43], v[162:165], v[198:201], v[40:43]
	v_mfma_f32_16x16x32_bf16 v[24:27], v[152:155], v[206:209], v[24:27]
	v_mfma_f32_16x16x32_bf16 v[28:31], v[162:165], v[206:209], v[28:31]
	v_mfma_f32_16x16x32_bf16 v[12:15], v[152:155], v[214:217], v[12:15]
	v_mfma_f32_16x16x32_bf16 v[8:11], v[162:165], v[214:217], v[8:11]
	v_mfma_f32_16x16x32_bf16 v[56:59], v[158:161], v[194:197], v[56:59]
	v_mfma_f32_16x16x32_bf16 v[60:63], v[166:169], v[194:197], v[60:63]
	v_mfma_f32_16x16x32_bf16 v[44:47], v[158:161], v[202:205], v[44:47]
	v_mfma_f32_16x16x32_bf16 v[40:43], v[166:169], v[202:205], v[40:43]
	v_mfma_f32_16x16x32_bf16 v[24:27], v[158:161], v[210:213], v[24:27]
	v_mfma_f32_16x16x32_bf16 v[28:31], v[166:169], v[210:213], v[28:31]
	v_mfma_f32_16x16x32_bf16 v[12:15], v[158:161], v[218:221], v[12:15]
	v_mfma_f32_16x16x32_bf16 v[8:11], v[166:169], v[218:221], v[8:11]
	v_mfma_f32_16x16x32_bf16 v[52:55], v[170:173], v[190:193], v[52:55]
	v_mfma_f32_16x16x32_bf16 v[48:51], v[178:181], v[190:193], v[48:51]
	v_mfma_f32_16x16x32_bf16 v[36:39], v[170:173], v[198:201], v[36:39]
	v_mfma_f32_16x16x32_bf16 v[32:35], v[178:181], v[198:201], v[32:35]
	v_mfma_f32_16x16x32_bf16 v[20:23], v[170:173], v[206:209], v[20:23]
	v_mfma_f32_16x16x32_bf16 v[16:19], v[178:181], v[206:209], v[16:19]
	v_mfma_f32_16x16x32_bf16 v[4:7], v[170:173], v[214:217], v[4:7]
	v_mfma_f32_16x16x32_bf16 v[0:3], v[178:181], v[214:217], v[0:3]
	v_mfma_f32_16x16x32_bf16 v[52:55], v[174:177], v[194:197], v[52:55]
	v_mfma_f32_16x16x32_bf16 v[48:51], v[182:185], v[194:197], v[48:51]
	v_mfma_f32_16x16x32_bf16 v[36:39], v[174:177], v[202:205], v[36:39]
	v_mfma_f32_16x16x32_bf16 v[32:35], v[182:185], v[202:205], v[32:35]
	v_mfma_f32_16x16x32_bf16 v[20:23], v[174:177], v[210:213], v[20:23]
	v_mfma_f32_16x16x32_bf16 v[16:19], v[182:185], v[210:213], v[16:19]
	v_mfma_f32_16x16x32_bf16 v[4:7], v[174:177], v[218:221], v[4:7]
	v_mfma_f32_16x16x32_bf16 v[0:3], v[182:185], v[218:221], v[0:3]
	s_setprio 0
	s_barrier
	s_add_i32 s49, s49, 2
	s_add_u32 s22, s22, 0x100
	s_addc_u32 s23, s23, 0
	s_cmp_gt_u32 s49, 13
	s_cbranch_scc0 .LBB0_681
	s_add_u32 s22, s45, 0xffffff00
	s_addc_u32 s23, s46, -1
	s_andn2_b64 vcc, exec, s[4:5]
	s_cbranch_vccnz .LBB0_684
	v_mov_b32_e32 v0, 0
	s_mov_b32 s8, s14
	s_mov_b32 s6, s16
	s_mov_b64 s[10:11], s[20:21]
	s_mov_b32 s41, s44
	v_mov_b32_e32 v1, v0
	v_mov_b32_e32 v2, v0
	v_mov_b32_e32 v3, v0
	v_mov_b32_e32 v4, v0
	v_mov_b32_e32 v5, v0
	v_mov_b32_e32 v6, v0
	v_mov_b32_e32 v7, v0
	v_mov_b32_e32 v16, v0
	v_mov_b32_e32 v17, v0
	v_mov_b32_e32 v18, v0
	v_mov_b32_e32 v19, v0
	v_mov_b32_e32 v20, v0
	v_mov_b32_e32 v21, v0
	v_mov_b32_e32 v22, v0
	v_mov_b32_e32 v23, v0
	v_mov_b32_e32 v32, v0
	v_mov_b32_e32 v33, v0
	v_mov_b32_e32 v34, v0
	v_mov_b32_e32 v35, v0
	v_mov_b32_e32 v36, v0
	v_mov_b32_e32 v37, v0
	v_mov_b32_e32 v38, v0
	v_mov_b32_e32 v39, v0
	v_mov_b32_e32 v48, v0
	v_mov_b32_e32 v49, v0
	v_mov_b32_e32 v50, v0
	v_mov_b32_e32 v51, v0
	v_mov_b32_e32 v52, v0
	v_mov_b32_e32 v53, v0
	v_mov_b32_e32 v54, v0
	v_mov_b32_e32 v55, v0
	v_mov_b32_e32 v8, v0
	v_mov_b32_e32 v9, v0
	v_mov_b32_e32 v10, v0
	v_mov_b32_e32 v11, v0
	v_mov_b32_e32 v12, v0
	v_mov_b32_e32 v13, v0
	v_mov_b32_e32 v14, v0
	v_mov_b32_e32 v15, v0
	v_mov_b32_e32 v28, v0
	v_mov_b32_e32 v29, v0
	v_mov_b32_e32 v30, v0
	v_mov_b32_e32 v31, v0
	v_mov_b32_e32 v24, v0
	v_mov_b32_e32 v25, v0
	v_mov_b32_e32 v26, v0
	v_mov_b32_e32 v27, v0
	v_mov_b32_e32 v40, v0
	v_mov_b32_e32 v41, v0
	v_mov_b32_e32 v42, v0
	v_mov_b32_e32 v43, v0
	v_mov_b32_e32 v44, v0
	v_mov_b32_e32 v45, v0
	v_mov_b32_e32 v46, v0
	v_mov_b32_e32 v47, v0
	v_mov_b32_e32 v60, v0
	v_mov_b32_e32 v61, v0
	v_mov_b32_e32 v62, v0
	v_mov_b32_e32 v63, v0
	v_mov_b32_e32 v56, v0
	v_mov_b32_e32 v57, v0
	v_mov_b32_e32 v58, v0
	v_mov_b32_e32 v59, v0
	v_mov_b32_e32 v64, v0
	v_mov_b32_e32 v65, v0
	v_mov_b32_e32 v66, v0
	v_mov_b32_e32 v67, v0
	v_mov_b32_e32 v68, v0
	v_mov_b32_e32 v69, v0
	v_mov_b32_e32 v70, v0
	v_mov_b32_e32 v71, v0
	v_mov_b32_e32 v80, v0
	v_mov_b32_e32 v81, v0
	v_mov_b32_e32 v82, v0
	v_mov_b32_e32 v83, v0
	v_mov_b32_e32 v84, v0
	v_mov_b32_e32 v85, v0
	v_mov_b32_e32 v86, v0
	v_mov_b32_e32 v87, v0
	v_mov_b32_e32 v96, v0
	v_mov_b32_e32 v97, v0
	v_mov_b32_e32 v98, v0
	v_mov_b32_e32 v99, v0
	v_mov_b32_e32 v100, v0
	v_mov_b32_e32 v101, v0
	v_mov_b32_e32 v102, v0
	v_mov_b32_e32 v103, v0
	v_mov_b32_e32 v112, v0
	v_mov_b32_e32 v113, v0
	v_mov_b32_e32 v114, v0
	v_mov_b32_e32 v115, v0
	v_mov_b32_e32 v116, v0
	v_mov_b32_e32 v117, v0
	v_mov_b32_e32 v118, v0
	v_mov_b32_e32 v119, v0
	v_mov_b32_e32 v72, v0
	v_mov_b32_e32 v73, v0
	v_mov_b32_e32 v74, v0
	v_mov_b32_e32 v75, v0
	v_mov_b32_e32 v76, v0
	v_mov_b32_e32 v77, v0
	v_mov_b32_e32 v78, v0
	v_mov_b32_e32 v79, v0
	v_mov_b32_e32 v88, v0
	v_mov_b32_e32 v89, v0
	v_mov_b32_e32 v90, v0
	v_mov_b32_e32 v91, v0
	v_mov_b32_e32 v92, v0
	v_mov_b32_e32 v93, v0
	v_mov_b32_e32 v94, v0
	v_mov_b32_e32 v95, v0
	v_mov_b32_e32 v104, v0
	v_mov_b32_e32 v105, v0
	v_mov_b32_e32 v106, v0
	v_mov_b32_e32 v107, v0
	v_mov_b32_e32 v108, v0
	v_mov_b32_e32 v109, v0
	v_mov_b32_e32 v110, v0
	v_mov_b32_e32 v111, v0
	v_mov_b32_e32 v120, v0
	v_mov_b32_e32 v121, v0
	v_mov_b32_e32 v122, v0
	v_mov_b32_e32 v123, v0
	v_mov_b32_e32 v124, v0
	v_mov_b32_e32 v125, v0
	v_mov_b32_e32 v126, v0
	v_mov_b32_e32 v127, v0
	s_andn2_b64 vcc, exec, s[0:1]
	s_cbranch_vccnz .LBB0_685
	s_branch .LBB0_686
